# k24: k20 + LDS wait moved ahead of the barrier so the MMA phases hold only MFMAs
# baseline (speedup 1.0000x reference)
; #define PG8_STAGE(bufoff, gbase, voff) do { _Pragma("unroll") for (int _i = 0; _i < 2; ++_i) \
;         __builtin_amdgcn_global_load_lds((const unsigned*)((const char*)(gbase) + (voff)[_i]), (LAS unsigned*)(lds + (bufoff) + ldsw + _i * 8192), 16, 0, 0); } while (0)
; #define PG8_LDA(dst, b, h) do { _Pragma("unroll") for (int m = 0; m < 4; ++m) _Pragma("unroll") for (int k = 0; k < 2; ++k) dst[m][k] = *(const LAS bf16x8*)(lds + PG8_SA(b, h) + aoff + m * 2048 + k * 1024); } while (0)
; #define PG8_LDB(dst, b, h) do { _Pragma("unroll") for (int n = 0; n < 2; ++n) _Pragma("unroll") for (int k = 0; k < 2; ++k) dst[n][k] = *(const LAS bf16x8*)(lds + PG8_SB(b, h) + boff + n * 2048 + k * 1024); } while (0)
; #define PG8_MMA(ai, bj, At, Bt) do { __builtin_amdgcn_s_setprio(1); _Pragma("unroll") for (int m = 0; m < 4; ++m) _Pragma("unroll") for (int n = 0; n < 2; ++n) _Pragma("unroll") for (int k = 0; k < 2; ++k) \
;         acc[ai][bj][m][n] = __builtin_amdgcn_mfma_f32_16x16x32_bf16(Bt[n][k], At[m][k], acc[ai][bj][m][n], 0, 0, 0); __builtin_amdgcn_s_setprio(0); } while (0)
; #define PG8_WAIT_L(n) asm volatile("s_waitcnt lgkmcnt(" #n ")" ::: "memory")
; #define PG8_BAR __builtin_amdgcn_s_barrier()
; #define PG8_SCHED __builtin_amdgcn_sched_barrier(0)
; template <class Epi>
; __device__ __forceinline__ void gemm_phase(LAS unsigned char* lds, const Gemm g, const Epi& E) {
;     ...
;             const bool last = (t == nt - 2);
;             const char* a1 = cA + (size_t)(t + 1) * kstep;
;             const char* a2 = last ? nA : cA + (size_t)(t + 2) * kstep; const char* b2 = last ? nB : cB + (size_t)(t + 2) * kstep;
;             const char* a3 = a2 + kstep; const char* b3 = b2 + kstep;
;             PG8_LDB(B0, 0, 0); PG8_SCHED; PG8_LDA(At, 0, 0); PG8_STAGE(PG8_SA(1, 1), a1 + hstepA, voffA);
;             PG8_WAIT_L(8); PG8_BAR; PG8_WAIT_L(0); PG8_MMA(0, 0, At, B0); PG8_BAR; PG8_SCHED;
;             PG8_LDB(B1, 0, 1); PG8_STAGE(PG8_SB(0, 0), b2, voffB);
;             PG8_BAR; PG8_WAIT_L(0); PG8_MMA(0, 1, At, B1); PG8_BAR;
;             PG8_LDA(At, 0, 1); PG8_STAGE(PG8_SA(0, 0), a2, voffA);
;             PG8_BAR; PG8_WAIT_L(0); PG8_MMA(1, 0, At, B0); PG8_BAR; PG8_SCHED;
.LBB0_296:
	s_add_u32 s9, s16, s5
	s_addc_u32 s18, s17, 0
	s_add_u32 s36, s9, 0x100
	s_addc_u32 s60, s18, 0
	s_and_b64 s[0:1], s[58:59], exec
	s_cselect_b32 s67, s11, s60
	s_cselect_b32 s66, s10, s36
	s_add_u32 s0, s14, s5
	s_addc_u32 s1, s15, 0
	s_add_u32 s5, s0, 0x100
	s_addc_u32 s36, s1, 0
	s_add_i32 s73, 0, 0x10000
	s_and_b64 s[0:1], s[58:59], exec
	s_cselect_b32 s75, s13, s36
	s_cselect_b32 s74, s12, s5
	s_add_u32 s78, s9, 0x40080
	s_addc_u32 s79, s18, 0
	s_add_i32 s72, s73, s30
	s_add_i32 m0, s26, 0xc000
	s_add_i32 s50, s26, 0xe000
	s_add_i32 s27, 0, 0x14000
	s_add_i32 s24, s72, 0x2000
	s_add_u32 s64, s74, 0x10000
	v_add_u32_e32 v142, s73, v159
	s_addc_u32 s65, s75, 0
	s_add_i32 s18, s27, s30
	ds_read_b128 v[130:133], v142
	ds_read_b128 v[134:137], v142 offset:1024
	ds_read_b128 v[138:141], v142 offset:2048
	ds_read_b128 v[142:145], v142 offset:3072
	s_add_i32 s36, s18, 0x2000
	s_add_i32 vcc_hi, 0, 0x18000
	s_add_u32 s60, s66, 0x40000
	s_addc_u32 s61, s67, 0
	s_add_i32 vcc_lo, vcc_hi, s30
	s_add_i32 s9, 0, 0x1c000
	s_add_i32 s5, vcc_lo, 0x2000
	s_add_u32 s58, s74, 0x10080
	s_addc_u32 s59, s75, 0
	s_add_i32 s0, s9, s30
	s_add_i32 s1, s0, 0x2000
	v_lshl_add_u64 v[192:193], s[78:79], 0, v[152:153]
	ds_read_b128 v[154:157], v160
	ds_read_b128 v[162:165], v160 offset:1024
	ds_read_b128 v[166:169], v160 offset:2048
	ds_read_b128 v[170:173], v160 offset:3072
	ds_read_b128 v[174:177], v160 offset:4096
	ds_read_b128 v[180:183], v160 offset:5120
	ds_read_b128 v[184:187], v160 offset:6144
	ds_read_b128 v[188:191], v160 offset:7168
	global_load_lds_dwordx4 v[192:193], off
	v_lshl_add_u64 v[192:193], s[78:79], 0, v[148:149]
	s_mov_b32 m0, s50
	s_nop 0
	global_load_lds_dwordx4 v[192:193], off
	s_waitcnt lgkmcnt(0)
	s_barrier
	v_mfma_f32_16x16x32_bf16 v[126:129], v[130:133], v[154:157], v[126:129]
	v_mfma_f32_16x16x32_bf16 v[122:125], v[138:141], v[154:157], v[122:125]
	v_mfma_f32_16x16x32_bf16 v[114:117], v[130:133], v[166:169], v[114:117]
	v_mfma_f32_16x16x32_bf16 v[110:113], v[138:141], v[166:169], v[110:113]
	v_mfma_f32_16x16x32_bf16 v[102:105], v[130:133], v[174:177], v[102:105]
	v_mfma_f32_16x16x32_bf16 v[94:97], v[138:141], v[174:177], v[94:97]
	v_mfma_f32_16x16x32_bf16 v[86:89], v[130:133], v[184:187], v[86:89]
	v_mfma_f32_16x16x32_bf16 v[78:81], v[138:141], v[184:187], v[78:81]
	v_mfma_f32_16x16x32_bf16 v[126:129], v[134:137], v[162:165], v[126:129]
	v_mfma_f32_16x16x32_bf16 v[122:125], v[142:145], v[162:165], v[122:125]
	v_mfma_f32_16x16x32_bf16 v[114:117], v[134:137], v[170:173], v[114:117]
	v_mfma_f32_16x16x32_bf16 v[110:113], v[142:145], v[170:173], v[110:113]
	v_mfma_f32_16x16x32_bf16 v[102:105], v[134:137], v[180:183], v[102:105]
	v_mfma_f32_16x16x32_bf16 v[94:97], v[142:145], v[180:183], v[94:97]
	v_mfma_f32_16x16x32_bf16 v[86:89], v[134:137], v[188:191], v[86:89]
	v_mfma_f32_16x16x32_bf16 v[78:81], v[142:145], v[188:191], v[78:81]
	s_barrier
	s_mov_b32 m0, s72
	v_add_u32_e32 v161, s27, v159
	v_lshl_add_u64 v[208:209], s[74:75], 0, v[150:151]
	ds_read_b128 v[192:195], v161
	ds_read_b128 v[196:199], v161 offset:1024
	ds_read_b128 v[200:203], v161 offset:2048
	ds_read_b128 v[204:207], v161 offset:3072
	global_load_lds_dwordx4 v[208:209], off
	v_lshl_add_u64 v[226:227], s[74:75], 0, v[146:147]
	s_mov_b32 m0, s24
	s_nop 0
	global_load_lds_dwordx4 v[226:227], off
	s_nop 1
	s_mov_b32 m0, s26
	v_lshl_add_u64 v[228:229], s[66:67], 0, v[152:153]
	s_waitcnt lgkmcnt(0)
	s_barrier
	v_mfma_f32_16x16x32_bf16 v[118:121], v[192:195], v[154:157], v[118:121]
	v_mfma_f32_16x16x32_bf16 v[106:109], v[200:203], v[154:157], v[106:109]
	v_mfma_f32_16x16x32_bf16 v[98:101], v[192:195], v[166:169], v[98:101]
	v_mfma_f32_16x16x32_bf16 v[90:93], v[200:203], v[166:169], v[90:93]
	v_mfma_f32_16x16x32_bf16 v[82:85], v[192:195], v[174:177], v[82:85]
	v_mfma_f32_16x16x32_bf16 v[74:77], v[200:203], v[174:177], v[74:77]
	v_mfma_f32_16x16x32_bf16 v[70:73], v[192:195], v[184:187], v[70:73]
	v_mfma_f32_16x16x32_bf16 v[66:69], v[200:203], v[184:187], v[66:69]
	v_mfma_f32_16x16x32_bf16 v[118:121], v[196:199], v[162:165], v[118:121]
	v_mfma_f32_16x16x32_bf16 v[106:109], v[204:207], v[162:165], v[106:109]
	v_mfma_f32_16x16x32_bf16 v[98:101], v[196:199], v[170:173], v[98:101]
	v_mfma_f32_16x16x32_bf16 v[90:93], v[204:207], v[170:173], v[90:93]
	v_mfma_f32_16x16x32_bf16 v[82:85], v[196:199], v[180:183], v[82:85]
	v_mfma_f32_16x16x32_bf16 v[74:77], v[204:207], v[180:183], v[74:77]
	v_mfma_f32_16x16x32_bf16 v[70:73], v[196:199], v[188:191], v[70:73]
	v_mfma_f32_16x16x32_bf16 v[66:69], v[204:207], v[188:191], v[66:69]
	s_barrier
	ds_read_b128 v[154:157], v160 offset:16384
	ds_read_b128 v[162:165], v160 offset:17408
	ds_read_b128 v[166:169], v160 offset:18432
	ds_read_b128 v[170:173], v160 offset:19456
	ds_read_b128 v[174:177], v160 offset:20480
	ds_read_b128 v[180:183], v160 offset:21504
	ds_read_b128 v[184:187], v160 offset:22528
	ds_read_b128 v[188:191], v160 offset:23552
	global_load_lds_dwordx4 v[228:229], off
	v_lshl_add_u64 v[230:231], s[66:67], 0, v[148:149]
	s_mov_b32 m0, s52
	s_nop 0
	global_load_lds_dwordx4 v[230:231], off
	s_waitcnt lgkmcnt(0)
	s_barrier
; #define PG8_STAGE(bufoff, gbase, voff) do { _Pragma("unroll") for (int _i = 0; _i < 2; ++_i) \
;         __builtin_amdgcn_global_load_lds((const unsigned*)((const char*)(gbase) + (voff)[_i]), (LAS unsigned*)(lds + (bufoff) + ldsw + _i * 8192), 16, 0, 0); } while (0)
; #define PG8_LDA(dst, b, h) do { _Pragma("unroll") for (int m = 0; m < 4; ++m) _Pragma("unroll") for (int k = 0; k < 2; ++k) dst[m][k] = *(const LAS bf16x8*)(lds + PG8_SA(b, h) + aoff + m * 2048 + k * 1024); } while (0)
; #define PG8_LDB(dst, b, h) do { _Pragma("unroll") for (int n = 0; n < 2; ++n) _Pragma("unroll") for (int k = 0; k < 2; ++k) dst[n][k] = *(const LAS bf16x8*)(lds + PG8_SB(b, h) + boff + n * 2048 + k * 1024); } while (0)
; #define PG8_MMA(ai, bj, At, Bt) do { __builtin_amdgcn_s_setprio(1); _Pragma("unroll") for (int m = 0; m < 4; ++m) _Pragma("unroll") for (int n = 0; n < 2; ++n) _Pragma("unroll") for (int k = 0; k < 2; ++k) \
;         acc[ai][bj][m][n] = __builtin_amdgcn_mfma_f32_16x16x32_bf16(Bt[n][k], At[m][k], acc[ai][bj][m][n], 0, 0, 0); __builtin_amdgcn_s_setprio(0); } while (0)
; #define PG8_WAIT_V(n) asm volatile("s_waitcnt vmcnt(" #n ")" ::: "memory")
; #define PG8_WAIT_L(n) asm volatile("s_waitcnt lgkmcnt(" #n ")" ::: "memory")
; #define PG8_BAR __builtin_amdgcn_s_barrier()
; #define PG8_SCHED __builtin_amdgcn_sched_barrier(0)
; template <class Epi>
; __device__ __forceinline__ void gemm_phase(LAS unsigned char* lds, const Gemm g, const Epi& E) {
;     ...
;             PG8_BAR; PG8_WAIT_L(0); PG8_MMA(1, 0, At, B0); PG8_BAR; PG8_SCHED;
;             PG8_STAGE(PG8_SB(0, 1), b2 + hstepB, voffB);
;             PG8_WAIT_V(6); PG8_BAR; PG8_MMA(1, 1, At, B1); PG8_BAR;
;             PG8_LDB(B0, 1, 0); PG8_SCHED; PG8_LDA(At, 1, 0); PG8_STAGE(PG8_SA(0, 1), a2 + hstepA, voffA);
;             PG8_WAIT_L(8); PG8_BAR; PG8_WAIT_L(0); PG8_MMA(0, 0, At, B0); PG8_BAR; PG8_SCHED;
;             PG8_LDB(B1, 1, 1); PG8_STAGE(PG8_SB(1, 0), b3, voffB);
;             PG8_BAR; PG8_WAIT_L(0); PG8_MMA(0, 1, At, B1); PG8_BAR;
	v_mfma_f32_16x16x32_bf16 v[62:65], v[130:133], v[154:157], v[62:65]
	v_mfma_f32_16x16x32_bf16 v[58:61], v[138:141], v[154:157], v[58:61]
	v_mfma_f32_16x16x32_bf16 v[54:57], v[130:133], v[166:169], v[54:57]
	v_mfma_f32_16x16x32_bf16 v[46:49], v[138:141], v[166:169], v[46:49]
	v_mfma_f32_16x16x32_bf16 v[38:41], v[130:133], v[174:177], v[38:41]
	v_mfma_f32_16x16x32_bf16 v[30:33], v[138:141], v[174:177], v[30:33]
	v_mfma_f32_16x16x32_bf16 v[22:25], v[130:133], v[184:187], v[22:25]
	v_mfma_f32_16x16x32_bf16 v[14:17], v[138:141], v[184:187], v[14:17]
	v_mfma_f32_16x16x32_bf16 v[62:65], v[134:137], v[162:165], v[62:65]
	v_mfma_f32_16x16x32_bf16 v[58:61], v[142:145], v[162:165], v[58:61]
	v_mfma_f32_16x16x32_bf16 v[54:57], v[134:137], v[170:173], v[54:57]
	v_mfma_f32_16x16x32_bf16 v[46:49], v[142:145], v[170:173], v[46:49]
	v_mfma_f32_16x16x32_bf16 v[38:41], v[134:137], v[180:183], v[38:41]
	v_mfma_f32_16x16x32_bf16 v[30:33], v[142:145], v[180:183], v[30:33]
	v_mfma_f32_16x16x32_bf16 v[22:25], v[134:137], v[188:191], v[22:25]
	v_mfma_f32_16x16x32_bf16 v[14:17], v[142:145], v[188:191], v[14:17]
	s_barrier
	s_mov_b32 m0, s18
	v_lshl_add_u64 v[130:131], s[64:65], 0, v[150:151]
	global_load_lds_dwordx4 v[130:131], off
	v_lshl_add_u64 v[130:131], s[64:65], 0, v[146:147]
	s_mov_b32 m0, s36
	s_nop 0
	global_load_lds_dwordx4 v[130:131], off
	v_add_u32_e32 v142, vcc_hi, v159
	s_waitcnt vmcnt(6)
	s_barrier
	v_mfma_f32_16x16x32_bf16 v[50:53], v[192:195], v[154:157], v[50:53]
	v_mfma_f32_16x16x32_bf16 v[42:45], v[200:203], v[154:157], v[42:45]
	v_mfma_f32_16x16x32_bf16 v[34:37], v[192:195], v[166:169], v[34:37]
	v_mfma_f32_16x16x32_bf16 v[26:29], v[200:203], v[166:169], v[26:29]
	v_mfma_f32_16x16x32_bf16 v[18:21], v[192:195], v[174:177], v[18:21]
	v_mfma_f32_16x16x32_bf16 v[10:13], v[200:203], v[174:177], v[10:13]
	v_mfma_f32_16x16x32_bf16 v[6:9], v[192:195], v[184:187], v[6:9]
	v_mfma_f32_16x16x32_bf16 v[2:5], v[200:203], v[184:187], v[2:5]
	v_mfma_f32_16x16x32_bf16 v[50:53], v[196:199], v[162:165], v[50:53]
	v_mfma_f32_16x16x32_bf16 v[42:45], v[204:207], v[162:165], v[42:45]
	v_mfma_f32_16x16x32_bf16 v[34:37], v[196:199], v[170:173], v[34:37]
	v_mfma_f32_16x16x32_bf16 v[26:29], v[204:207], v[170:173], v[26:29]
	v_mfma_f32_16x16x32_bf16 v[18:21], v[196:199], v[180:183], v[18:21]
	v_mfma_f32_16x16x32_bf16 v[10:13], v[204:207], v[180:183], v[10:13]
	v_mfma_f32_16x16x32_bf16 v[6:9], v[196:199], v[188:191], v[6:9]
	v_mfma_f32_16x16x32_bf16 v[2:5], v[204:207], v[188:191], v[2:5]
	s_barrier
	ds_read_b128 v[130:133], v142
	ds_read_b128 v[134:137], v142 offset:1024
	ds_read_b128 v[138:141], v142 offset:2048
	ds_read_b128 v[142:145], v142 offset:3072
	s_mov_b32 m0, s53
	v_lshl_add_u64 v[192:193], s[60:61], 0, v[152:153]
	ds_read_b128 v[154:157], v160 offset:32768
	ds_read_b128 v[162:165], v160 offset:33792
	ds_read_b128 v[166:169], v160 offset:34816
	ds_read_b128 v[170:173], v160 offset:35840
	ds_read_b128 v[174:177], v160 offset:36864
	ds_read_b128 v[180:183], v160 offset:37888
	ds_read_b128 v[184:187], v160 offset:38912
	ds_read_b128 v[188:191], v160 offset:39936
	global_load_lds_dwordx4 v[192:193], off
	v_lshl_add_u64 v[192:193], s[60:61], 0, v[148:149]
	s_mov_b32 m0, s68
	s_nop 0
	global_load_lds_dwordx4 v[192:193], off
	s_waitcnt lgkmcnt(0)
	s_barrier
	v_mfma_f32_16x16x32_bf16 v[126:129], v[130:133], v[154:157], v[126:129]
	v_mfma_f32_16x16x32_bf16 v[122:125], v[138:141], v[154:157], v[122:125]
	v_mfma_f32_16x16x32_bf16 v[114:117], v[130:133], v[166:169], v[114:117]
	v_mfma_f32_16x16x32_bf16 v[110:113], v[138:141], v[166:169], v[110:113]
	v_mfma_f32_16x16x32_bf16 v[102:105], v[130:133], v[174:177], v[102:105]
	v_mfma_f32_16x16x32_bf16 v[94:97], v[138:141], v[174:177], v[94:97]
	v_mfma_f32_16x16x32_bf16 v[86:89], v[130:133], v[184:187], v[86:89]
	v_mfma_f32_16x16x32_bf16 v[78:81], v[138:141], v[184:187], v[78:81]
	v_mfma_f32_16x16x32_bf16 v[126:129], v[134:137], v[162:165], v[126:129]
	v_mfma_f32_16x16x32_bf16 v[122:125], v[142:145], v[162:165], v[122:125]
	v_mfma_f32_16x16x32_bf16 v[114:117], v[134:137], v[170:173], v[114:117]
	v_mfma_f32_16x16x32_bf16 v[110:113], v[142:145], v[170:173], v[110:113]
	v_mfma_f32_16x16x32_bf16 v[102:105], v[134:137], v[180:183], v[102:105]
	v_mfma_f32_16x16x32_bf16 v[94:97], v[142:145], v[180:183], v[94:97]
	v_mfma_f32_16x16x32_bf16 v[86:89], v[134:137], v[188:191], v[86:89]
	v_mfma_f32_16x16x32_bf16 v[78:81], v[142:145], v[188:191], v[78:81]
	s_barrier
	s_mov_b32 m0, vcc_lo
	v_add_u32_e32 v161, s9, v159
	v_lshl_add_u64 v[208:209], v[208:209], 0, s[86:87]
	ds_read_b128 v[192:195], v161
	ds_read_b128 v[196:199], v161 offset:1024
	ds_read_b128 v[200:203], v161 offset:2048
	ds_read_b128 v[204:207], v161 offset:3072
	global_load_lds_dwordx4 v[208:209], off
	v_lshl_add_u64 v[208:209], v[226:227], 0, s[86:87]
	s_mov_b32 m0, s5
	s_nop 0
	global_load_lds_dwordx4 v[208:209], off
	s_nop 1
	s_mov_b32 m0, s71
	v_lshl_add_u64 v[208:209], v[228:229], 0, s[86:87]
	s_waitcnt lgkmcnt(0)
	s_barrier
; #define PG8_STAGE(bufoff, gbase, voff) do { _Pragma("unroll") for (int _i = 0; _i < 2; ++_i) \
;         __builtin_amdgcn_global_load_lds((const unsigned*)((const char*)(gbase) + (voff)[_i]), (LAS unsigned*)(lds + (bufoff) + ldsw + _i * 8192), 16, 0, 0); } while (0)
; #define PG8_LDA(dst, b, h) do { _Pragma("unroll") for (int m = 0; m < 4; ++m) _Pragma("unroll") for (int k = 0; k < 2; ++k) dst[m][k] = *(const LAS bf16x8*)(lds + PG8_SA(b, h) + aoff + m * 2048 + k * 1024); } while (0)
; #define PG8_MMA(ai, bj, At, Bt) do { __builtin_amdgcn_s_setprio(1); _Pragma("unroll") for (int m = 0; m < 4; ++m) _Pragma("unroll") for (int n = 0; n < 2; ++n) _Pragma("unroll") for (int k = 0; k < 2; ++k) \
;         acc[ai][bj][m][n] = __builtin_amdgcn_mfma_f32_16x16x32_bf16(Bt[n][k], At[m][k], acc[ai][bj][m][n], 0, 0, 0); __builtin_amdgcn_s_setprio(0); } while (0)
; #define PG8_WAIT_V(n) asm volatile("s_waitcnt vmcnt(" #n ")" ::: "memory")
; #define PG8_WAIT_L(n) asm volatile("s_waitcnt lgkmcnt(" #n ")" ::: "memory")
; #define PG8_BAR __builtin_amdgcn_s_barrier()
; #define PG8_SCHED __builtin_amdgcn_sched_barrier(0)
; template <class Epi>
; __device__ __forceinline__ void gemm_phase(LAS unsigned char* lds, const Gemm g, const Epi& E) {
;     ...
;             PG8_BAR; PG8_WAIT_L(0); PG8_MMA(0, 1, At, B1); PG8_BAR;
;             PG8_LDA(At, 1, 1); PG8_STAGE(PG8_SA(1, 0), a3, voffA);
;             PG8_BAR; PG8_WAIT_L(0); PG8_MMA(1, 0, At, B0); PG8_BAR; PG8_SCHED;
;             PG8_STAGE(PG8_SB(1, 1), b3 + hstepB, voffB);
;             PG8_WAIT_V(6); PG8_BAR; PG8_MMA(1, 1, At, B1); PG8_BAR;
;     __device__ __forceinline__ void operator()(const AccT& acc, const Unit& u, int wr, int wc, int fr, int fq) const {
;     ...
;         const int gpm = mapA.src(u.pm);
;         const int mb = gpm < 32 ? 32 : (gpm - 32) >> 3;
;         const int row0 = gpm * 256 + wr * 64 + fr, col0 = u.pn * 256 + wc * 32 + 4 * fq;
;         const float* gp = modl + ((size_t)mb * 6 + gi) * 1024;
;         f32x4 gv[2][2];
; #pragma unroll
;         for (int bj = 0; bj < 2; ++bj)
; #pragma unroll
;             for (int n = 0; n < 2; ++n) { gv[bj][n] = *(const f32x4*)(gp + col0 + bj * 128 + n * 16); if (scale) gv[bj][n] = gv[bj][n] * *(const f32x4*)(scale + col0 + bj * 128 + n * 16); }
	v_mfma_f32_16x16x32_bf16 v[118:121], v[192:195], v[154:157], v[118:121]
	v_mfma_f32_16x16x32_bf16 v[106:109], v[200:203], v[154:157], v[106:109]
	v_mfma_f32_16x16x32_bf16 v[98:101], v[192:195], v[166:169], v[98:101]
	v_mfma_f32_16x16x32_bf16 v[90:93], v[200:203], v[166:169], v[90:93]
	v_mfma_f32_16x16x32_bf16 v[82:85], v[192:195], v[174:177], v[82:85]
	v_mfma_f32_16x16x32_bf16 v[74:77], v[200:203], v[174:177], v[74:77]
	v_mfma_f32_16x16x32_bf16 v[70:73], v[192:195], v[184:187], v[70:73]
	v_mfma_f32_16x16x32_bf16 v[66:69], v[200:203], v[184:187], v[66:69]
	v_mfma_f32_16x16x32_bf16 v[118:121], v[196:199], v[162:165], v[118:121]
	v_mfma_f32_16x16x32_bf16 v[106:109], v[204:207], v[162:165], v[106:109]
	v_mfma_f32_16x16x32_bf16 v[98:101], v[196:199], v[170:173], v[98:101]
	v_mfma_f32_16x16x32_bf16 v[90:93], v[204:207], v[170:173], v[90:93]
	v_mfma_f32_16x16x32_bf16 v[82:85], v[196:199], v[180:183], v[82:85]
	v_mfma_f32_16x16x32_bf16 v[74:77], v[204:207], v[180:183], v[74:77]
	v_mfma_f32_16x16x32_bf16 v[70:73], v[196:199], v[188:191], v[70:73]
	v_mfma_f32_16x16x32_bf16 v[66:69], v[204:207], v[188:191], v[66:69]
	s_barrier
	ds_read_b128 v[154:157], v160 offset:49152
	ds_read_b128 v[162:165], v160 offset:50176
	ds_read_b128 v[166:169], v160 offset:51200
	ds_read_b128 v[170:173], v160 offset:52224
	ds_read_b128 v[174:177], v160 offset:53248
	ds_read_b128 v[180:183], v160 offset:54272
	ds_read_b128 v[184:187], v160 offset:55296
	ds_read_b128 v[188:191], v160 offset:56320
	global_load_lds_dwordx4 v[208:209], off
	v_lshl_add_u64 v[208:209], v[230:231], 0, s[86:87]
	s_mov_b32 m0, s80
	s_nop 0
	global_load_lds_dwordx4 v[208:209], off
	s_waitcnt lgkmcnt(0)
	s_barrier
	v_mfma_f32_16x16x32_bf16 v[62:65], v[130:133], v[154:157], v[62:65]
	v_mfma_f32_16x16x32_bf16 v[58:61], v[138:141], v[154:157], v[58:61]
	v_mfma_f32_16x16x32_bf16 v[54:57], v[130:133], v[166:169], v[54:57]
	v_mfma_f32_16x16x32_bf16 v[46:49], v[138:141], v[166:169], v[46:49]
	v_mfma_f32_16x16x32_bf16 v[38:41], v[130:133], v[174:177], v[38:41]
	v_mfma_f32_16x16x32_bf16 v[30:33], v[138:141], v[174:177], v[30:33]
	v_mfma_f32_16x16x32_bf16 v[22:25], v[130:133], v[184:187], v[22:25]
	v_mfma_f32_16x16x32_bf16 v[14:17], v[138:141], v[184:187], v[14:17]
	v_mfma_f32_16x16x32_bf16 v[62:65], v[134:137], v[162:165], v[62:65]
	v_mfma_f32_16x16x32_bf16 v[58:61], v[142:145], v[162:165], v[58:61]
	v_mfma_f32_16x16x32_bf16 v[54:57], v[134:137], v[170:173], v[54:57]
	v_mfma_f32_16x16x32_bf16 v[46:49], v[142:145], v[170:173], v[46:49]
	v_mfma_f32_16x16x32_bf16 v[38:41], v[134:137], v[180:183], v[38:41]
	v_mfma_f32_16x16x32_bf16 v[30:33], v[142:145], v[180:183], v[30:33]
	v_mfma_f32_16x16x32_bf16 v[22:25], v[134:137], v[188:191], v[22:25]
	v_mfma_f32_16x16x32_bf16 v[14:17], v[142:145], v[188:191], v[14:17]
	s_barrier
	s_mov_b32 m0, s0
	v_lshl_add_u64 v[130:131], s[58:59], 0, v[150:151]
	global_load_lds_dwordx4 v[130:131], off
	v_lshl_add_u64 v[130:131], s[58:59], 0, v[146:147]
	s_mov_b32 m0, s1
	s_nop 0
	global_load_lds_dwordx4 v[130:131], off
	s_waitcnt vmcnt(6)
	s_barrier
	v_mfma_f32_16x16x32_bf16 v[50:53], v[192:195], v[154:157], v[50:53]
	v_mfma_f32_16x16x32_bf16 v[42:45], v[200:203], v[154:157], v[42:45]
	v_mfma_f32_16x16x32_bf16 v[34:37], v[192:195], v[166:169], v[34:37]
	v_mfma_f32_16x16x32_bf16 v[26:29], v[200:203], v[166:169], v[26:29]
	v_mfma_f32_16x16x32_bf16 v[18:21], v[192:195], v[174:177], v[18:21]
	v_mfma_f32_16x16x32_bf16 v[10:13], v[200:203], v[174:177], v[10:13]
	v_mfma_f32_16x16x32_bf16 v[6:9], v[192:195], v[184:187], v[6:9]
	v_mfma_f32_16x16x32_bf16 v[2:5], v[200:203], v[184:187], v[2:5]
	v_mfma_f32_16x16x32_bf16 v[50:53], v[196:199], v[162:165], v[50:53]
	v_mfma_f32_16x16x32_bf16 v[42:45], v[204:207], v[162:165], v[42:45]
	v_mfma_f32_16x16x32_bf16 v[34:37], v[196:199], v[170:173], v[34:37]
	v_mfma_f32_16x16x32_bf16 v[26:29], v[204:207], v[170:173], v[26:29]
	v_mfma_f32_16x16x32_bf16 v[18:21], v[196:199], v[180:183], v[18:21]
	v_mfma_f32_16x16x32_bf16 v[10:13], v[204:207], v[180:183], v[10:13]
	v_mfma_f32_16x16x32_bf16 v[6:9], v[196:199], v[188:191], v[6:9]
	v_mfma_f32_16x16x32_bf16 v[2:5], v[204:207], v[188:191], v[2:5]
	s_movk_i32 s5, 0x100
	s_andn2_b64 vcc, exec, s[28:29]
	s_mov_b64 s[58:59], -1
	s_mov_b64 s[28:29], 0
	s_barrier
	s_cbranch_vccz .LBB0_296
	s_cmp_ge_i32 s93, s31
	s_cselect_b32 s0, s44, 0
	s_add_i32 s0, s93, s0
	s_sub_i32 s1, s0, 32
	s_lshl_b32 s4, s4, 8
	s_ashr_i32 s1, s1, 3
	s_or_b32 s4, s4, s70
	v_mov_b32_e32 v130, v1
	v_mov_b32_e32 v161, v158
	s_mul_i32 s1, s1, 6
	s_cmp_gt_i32 s0, 31
	v_readlane_b32 s14, v255, 14
	v_lshl_add_u32 v154, v130, 2, s4
	s_cselect_b32 s4, s1, 0xc0
	s_ashr_i32 s5, s4, 31
	s_lshl_b64 s[4:5], s[4:5], 12
	v_readlane_b32 s15, v255, 15
	s_add_u32 s4, s14, s4
	v_ashrrev_i32_e32 v155, 31, v154
	s_addc_u32 s5, s15, s5
	v_lshlrev_b64 v[136:137], 2, v[154:155]
	v_lshl_add_u64 v[134:135], s[4:5], 0, v[136:137]
	v_add_co_u32_e32 v130, vcc, 0x2000, v134
	v_readlane_b32 s14, v254, 30
	s_nop 0
	v_addc_co_u32_e32 v131, vcc, 0, v135, vcc
	global_load_dwordx4 v[130:133], v[130:131], off
	v_readlane_b32 s15, v254, 31
	s_andn2_b64 vcc, exec, s[14:15]
	v_lshl_add_u64 v[156:157], s[6:7], 0, v[136:137]
	v_cndmask_b32_e64 v138, 0, 1, s[14:15]
	v_cmp_ne_u32_e64 s[4:5], 1, v138
	s_cbranch_vccnz .LBB0_299
	global_load_dwordx4 v[136:139], v[156:157], off
	s_waitcnt vmcnt(0)
	v_pk_mul_f32 v[132:133], v[132:133], v[138:139]
	v_pk_mul_f32 v[130:131], v[130:131], v[136:137]

; #define PG8_STAGE(bufoff, gbase, voff) do { _Pragma("unroll") for (int _i = 0; _i < 2; ++_i) \
;         __builtin_amdgcn_global_load_lds((const unsigned*)((const char*)(gbase) + (voff)[_i]), (LAS unsigned*)(lds + (bufoff) + ldsw + _i * 8192), 16, 0, 0); } while (0)
; #define PG8_LDA(dst, b, h) do { _Pragma("unroll") for (int m = 0; m < 4; ++m) _Pragma("unroll") for (int k = 0; k < 2; ++k) dst[m][k] = *(const LAS bf16x8*)(lds + PG8_SA(b, h) + aoff + m * 2048 + k * 1024); } while (0)
; #define PG8_LDB(dst, b, h) do { _Pragma("unroll") for (int n = 0; n < 2; ++n) _Pragma("unroll") for (int k = 0; k < 2; ++k) dst[n][k] = *(const LAS bf16x8*)(lds + PG8_SB(b, h) + boff + n * 2048 + k * 1024); } while (0)
; #define PG8_MMA(ai, bj, At, Bt) do { __builtin_amdgcn_s_setprio(1); _Pragma("unroll") for (int m = 0; m < 4; ++m) _Pragma("unroll") for (int n = 0; n < 2; ++n) _Pragma("unroll") for (int k = 0; k < 2; ++k) \
;         acc[ai][bj][m][n] = __builtin_amdgcn_mfma_f32_16x16x32_bf16(Bt[n][k], At[m][k], acc[ai][bj][m][n], 0, 0, 0); __builtin_amdgcn_s_setprio(0); } while (0)
; #define PG8_WAIT_L(n) asm volatile("s_waitcnt lgkmcnt(" #n ")" ::: "memory")
; #define PG8_BAR __builtin_amdgcn_s_barrier()
; #define PG8_SCHED __builtin_amdgcn_sched_barrier(0)
; template <class Epi>
; __device__ __forceinline__ void gemm_phase(LAS unsigned char* lds, const Gemm g, const Epi& E) {
;     ...
;             const bool last = (t == nt - 2);
;             const char* a1 = cA + (size_t)(t + 1) * kstep;
;             const char* a2 = last ? nA : cA + (size_t)(t + 2) * kstep; const char* b2 = last ? nB : cB + (size_t)(t + 2) * kstep;
;             const char* a3 = a2 + kstep; const char* b3 = b2 + kstep;
;             PG8_LDB(B0, 0, 0); PG8_SCHED; PG8_LDA(At, 0, 0); PG8_STAGE(PG8_SA(1, 1), a1 + hstepA, voffA);
;             PG8_WAIT_L(8); PG8_BAR; PG8_WAIT_L(0); PG8_MMA(0, 0, At, B0); PG8_BAR; PG8_SCHED;
;             PG8_LDB(B1, 0, 1); PG8_STAGE(PG8_SB(0, 0), b2, voffB);
;             PG8_BAR; PG8_WAIT_L(0); PG8_MMA(0, 1, At, B1); PG8_BAR;
;             PG8_LDA(At, 0, 1); PG8_STAGE(PG8_SA(0, 0), a2, voffA);
;             PG8_BAR; PG8_WAIT_L(0); PG8_MMA(1, 0, At, B0); PG8_BAR; PG8_SCHED;
.LBB0_331:
	s_add_u32 s60, s4, 0xfffc0080
	s_addc_u32 s61, s5, -1
	s_add_i32 s72, 0, 0x10000
	v_add_u32_e32 v94, s72, v201
	ds_read_b128 v[74:77], v94
	ds_read_b128 v[82:85], v94 offset:1024
	ds_read_b128 v[86:89], v94 offset:2048
	ds_read_b128 v[94:97], v94 offset:3072
	s_cmp_eq_u32 s53, 12
	s_cselect_b32 s65, s29, s61
	s_cselect_b32 s64, s28, s60
	s_cselect_b32 s61, s59, s52
	s_cselect_b32 s60, s58, s15
	v_lshl_add_u64 v[192:193], s[4:5], 0, v[188:189]
	s_add_i32 m0, s24, 0xc000
	ds_read_b128 v[106:109], v202
	ds_read_b128 v[110:113], v202 offset:1024
	ds_read_b128 v[130:133], v202 offset:2048
	ds_read_b128 v[134:137], v202 offset:3072
	ds_read_b128 v[154:157], v202 offset:4096
	ds_read_b128 v[158:161], v202 offset:5120
	ds_read_b128 v[170:173], v202 offset:6144
	ds_read_b128 v[174:177], v202 offset:7168
	global_load_lds_dwordx4 v[192:193], off
	v_lshl_add_u64 v[192:193], s[4:5], 0, v[190:191]
	s_add_i32 m0, s24, 0xe000
	s_nop 0
	global_load_lds_dwordx4 v[192:193], off
	s_waitcnt lgkmcnt(0)
	s_barrier
	v_mfma_f32_16x16x32_bf16 v[166:169], v[74:77], v[106:109], v[166:169]
	v_mfma_f32_16x16x32_bf16 v[162:165], v[86:89], v[106:109], v[162:165]
	v_mfma_f32_16x16x32_bf16 v[142:145], v[74:77], v[130:133], v[142:145]
	v_mfma_f32_16x16x32_bf16 v[138:141], v[86:89], v[130:133], v[138:141]
	v_mfma_f32_16x16x32_bf16 v[118:121], v[74:77], v[154:157], v[118:121]
	v_mfma_f32_16x16x32_bf16 v[114:117], v[86:89], v[154:157], v[114:117]
	v_mfma_f32_16x16x32_bf16 v[90:93], v[74:77], v[170:173], v[90:93]
	v_mfma_f32_16x16x32_bf16 v[78:81], v[86:89], v[170:173], v[78:81]
	v_mfma_f32_16x16x32_bf16 v[166:169], v[82:85], v[110:113], v[166:169]
	v_mfma_f32_16x16x32_bf16 v[162:165], v[94:97], v[110:113], v[162:165]
	v_mfma_f32_16x16x32_bf16 v[142:145], v[82:85], v[134:137], v[142:145]
	v_mfma_f32_16x16x32_bf16 v[138:141], v[94:97], v[134:137], v[138:141]
	v_mfma_f32_16x16x32_bf16 v[118:121], v[82:85], v[158:161], v[118:121]
	v_mfma_f32_16x16x32_bf16 v[114:117], v[94:97], v[158:161], v[114:117]
	v_mfma_f32_16x16x32_bf16 v[90:93], v[82:85], v[174:177], v[90:93]
	v_mfma_f32_16x16x32_bf16 v[78:81], v[94:97], v[174:177], v[78:81]
	s_barrier
	s_add_i32 s74, 0, 0x14000
	s_add_i32 s72, s72, s1
	v_add_u32_e32 v203, s74, v201
	v_lshl_add_u64 v[208:209], s[60:61], 0, v[184:185]
	s_mov_b32 m0, s72
	ds_read_b128 v[192:195], v203
	ds_read_b128 v[196:199], v203 offset:1024
	ds_read_b128 v[204:207], v203 offset:2048
	ds_read_b128 v[226:229], v203 offset:3072
	global_load_lds_dwordx4 v[208:209], off
	v_lshl_add_u64 v[234:235], s[60:61], 0, v[180:181]
	s_add_i32 m0, s72, 0x2000
	s_nop 0
	global_load_lds_dwordx4 v[234:235], off
	s_nop 1
	s_mov_b32 m0, s24
	v_lshl_add_u64 v[236:237], s[64:65], 0, v[186:187]
	s_waitcnt lgkmcnt(0)
	s_barrier
	v_mfma_f32_16x16x32_bf16 v[150:153], v[192:195], v[106:109], v[150:153]
	v_mfma_f32_16x16x32_bf16 v[106:109], v[204:207], v[106:109], v[146:149]
	v_mfma_f32_16x16x32_bf16 v[122:125], v[204:207], v[130:133], v[122:125]
	v_mfma_f32_16x16x32_bf16 v[102:105], v[192:195], v[154:157], v[102:105]
	v_mfma_f32_16x16x32_bf16 v[98:101], v[204:207], v[154:157], v[98:101]
	v_mfma_f32_16x16x32_bf16 v[70:73], v[192:195], v[170:173], v[70:73]
	v_mfma_f32_16x16x32_bf16 v[66:69], v[204:207], v[170:173], v[66:69]
	v_mfma_f32_16x16x32_bf16 v[150:153], v[196:199], v[110:113], v[150:153]
	v_mfma_f32_16x16x32_bf16 v[106:109], v[226:229], v[110:113], v[106:109]
	v_mfma_f32_16x16x32_bf16 v[110:113], v[192:195], v[130:133], v[126:129]
	v_mfma_f32_16x16x32_bf16 v[122:125], v[226:229], v[134:137], v[122:125]
	v_mfma_f32_16x16x32_bf16 v[102:105], v[196:199], v[158:161], v[102:105]
	v_mfma_f32_16x16x32_bf16 v[98:101], v[226:229], v[158:161], v[98:101]
	v_mfma_f32_16x16x32_bf16 v[70:73], v[196:199], v[174:177], v[70:73]
	v_mfma_f32_16x16x32_bf16 v[66:69], v[226:229], v[174:177], v[66:69]
	v_mfma_f32_16x16x32_bf16 v[110:113], v[196:199], v[134:137], v[110:113]
	s_barrier
	ds_read_b128 v[126:129], v202 offset:16384
	ds_read_b128 v[130:133], v202 offset:17408
	ds_read_b128 v[134:137], v202 offset:18432
	ds_read_b128 v[146:149], v202 offset:19456
	ds_read_b128 v[154:157], v202 offset:20480
	ds_read_b128 v[158:161], v202 offset:21504
	ds_read_b128 v[170:173], v202 offset:22528
	ds_read_b128 v[174:177], v202 offset:23552
	global_load_lds_dwordx4 v[236:237], off
	v_lshl_add_u64 v[238:239], s[64:65], 0, v[182:183]
	s_mov_b32 m0, s25
	s_nop 0
	global_load_lds_dwordx4 v[238:239], off
	s_waitcnt lgkmcnt(0)
	s_barrier
	v_mfma_f32_16x16x32_bf16 v[62:65], v[74:77], v[126:129], v[62:65]
	v_mfma_f32_16x16x32_bf16 v[58:61], v[86:89], v[126:129], v[58:61]
	v_mfma_f32_16x16x32_bf16 v[46:49], v[74:77], v[134:137], v[46:49]
	v_mfma_f32_16x16x32_bf16 v[42:45], v[86:89], v[134:137], v[42:45]
	v_mfma_f32_16x16x32_bf16 v[30:33], v[74:77], v[154:157], v[30:33]
	v_mfma_f32_16x16x32_bf16 v[26:29], v[86:89], v[154:157], v[26:29]
	v_mfma_f32_16x16x32_bf16 v[14:17], v[74:77], v[170:173], v[14:17]
	v_mfma_f32_16x16x32_bf16 v[10:13], v[86:89], v[170:173], v[10:13]
	v_mfma_f32_16x16x32_bf16 v[62:65], v[82:85], v[130:133], v[62:65]
	v_mfma_f32_16x16x32_bf16 v[58:61], v[94:97], v[130:133], v[58:61]
	v_mfma_f32_16x16x32_bf16 v[46:49], v[82:85], v[146:149], v[46:49]
	v_mfma_f32_16x16x32_bf16 v[42:45], v[94:97], v[146:149], v[42:45]
	v_mfma_f32_16x16x32_bf16 v[30:33], v[82:85], v[158:161], v[30:33]
	v_mfma_f32_16x16x32_bf16 v[26:29], v[94:97], v[158:161], v[26:29]
	v_mfma_f32_16x16x32_bf16 v[14:17], v[82:85], v[174:177], v[14:17]
	v_mfma_f32_16x16x32_bf16 v[10:13], v[94:97], v[174:177], v[10:13]
	s_barrier
; #define PG8_STAGE(bufoff, gbase, voff) do { _Pragma("unroll") for (int _i = 0; _i < 2; ++_i) \
;         __builtin_amdgcn_global_load_lds((const unsigned*)((const char*)(gbase) + (voff)[_i]), (LAS unsigned*)(lds + (bufoff) + ldsw + _i * 8192), 16, 0, 0); } while (0)
; #define PG8_LDA(dst, b, h) do { _Pragma("unroll") for (int m = 0; m < 4; ++m) _Pragma("unroll") for (int k = 0; k < 2; ++k) dst[m][k] = *(const LAS bf16x8*)(lds + PG8_SA(b, h) + aoff + m * 2048 + k * 1024); } while (0)
; #define PG8_LDB(dst, b, h) do { _Pragma("unroll") for (int n = 0; n < 2; ++n) _Pragma("unroll") for (int k = 0; k < 2; ++k) dst[n][k] = *(const LAS bf16x8*)(lds + PG8_SB(b, h) + boff + n * 2048 + k * 1024); } while (0)
; #define PG8_MMA(ai, bj, At, Bt) do { __builtin_amdgcn_s_setprio(1); _Pragma("unroll") for (int m = 0; m < 4; ++m) _Pragma("unroll") for (int n = 0; n < 2; ++n) _Pragma("unroll") for (int k = 0; k < 2; ++k) \
;         acc[ai][bj][m][n] = __builtin_amdgcn_mfma_f32_16x16x32_bf16(Bt[n][k], At[m][k], acc[ai][bj][m][n], 0, 0, 0); __builtin_amdgcn_s_setprio(0); } while (0)
; #define PG8_WAIT_V(n) asm volatile("s_waitcnt vmcnt(" #n ")" ::: "memory")
; #define PG8_WAIT_L(n) asm volatile("s_waitcnt lgkmcnt(" #n ")" ::: "memory")
; #define PG8_BAR __builtin_amdgcn_s_barrier()
; #define PG8_SCHED __builtin_amdgcn_sched_barrier(0)
; template <class Epi>
; __device__ __forceinline__ void gemm_phase(LAS unsigned char* lds, const Gemm g, const Epi& E) {
;     ...
;             PG8_STAGE(PG8_SB(0, 1), b2 + hstepB, voffB);
;             PG8_WAIT_V(6); PG8_BAR; PG8_MMA(1, 1, At, B1); PG8_BAR;
;             PG8_LDB(B0, 1, 0); PG8_SCHED; PG8_LDA(At, 1, 0); PG8_STAGE(PG8_SA(0, 1), a2 + hstepA, voffA);
;             PG8_WAIT_L(8); PG8_BAR; PG8_WAIT_L(0); PG8_MMA(0, 0, At, B0); PG8_BAR; PG8_SCHED;
;             PG8_LDB(B1, 1, 1); PG8_STAGE(PG8_SB(1, 0), b3, voffB);
;             PG8_BAR; PG8_WAIT_L(0); PG8_MMA(0, 1, At, B1); PG8_BAR;
	s_add_u32 s72, s60, 0x40000
	s_addc_u32 s73, s61, 0
	s_add_i32 s74, s74, s1
	v_lshl_add_u64 v[74:75], s[72:73], 0, v[184:185]
	s_mov_b32 m0, s74
	s_nop 0
	global_load_lds_dwordx4 v[74:75], off
	v_lshl_add_u64 v[74:75], s[72:73], 0, v[180:181]
	s_add_i32 m0, s74, 0x2000
	s_nop 0
	global_load_lds_dwordx4 v[74:75], off
	s_add_i32 s72, 0, 0x18000
	v_add_u32_e32 v94, s72, v201
	s_waitcnt vmcnt(6)
	s_barrier
	v_mfma_f32_16x16x32_bf16 v[54:57], v[192:195], v[126:129], v[54:57]
	v_mfma_f32_16x16x32_bf16 v[50:53], v[204:207], v[126:129], v[50:53]
	v_mfma_f32_16x16x32_bf16 v[38:41], v[192:195], v[134:137], v[38:41]
	v_mfma_f32_16x16x32_bf16 v[34:37], v[204:207], v[134:137], v[34:37]
	v_mfma_f32_16x16x32_bf16 v[22:25], v[192:195], v[154:157], v[22:25]
	v_mfma_f32_16x16x32_bf16 v[18:21], v[204:207], v[154:157], v[18:21]
	v_mfma_f32_16x16x32_bf16 v[6:9], v[192:195], v[170:173], v[6:9]
	v_mfma_f32_16x16x32_bf16 v[2:5], v[204:207], v[170:173], v[2:5]
	v_mfma_f32_16x16x32_bf16 v[54:57], v[196:199], v[130:133], v[54:57]
	v_mfma_f32_16x16x32_bf16 v[50:53], v[226:229], v[130:133], v[50:53]
	v_mfma_f32_16x16x32_bf16 v[38:41], v[196:199], v[146:149], v[38:41]
	v_mfma_f32_16x16x32_bf16 v[34:37], v[226:229], v[146:149], v[34:37]
	v_mfma_f32_16x16x32_bf16 v[22:25], v[196:199], v[158:161], v[22:25]
	v_mfma_f32_16x16x32_bf16 v[18:21], v[226:229], v[158:161], v[18:21]
	v_mfma_f32_16x16x32_bf16 v[6:9], v[196:199], v[174:177], v[6:9]
	v_mfma_f32_16x16x32_bf16 v[2:5], v[226:229], v[174:177], v[2:5]
	s_barrier
	ds_read_b128 v[74:77], v94
	ds_read_b128 v[82:85], v94 offset:1024
	ds_read_b128 v[86:89], v94 offset:2048
	ds_read_b128 v[94:97], v94 offset:3072
	s_add_u32 s64, s64, 0x40000
	s_addc_u32 s65, s65, 0
	s_mov_b32 m0, s31
	v_lshl_add_u64 v[146:147], s[64:65], 0, v[186:187]
	ds_read_b128 v[126:129], v202 offset:32768
	ds_read_b128 v[130:133], v202 offset:33792
	ds_read_b128 v[134:137], v202 offset:34816
	ds_read_b128 v[154:157], v202 offset:35840
	ds_read_b128 v[158:161], v202 offset:36864
	ds_read_b128 v[170:173], v202 offset:37888
	ds_read_b128 v[174:177], v202 offset:38912
	ds_read_b128 v[192:195], v202 offset:39936
	global_load_lds_dwordx4 v[146:147], off
	v_lshl_add_u64 v[146:147], s[64:65], 0, v[182:183]
	s_mov_b32 m0, s36
	s_nop 0
	global_load_lds_dwordx4 v[146:147], off
	s_waitcnt lgkmcnt(0)
	s_barrier
	v_mfma_f32_16x16x32_bf16 v[146:149], v[74:77], v[126:129], v[166:169]
	v_mfma_f32_16x16x32_bf16 v[166:169], v[82:85], v[130:133], v[146:149]
	v_mfma_f32_16x16x32_bf16 v[146:149], v[86:89], v[126:129], v[162:165]
	v_mfma_f32_16x16x32_bf16 v[142:145], v[74:77], v[134:137], v[142:145]
	v_mfma_f32_16x16x32_bf16 v[138:141], v[86:89], v[134:137], v[138:141]
	v_mfma_f32_16x16x32_bf16 v[118:121], v[74:77], v[158:161], v[118:121]
	v_mfma_f32_16x16x32_bf16 v[114:117], v[86:89], v[158:161], v[114:117]
	v_mfma_f32_16x16x32_bf16 v[90:93], v[74:77], v[174:177], v[90:93]
	v_mfma_f32_16x16x32_bf16 v[78:81], v[86:89], v[174:177], v[78:81]
	v_mfma_f32_16x16x32_bf16 v[162:165], v[94:97], v[130:133], v[146:149]
	v_mfma_f32_16x16x32_bf16 v[142:145], v[82:85], v[154:157], v[142:145]
	v_mfma_f32_16x16x32_bf16 v[138:141], v[94:97], v[154:157], v[138:141]
	v_mfma_f32_16x16x32_bf16 v[118:121], v[82:85], v[170:173], v[118:121]
	v_mfma_f32_16x16x32_bf16 v[114:117], v[94:97], v[170:173], v[114:117]
	v_mfma_f32_16x16x32_bf16 v[90:93], v[82:85], v[192:195], v[90:93]
	v_mfma_f32_16x16x32_bf16 v[78:81], v[94:97], v[192:195], v[78:81]
	s_barrier
	s_add_i32 s64, 0, 0x1c000
	v_add_u32_e32 v146, s64, v201
	s_add_i32 s65, s72, s1
	ds_read_b128 v[196:199], v146
	ds_read_b128 v[204:207], v146 offset:1024
	ds_read_b128 v[226:229], v146 offset:2048
	ds_read_b128 v[230:233], v146 offset:3072
	v_lshl_add_u64 v[146:147], v[208:209], 0, s[86:87]
	s_mov_b32 m0, s65
	s_nop 0
	global_load_lds_dwordx4 v[146:147], off
	v_lshl_add_u64 v[146:147], v[234:235], 0, s[86:87]
	s_add_i32 m0, s65, 0x2000
	s_nop 0
	global_load_lds_dwordx4 v[146:147], off
	s_waitcnt lgkmcnt(0)
	s_barrier
	v_mfma_f32_16x16x32_bf16 v[146:149], v[196:199], v[126:129], v[150:153]
	v_mfma_f32_16x16x32_bf16 v[106:109], v[226:229], v[126:129], v[106:109]
	v_mfma_f32_16x16x32_bf16 v[150:153], v[204:207], v[130:133], v[146:149]
	v_mfma_f32_16x16x32_bf16 v[146:149], v[230:233], v[130:133], v[106:109]
	v_mfma_f32_16x16x32_bf16 v[106:109], v[196:199], v[134:137], v[110:113]
	v_mfma_f32_16x16x32_bf16 v[126:129], v[204:207], v[154:157], v[106:109]
	v_mfma_f32_16x16x32_bf16 v[106:109], v[226:229], v[134:137], v[122:125]
	v_mfma_f32_16x16x32_bf16 v[102:105], v[196:199], v[158:161], v[102:105]
	v_mfma_f32_16x16x32_bf16 v[98:101], v[226:229], v[158:161], v[98:101]
	v_mfma_f32_16x16x32_bf16 v[70:73], v[196:199], v[174:177], v[70:73]
	v_mfma_f32_16x16x32_bf16 v[66:69], v[226:229], v[174:177], v[66:69]
	v_mfma_f32_16x16x32_bf16 v[122:125], v[230:233], v[154:157], v[106:109]
	v_mfma_f32_16x16x32_bf16 v[102:105], v[204:207], v[170:173], v[102:105]
	v_mfma_f32_16x16x32_bf16 v[98:101], v[230:233], v[170:173], v[98:101]
	v_mfma_f32_16x16x32_bf16 v[70:73], v[204:207], v[192:195], v[70:73]
	v_mfma_f32_16x16x32_bf16 v[66:69], v[230:233], v[192:195], v[66:69]
	s_mov_b32 m0, s50
	v_lshl_add_u64 v[192:193], v[236:237], 0, s[86:87]
	s_barrier
; #define PG8_STAGE(bufoff, gbase, voff) do { _Pragma("unroll") for (int _i = 0; _i < 2; ++_i) \
;         __builtin_amdgcn_global_load_lds((const unsigned*)((const char*)(gbase) + (voff)[_i]), (LAS unsigned*)(lds + (bufoff) + ldsw + _i * 8192), 16, 0, 0); } while (0)
; #define PG8_LDA(dst, b, h) do { _Pragma("unroll") for (int m = 0; m < 4; ++m) _Pragma("unroll") for (int k = 0; k < 2; ++k) dst[m][k] = *(const LAS bf16x8*)(lds + PG8_SA(b, h) + aoff + m * 2048 + k * 1024); } while (0)
; #define PG8_MMA(ai, bj, At, Bt) do { __builtin_amdgcn_s_setprio(1); _Pragma("unroll") for (int m = 0; m < 4; ++m) _Pragma("unroll") for (int n = 0; n < 2; ++n) _Pragma("unroll") for (int k = 0; k < 2; ++k) \
;         acc[ai][bj][m][n] = __builtin_amdgcn_mfma_f32_16x16x32_bf16(Bt[n][k], At[m][k], acc[ai][bj][m][n], 0, 0, 0); __builtin_amdgcn_s_setprio(0); } while (0)
; #define PG8_WAIT_V(n) asm volatile("s_waitcnt vmcnt(" #n ")" ::: "memory")
; template <class Epi>
; __device__ __forceinline__ void gemm_phase(LAS unsigned char* lds, const Gemm g, const Epi& E) {
;     ...
;             PG8_LDA(At, 1, 1); PG8_STAGE(PG8_SA(1, 0), a3, voffA);
;             PG8_BAR; PG8_WAIT_L(0); PG8_MMA(1, 0, At, B0); PG8_BAR; PG8_SCHED;
;             PG8_STAGE(PG8_SB(1, 1), b3 + hstepB, voffB);
;             PG8_WAIT_V(6); PG8_BAR; PG8_MMA(1, 1, At, B1); PG8_BAR;
;     __device__ __forceinline__ void operator()(const AccT& acc, const Unit& u, int wr, int wc, int fr, int fq) const {
;     ...
;         const int gpm = mapA.src(u.pm);
;         const bool isq = u.pn < 4, isv = u.pn >= 8;
;         const bool lat = gpm >= 32 && !isv;
;         bf16_t* base = isq ? Q : (isv ? Vv + (size_t)(u.pn - 8) * 256 : Kk);
;         const int hh = isv ? 0 : (u.pn & 3);
;         const int ldo = isv ? 2048 : 1024;
;         const float osc = isq ? 0.0625f : 1.0f;
;         const int p0 = 16 * wc + 4 * fq;
;         f32x4 ctR[2][2], ctC[4][2];
;         if (lat) {
; #pragma unroll
;             for (int ai = 0; ai < 2; ++ai) { const int pr = ((gpm - 32) * 4 + 2 * ai + wr) & 31;
;                 ctR[ai][0] = *(const f32x4*)(cs + pr * 64 + p0); ctR[ai][1] = *(const f32x4*)(cs + pr * 64 + p0 + 2); }
; #pragma unroll
;             for (int m = 0; m < 4; ++m) { const int pc = m * 16 + fr;
;                 ctC[m][0] = *(const f32x4*)(cs + pc * 64 + p0); ctC[m][1] = *(const f32x4*)(cs + pc * 64 + p0 + 2); }
;         }
	ds_read_b128 v[106:109], v202 offset:49152
	ds_read_b128 v[110:113], v202 offset:50176
	ds_read_b128 v[130:133], v202 offset:51200
	ds_read_b128 v[134:137], v202 offset:52224
	ds_read_b128 v[154:157], v202 offset:53248
	ds_read_b128 v[158:161], v202 offset:54272
	ds_read_b128 v[170:173], v202 offset:55296
	ds_read_b128 v[174:177], v202 offset:56320
	global_load_lds_dwordx4 v[192:193], off
	v_lshl_add_u64 v[192:193], v[238:239], 0, s[86:87]
	s_mov_b32 m0, s66
	s_nop 0
	global_load_lds_dwordx4 v[192:193], off
	s_waitcnt lgkmcnt(0)
	s_barrier
	v_mfma_f32_16x16x32_bf16 v[62:65], v[74:77], v[106:109], v[62:65]
	v_mfma_f32_16x16x32_bf16 v[58:61], v[86:89], v[106:109], v[58:61]
	v_mfma_f32_16x16x32_bf16 v[46:49], v[74:77], v[130:133], v[46:49]
	v_mfma_f32_16x16x32_bf16 v[42:45], v[86:89], v[130:133], v[42:45]
	v_mfma_f32_16x16x32_bf16 v[30:33], v[74:77], v[154:157], v[30:33]
	v_mfma_f32_16x16x32_bf16 v[26:29], v[86:89], v[154:157], v[26:29]
	v_mfma_f32_16x16x32_bf16 v[14:17], v[74:77], v[170:173], v[14:17]
	v_mfma_f32_16x16x32_bf16 v[10:13], v[86:89], v[170:173], v[10:13]
	v_mfma_f32_16x16x32_bf16 v[62:65], v[82:85], v[110:113], v[62:65]
	v_mfma_f32_16x16x32_bf16 v[58:61], v[94:97], v[110:113], v[58:61]
	v_mfma_f32_16x16x32_bf16 v[46:49], v[82:85], v[134:137], v[46:49]
	v_mfma_f32_16x16x32_bf16 v[42:45], v[94:97], v[134:137], v[42:45]
	v_mfma_f32_16x16x32_bf16 v[30:33], v[82:85], v[158:161], v[30:33]
	v_mfma_f32_16x16x32_bf16 v[26:29], v[94:97], v[158:161], v[26:29]
	v_mfma_f32_16x16x32_bf16 v[14:17], v[82:85], v[174:177], v[14:17]
	v_mfma_f32_16x16x32_bf16 v[10:13], v[94:97], v[174:177], v[10:13]
	s_barrier
	s_add_u32 s60, s60, 0x40080
	s_addc_u32 s61, s61, 0
	s_add_i32 s64, s64, s1
	v_lshl_add_u64 v[74:75], s[60:61], 0, v[184:185]
	s_mov_b32 m0, s64
	s_nop 0
	global_load_lds_dwordx4 v[74:75], off
	v_lshl_add_u64 v[74:75], s[60:61], 0, v[180:181]
	s_add_i32 m0, s64, 0x2000
	s_nop 0
	global_load_lds_dwordx4 v[74:75], off
	s_add_i32 s53, s53, 2
	s_add_u32 s4, s4, 0x100
	s_addc_u32 s5, s5, 0
	s_add_u32 s15, s15, 0x100
	s_addc_u32 s52, s52, 0
	s_cmp_gt_u32 s53, 13
	s_waitcnt vmcnt(6)
	s_barrier
	v_mfma_f32_16x16x32_bf16 v[54:57], v[196:199], v[106:109], v[54:57]
	v_mfma_f32_16x16x32_bf16 v[50:53], v[226:229], v[106:109], v[50:53]
	v_mfma_f32_16x16x32_bf16 v[38:41], v[196:199], v[130:133], v[38:41]
	v_mfma_f32_16x16x32_bf16 v[34:37], v[226:229], v[130:133], v[34:37]
	v_mfma_f32_16x16x32_bf16 v[22:25], v[196:199], v[154:157], v[22:25]
	v_mfma_f32_16x16x32_bf16 v[18:21], v[226:229], v[154:157], v[18:21]
	v_mfma_f32_16x16x32_bf16 v[6:9], v[196:199], v[170:173], v[6:9]
	v_mfma_f32_16x16x32_bf16 v[2:5], v[226:229], v[170:173], v[2:5]
	v_mfma_f32_16x16x32_bf16 v[54:57], v[204:207], v[110:113], v[54:57]
	v_mfma_f32_16x16x32_bf16 v[50:53], v[230:233], v[110:113], v[50:53]
	v_mfma_f32_16x16x32_bf16 v[38:41], v[204:207], v[134:137], v[38:41]
	v_mfma_f32_16x16x32_bf16 v[34:37], v[230:233], v[134:137], v[34:37]
	v_mfma_f32_16x16x32_bf16 v[22:25], v[204:207], v[158:161], v[22:25]
	v_mfma_f32_16x16x32_bf16 v[18:21], v[230:233], v[158:161], v[18:21]
	v_mfma_f32_16x16x32_bf16 v[6:9], v[204:207], v[174:177], v[6:9]
	v_mfma_f32_16x16x32_bf16 v[2:5], v[230:233], v[174:177], v[2:5]
	s_barrier
	s_cbranch_scc0 .LBB0_331
	s_cmp_lt_i32 s10, 16
	s_cselect_b32 s4, s68, s18
	s_add_i32 s15, s10, s4
	s_cmp_lt_i32 s11, 8
	s_cselect_b64 s[60:61], -1, 0
	s_cmp_gt_i32 s15, 31
	s_cselect_b64 s[4:5], -1, 0
	s_and_b64 s[52:53], s[60:61], s[4:5]
	v_cndmask_b32_e64 v74, 0, 1, s[52:53]
	v_mov_b32_e32 v194, v200
	v_mov_b32_e32 v193, v1
	v_cmp_ne_u32_e64 s[4:5], 1, v74
	s_andn2_b64 vcc, exec, s[52:53]
	s_cbranch_vccnz .LBB0_334
	v_lshl_add_u32 v74, v193, 2, s67
	v_readlane_b32 s52, v254, 2
	s_lshl_b32 s15, s15, 8
	v_ashrrev_i32_e32 v75, 31, v74
	v_readlane_b32 s53, v254, 3
	s_add_i32 s15, s15, s44
	s_nop 0
	v_lshl_add_u64 v[74:75], v[74:75], 3, s[52:53]
	s_and_b32 s52, s15, 0x7c0
	s_addk_i32 s15, 0x80
	s_lshl_b32 s76, s52, 3
	s_and_b32 s15, s15, 0x7c0
	v_lshl_add_u64 v[76:77], v[74:75], 0, s[76:77]
	s_lshl_b32 s76, s15, 3
	global_load_dwordx4 v[170:173], v[76:77], off offset:16
	global_load_dwordx4 v[174:177], v[76:77], off
	v_lshl_add_u64 v[76:77], v[74:75], 0, s[76:77]
	global_load_dwordx4 v[86:89], v[76:77], off offset:16
	global_load_dwordx4 v[94:97], v[76:77], off
	v_lshlrev_b32_e32 v76, 6, v194
	v_ashrrev_i32_e32 v77, 31, v76
	v_lshl_add_u64 v[82:83], v[76:77], 3, v[74:75]
	global_load_dwordx4 v[154:157], v[82:83], off offset:16
	global_load_dwordx4 v[158:161], v[82:83], off
	v_add_u32_e32 v82, 0x400, v76
	v_ashrrev_i32_e32 v83, 31, v82
	v_lshl_add_u64 v[82:83], v[82:83], 3, v[74:75]
	global_load_dwordx4 v[130:133], v[82:83], off offset:16
	global_load_dwordx4 v[134:137], v[82:83], off
	v_add_u32_e32 v82, 0x800, v76
	v_ashrrev_i32_e32 v83, 31, v82
	v_add_u32_e32 v76, 0xc00, v76
	v_lshl_add_u64 v[82:83], v[82:83], 3, v[74:75]
	v_ashrrev_i32_e32 v77, 31, v76
	global_load_dwordx4 v[106:109], v[82:83], off offset:16
	global_load_dwordx4 v[110:113], v[82:83], off
	v_lshl_add_u64 v[82:83], v[76:77], 3, v[74:75]
	global_load_dwordx4 v[74:77], v[82:83], off offset:16
	s_nop 0
	global_load_dwordx4 v[82:85], v[82:83], off

; #define PG8_STAGE(bufoff, gbase, voff) do { _Pragma("unroll") for (int _i = 0; _i < 2; ++_i) \
;         __builtin_amdgcn_global_load_lds((const unsigned*)((const char*)(gbase) + (voff)[_i]), (LAS unsigned*)(lds + (bufoff) + ldsw + _i * 8192), 16, 0, 0); } while (0)
; #define PG8_LDA(dst, b, h) do { _Pragma("unroll") for (int m = 0; m < 4; ++m) _Pragma("unroll") for (int k = 0; k < 2; ++k) dst[m][k] = *(const LAS bf16x8*)(lds + PG8_SA(b, h) + aoff + m * 2048 + k * 1024); } while (0)
; #define PG8_LDB(dst, b, h) do { _Pragma("unroll") for (int n = 0; n < 2; ++n) _Pragma("unroll") for (int k = 0; k < 2; ++k) dst[n][k] = *(const LAS bf16x8*)(lds + PG8_SB(b, h) + boff + n * 2048 + k * 1024); } while (0)
; #define PG8_MMA(ai, bj, At, Bt) do { __builtin_amdgcn_s_setprio(1); _Pragma("unroll") for (int m = 0; m < 4; ++m) _Pragma("unroll") for (int n = 0; n < 2; ++n) _Pragma("unroll") for (int k = 0; k < 2; ++k) \
;         acc[ai][bj][m][n] = __builtin_amdgcn_mfma_f32_16x16x32_bf16(Bt[n][k], At[m][k], acc[ai][bj][m][n], 0, 0, 0); __builtin_amdgcn_s_setprio(0); } while (0)
; #define PG8_WAIT_L(n) asm volatile("s_waitcnt lgkmcnt(" #n ")" ::: "memory")
; #define PG8_BAR __builtin_amdgcn_s_barrier()
; #define PG8_SCHED __builtin_amdgcn_sched_barrier(0)
; template <class Epi>
; __device__ __forceinline__ void gemm_phase(LAS unsigned char* lds, const Gemm g, const Epi& E) {
;     ...
;             const bool last = (t == nt - 2);
;             const char* a1 = cA + (size_t)(t + 1) * kstep;
;             const char* a2 = last ? nA : cA + (size_t)(t + 2) * kstep; const char* b2 = last ? nB : cB + (size_t)(t + 2) * kstep;
;             const char* a3 = a2 + kstep; const char* b3 = b2 + kstep;
;             PG8_LDB(B0, 0, 0); PG8_SCHED; PG8_LDA(At, 0, 0); PG8_STAGE(PG8_SA(1, 1), a1 + hstepA, voffA);
;             PG8_WAIT_L(8); PG8_BAR; PG8_WAIT_L(0); PG8_MMA(0, 0, At, B0); PG8_BAR; PG8_SCHED;
;             PG8_LDB(B1, 0, 1); PG8_STAGE(PG8_SB(0, 0), b2, voffB);
;             PG8_BAR; PG8_WAIT_L(0); PG8_MMA(0, 1, At, B1); PG8_BAR;
;             PG8_LDA(At, 0, 1); PG8_STAGE(PG8_SA(0, 0), a2, voffA);
;             PG8_BAR; PG8_WAIT_L(0); PG8_MMA(1, 0, At, B0); PG8_BAR; PG8_SCHED;
.LBB0_475:
	s_add_u32 s16, s14, 0xfffc0080
	s_addc_u32 s17, s15, -1
	s_add_i32 s66, 0, 0x10000
	v_add_u32_e32 v86, s66, v226
	ds_read_b128 v[66:69], v86
	ds_read_b128 v[70:73], v86 offset:1024
	ds_read_b128 v[82:85], v86 offset:2048
	ds_read_b128 v[86:89], v86 offset:3072
	s_cmp_eq_u32 s65, 12
	s_cselect_b32 s29, s11, s17
	s_cselect_b32 s28, s10, s16
	s_cselect_b32 s17, s5, s53
	s_cselect_b32 s16, s4, s9
	v_lshl_add_u64 v[192:193], s[14:15], 0, v[174:175]
	s_add_i32 m0, s13, 0xc000
	ds_read_b128 v[146:149], v227
	ds_read_b128 v[150:153], v227 offset:1024
	ds_read_b128 v[154:157], v227 offset:2048
	ds_read_b128 v[158:161], v227 offset:3072
	ds_read_b128 v[162:165], v227 offset:4096
	ds_read_b128 v[180:183], v227 offset:5120
	ds_read_b128 v[184:187], v227 offset:6144
	ds_read_b128 v[188:191], v227 offset:7168
	global_load_lds_dwordx4 v[192:193], off
	v_lshl_add_u64 v[192:193], s[14:15], 0, v[176:177]
	s_add_i32 m0, s13, 0xe000
	s_nop 0
	global_load_lds_dwordx4 v[192:193], off
	s_waitcnt lgkmcnt(0)
	s_barrier
	v_mfma_f32_16x16x32_bf16 v[142:145], v[66:69], v[146:149], v[142:145]
	v_mfma_f32_16x16x32_bf16 v[138:141], v[82:85], v[146:149], v[138:141]
	v_mfma_f32_16x16x32_bf16 v[126:129], v[66:69], v[154:157], v[126:129]
	v_mfma_f32_16x16x32_bf16 v[122:125], v[82:85], v[154:157], v[122:125]
	v_mfma_f32_16x16x32_bf16 v[110:113], v[66:69], v[162:165], v[110:113]
	v_mfma_f32_16x16x32_bf16 v[106:109], v[82:85], v[162:165], v[106:109]
	v_mfma_f32_16x16x32_bf16 v[94:97], v[66:69], v[184:187], v[94:97]
	v_mfma_f32_16x16x32_bf16 v[90:93], v[82:85], v[184:187], v[90:93]
	v_mfma_f32_16x16x32_bf16 v[142:145], v[70:73], v[150:153], v[142:145]
	v_mfma_f32_16x16x32_bf16 v[138:141], v[86:89], v[150:153], v[138:141]
	v_mfma_f32_16x16x32_bf16 v[126:129], v[70:73], v[158:161], v[126:129]
	v_mfma_f32_16x16x32_bf16 v[122:125], v[86:89], v[158:161], v[122:125]
	v_mfma_f32_16x16x32_bf16 v[110:113], v[70:73], v[180:183], v[110:113]
	v_mfma_f32_16x16x32_bf16 v[106:109], v[86:89], v[180:183], v[106:109]
	v_mfma_f32_16x16x32_bf16 v[94:97], v[70:73], v[188:191], v[94:97]
	v_mfma_f32_16x16x32_bf16 v[90:93], v[86:89], v[188:191], v[90:93]
	s_barrier
	s_add_i32 s68, 0, 0x14000
	s_add_i32 s66, s66, s18
	v_add_u32_e32 v204, s68, v226
	v_lshl_add_u64 v[208:209], s[16:17], 0, v[170:171]
	s_mov_b32 m0, s66
	ds_read_b128 v[192:195], v204
	ds_read_b128 v[196:199], v204 offset:1024
	ds_read_b128 v[200:203], v204 offset:2048
	ds_read_b128 v[204:207], v204 offset:3072
	global_load_lds_dwordx4 v[208:209], off
	v_lshl_add_u64 v[228:229], s[16:17], 0, v[166:167]
	s_add_i32 m0, s66, 0x2000
	s_nop 0
	global_load_lds_dwordx4 v[228:229], off
	s_nop 1
	s_mov_b32 m0, s13
	v_lshl_add_u64 v[230:231], s[28:29], 0, v[172:173]
	s_waitcnt lgkmcnt(0)
	s_barrier
	v_mfma_f32_16x16x32_bf16 v[134:137], v[192:195], v[146:149], v[134:137]
	v_mfma_f32_16x16x32_bf16 v[130:133], v[200:203], v[146:149], v[130:133]
	v_mfma_f32_16x16x32_bf16 v[118:121], v[192:195], v[154:157], v[118:121]
	v_mfma_f32_16x16x32_bf16 v[114:117], v[200:203], v[154:157], v[114:117]
	v_mfma_f32_16x16x32_bf16 v[102:105], v[192:195], v[162:165], v[102:105]
	v_mfma_f32_16x16x32_bf16 v[98:101], v[200:203], v[162:165], v[98:101]
	v_mfma_f32_16x16x32_bf16 v[78:81], v[192:195], v[184:187], v[78:81]
	v_mfma_f32_16x16x32_bf16 v[74:77], v[200:203], v[184:187], v[74:77]
	v_mfma_f32_16x16x32_bf16 v[134:137], v[196:199], v[150:153], v[134:137]
	v_mfma_f32_16x16x32_bf16 v[130:133], v[204:207], v[150:153], v[130:133]
	v_mfma_f32_16x16x32_bf16 v[118:121], v[196:199], v[158:161], v[118:121]
	v_mfma_f32_16x16x32_bf16 v[114:117], v[204:207], v[158:161], v[114:117]
	v_mfma_f32_16x16x32_bf16 v[102:105], v[196:199], v[180:183], v[102:105]
	v_mfma_f32_16x16x32_bf16 v[98:101], v[204:207], v[180:183], v[98:101]
	v_mfma_f32_16x16x32_bf16 v[78:81], v[196:199], v[188:191], v[78:81]
	v_mfma_f32_16x16x32_bf16 v[74:77], v[204:207], v[188:191], v[74:77]
	s_barrier
	ds_read_b128 v[146:149], v227 offset:16384
	ds_read_b128 v[150:153], v227 offset:17408
	ds_read_b128 v[154:157], v227 offset:18432
	ds_read_b128 v[158:161], v227 offset:19456
	ds_read_b128 v[162:165], v227 offset:20480
	ds_read_b128 v[180:183], v227 offset:21504
	ds_read_b128 v[184:187], v227 offset:22528
	ds_read_b128 v[188:191], v227 offset:23552
	global_load_lds_dwordx4 v[230:231], off
	v_lshl_add_u64 v[232:233], s[28:29], 0, v[168:169]
	s_mov_b32 m0, s31
	s_nop 0
	global_load_lds_dwordx4 v[232:233], off
	s_waitcnt lgkmcnt(0)
	s_barrier
	v_mfma_f32_16x16x32_bf16 v[62:65], v[66:69], v[146:149], v[62:65]
	v_mfma_f32_16x16x32_bf16 v[58:61], v[82:85], v[146:149], v[58:61]
	v_mfma_f32_16x16x32_bf16 v[46:49], v[66:69], v[154:157], v[46:49]
	v_mfma_f32_16x16x32_bf16 v[42:45], v[82:85], v[154:157], v[42:45]
	v_mfma_f32_16x16x32_bf16 v[30:33], v[66:69], v[162:165], v[30:33]
	v_mfma_f32_16x16x32_bf16 v[26:29], v[82:85], v[162:165], v[26:29]
	v_mfma_f32_16x16x32_bf16 v[14:17], v[66:69], v[184:187], v[14:17]
	v_mfma_f32_16x16x32_bf16 v[10:13], v[82:85], v[184:187], v[10:13]
	v_mfma_f32_16x16x32_bf16 v[62:65], v[70:73], v[150:153], v[62:65]
	v_mfma_f32_16x16x32_bf16 v[58:61], v[86:89], v[150:153], v[58:61]
	v_mfma_f32_16x16x32_bf16 v[46:49], v[70:73], v[158:161], v[46:49]
	v_mfma_f32_16x16x32_bf16 v[42:45], v[86:89], v[158:161], v[42:45]
	v_mfma_f32_16x16x32_bf16 v[30:33], v[70:73], v[180:183], v[30:33]
	v_mfma_f32_16x16x32_bf16 v[26:29], v[86:89], v[180:183], v[26:29]
	v_mfma_f32_16x16x32_bf16 v[14:17], v[70:73], v[188:191], v[14:17]
	v_mfma_f32_16x16x32_bf16 v[10:13], v[86:89], v[188:191], v[10:13]
	s_barrier
; #define PG8_STAGE(bufoff, gbase, voff) do { _Pragma("unroll") for (int _i = 0; _i < 2; ++_i) \
;         __builtin_amdgcn_global_load_lds((const unsigned*)((const char*)(gbase) + (voff)[_i]), (LAS unsigned*)(lds + (bufoff) + ldsw + _i * 8192), 16, 0, 0); } while (0)
; #define PG8_LDA(dst, b, h) do { _Pragma("unroll") for (int m = 0; m < 4; ++m) _Pragma("unroll") for (int k = 0; k < 2; ++k) dst[m][k] = *(const LAS bf16x8*)(lds + PG8_SA(b, h) + aoff + m * 2048 + k * 1024); } while (0)
; #define PG8_LDB(dst, b, h) do { _Pragma("unroll") for (int n = 0; n < 2; ++n) _Pragma("unroll") for (int k = 0; k < 2; ++k) dst[n][k] = *(const LAS bf16x8*)(lds + PG8_SB(b, h) + boff + n * 2048 + k * 1024); } while (0)
; #define PG8_MMA(ai, bj, At, Bt) do { __builtin_amdgcn_s_setprio(1); _Pragma("unroll") for (int m = 0; m < 4; ++m) _Pragma("unroll") for (int n = 0; n < 2; ++n) _Pragma("unroll") for (int k = 0; k < 2; ++k) \
;         acc[ai][bj][m][n] = __builtin_amdgcn_mfma_f32_16x16x32_bf16(Bt[n][k], At[m][k], acc[ai][bj][m][n], 0, 0, 0); __builtin_amdgcn_s_setprio(0); } while (0)
; #define PG8_WAIT_V(n) asm volatile("s_waitcnt vmcnt(" #n ")" ::: "memory")
; #define PG8_WAIT_L(n) asm volatile("s_waitcnt lgkmcnt(" #n ")" ::: "memory")
; #define PG8_BAR __builtin_amdgcn_s_barrier()
; #define PG8_SCHED __builtin_amdgcn_sched_barrier(0)
; template <class Epi>
; __device__ __forceinline__ void gemm_phase(LAS unsigned char* lds, const Gemm g, const Epi& E) {
;     ...
;             PG8_STAGE(PG8_SB(0, 1), b2 + hstepB, voffB);
;             PG8_WAIT_V(6); PG8_BAR; PG8_MMA(1, 1, At, B1); PG8_BAR;
;             PG8_LDB(B0, 1, 0); PG8_SCHED; PG8_LDA(At, 1, 0); PG8_STAGE(PG8_SA(0, 1), a2 + hstepA, voffA);
;             PG8_WAIT_L(8); PG8_BAR; PG8_WAIT_L(0); PG8_MMA(0, 0, At, B0); PG8_BAR; PG8_SCHED;
;             PG8_LDB(B1, 1, 1); PG8_STAGE(PG8_SB(1, 0), b3, voffB);
;             PG8_BAR; PG8_WAIT_L(0); PG8_MMA(0, 1, At, B1); PG8_BAR;
;             PG8_LDA(At, 1, 1); PG8_STAGE(PG8_SA(1, 0), a3, voffA);
	s_add_u32 s66, s16, 0x40000
	s_addc_u32 s67, s17, 0
	s_add_i32 s68, s68, s18
	v_lshl_add_u64 v[66:67], s[66:67], 0, v[170:171]
	s_mov_b32 m0, s68
	s_nop 0
	global_load_lds_dwordx4 v[66:67], off
	v_lshl_add_u64 v[66:67], s[66:67], 0, v[166:167]
	s_add_i32 m0, s68, 0x2000
	s_nop 0
	global_load_lds_dwordx4 v[66:67], off
	s_add_i32 s66, 0, 0x18000
	v_add_u32_e32 v86, s66, v226
	s_waitcnt vmcnt(6)
	s_barrier
	v_mfma_f32_16x16x32_bf16 v[54:57], v[192:195], v[146:149], v[54:57]
	v_mfma_f32_16x16x32_bf16 v[50:53], v[200:203], v[146:149], v[50:53]
	v_mfma_f32_16x16x32_bf16 v[38:41], v[192:195], v[154:157], v[38:41]
	v_mfma_f32_16x16x32_bf16 v[34:37], v[200:203], v[154:157], v[34:37]
	v_mfma_f32_16x16x32_bf16 v[22:25], v[192:195], v[162:165], v[22:25]
	v_mfma_f32_16x16x32_bf16 v[18:21], v[200:203], v[162:165], v[18:21]
	v_mfma_f32_16x16x32_bf16 v[6:9], v[192:195], v[184:187], v[6:9]
	v_mfma_f32_16x16x32_bf16 v[2:5], v[200:203], v[184:187], v[2:5]
	v_mfma_f32_16x16x32_bf16 v[54:57], v[196:199], v[150:153], v[54:57]
	v_mfma_f32_16x16x32_bf16 v[50:53], v[204:207], v[150:153], v[50:53]
	v_mfma_f32_16x16x32_bf16 v[38:41], v[196:199], v[158:161], v[38:41]
	v_mfma_f32_16x16x32_bf16 v[34:37], v[204:207], v[158:161], v[34:37]
	v_mfma_f32_16x16x32_bf16 v[22:25], v[196:199], v[180:183], v[22:25]
	v_mfma_f32_16x16x32_bf16 v[18:21], v[204:207], v[180:183], v[18:21]
	v_mfma_f32_16x16x32_bf16 v[6:9], v[196:199], v[188:191], v[6:9]
	v_mfma_f32_16x16x32_bf16 v[2:5], v[204:207], v[188:191], v[2:5]
	s_barrier
	ds_read_b128 v[66:69], v86
	ds_read_b128 v[70:73], v86 offset:1024
	ds_read_b128 v[82:85], v86 offset:2048
	ds_read_b128 v[86:89], v86 offset:3072
	s_add_u32 s28, s28, 0x40000
	s_addc_u32 s29, s29, 0
	s_mov_b32 m0, s36
	v_lshl_add_u64 v[192:193], s[28:29], 0, v[172:173]
	ds_read_b128 v[146:149], v227 offset:32768
	ds_read_b128 v[150:153], v227 offset:33792
	ds_read_b128 v[154:157], v227 offset:34816
	ds_read_b128 v[158:161], v227 offset:35840
	ds_read_b128 v[162:165], v227 offset:36864
	ds_read_b128 v[180:183], v227 offset:37888
	ds_read_b128 v[184:187], v227 offset:38912
	ds_read_b128 v[188:191], v227 offset:39936
	global_load_lds_dwordx4 v[192:193], off
	v_lshl_add_u64 v[192:193], s[28:29], 0, v[168:169]
	s_mov_b32 m0, s44
	s_nop 0
	global_load_lds_dwordx4 v[192:193], off
	s_waitcnt lgkmcnt(0)
	s_barrier
	v_mfma_f32_16x16x32_bf16 v[142:145], v[66:69], v[146:149], v[142:145]
	v_mfma_f32_16x16x32_bf16 v[138:141], v[82:85], v[146:149], v[138:141]
	v_mfma_f32_16x16x32_bf16 v[126:129], v[66:69], v[154:157], v[126:129]
	v_mfma_f32_16x16x32_bf16 v[122:125], v[82:85], v[154:157], v[122:125]
	v_mfma_f32_16x16x32_bf16 v[110:113], v[66:69], v[162:165], v[110:113]
	v_mfma_f32_16x16x32_bf16 v[106:109], v[82:85], v[162:165], v[106:109]
	v_mfma_f32_16x16x32_bf16 v[94:97], v[66:69], v[184:187], v[94:97]
	v_mfma_f32_16x16x32_bf16 v[90:93], v[82:85], v[184:187], v[90:93]
	v_mfma_f32_16x16x32_bf16 v[142:145], v[70:73], v[150:153], v[142:145]
	v_mfma_f32_16x16x32_bf16 v[138:141], v[86:89], v[150:153], v[138:141]
	v_mfma_f32_16x16x32_bf16 v[126:129], v[70:73], v[158:161], v[126:129]
	v_mfma_f32_16x16x32_bf16 v[122:125], v[86:89], v[158:161], v[122:125]
	v_mfma_f32_16x16x32_bf16 v[110:113], v[70:73], v[180:183], v[110:113]
	v_mfma_f32_16x16x32_bf16 v[106:109], v[86:89], v[180:183], v[106:109]
	v_mfma_f32_16x16x32_bf16 v[94:97], v[70:73], v[188:191], v[94:97]
	v_mfma_f32_16x16x32_bf16 v[90:93], v[86:89], v[188:191], v[90:93]
	s_barrier
	s_add_i32 s28, 0, 0x1c000
	s_add_i32 s29, s66, s18
	v_add_u32_e32 v204, s28, v226
	v_lshl_add_u64 v[208:209], v[208:209], 0, s[86:87]
	s_mov_b32 m0, s29
	ds_read_b128 v[192:195], v204
	ds_read_b128 v[196:199], v204 offset:1024
	ds_read_b128 v[200:203], v204 offset:2048
	ds_read_b128 v[204:207], v204 offset:3072
	global_load_lds_dwordx4 v[208:209], off
	v_lshl_add_u64 v[208:209], v[228:229], 0, s[86:87]
	s_add_i32 m0, s29, 0x2000
	s_nop 0
	global_load_lds_dwordx4 v[208:209], off
	s_nop 1
	s_mov_b32 m0, s59
	v_lshl_add_u64 v[208:209], v[230:231], 0, s[86:87]
	s_waitcnt lgkmcnt(0)
	s_barrier
	v_mfma_f32_16x16x32_bf16 v[134:137], v[192:195], v[146:149], v[134:137]
	v_mfma_f32_16x16x32_bf16 v[130:133], v[200:203], v[146:149], v[130:133]
	v_mfma_f32_16x16x32_bf16 v[118:121], v[192:195], v[154:157], v[118:121]
	v_mfma_f32_16x16x32_bf16 v[114:117], v[200:203], v[154:157], v[114:117]
	v_mfma_f32_16x16x32_bf16 v[102:105], v[192:195], v[162:165], v[102:105]
	v_mfma_f32_16x16x32_bf16 v[98:101], v[200:203], v[162:165], v[98:101]
	v_mfma_f32_16x16x32_bf16 v[78:81], v[192:195], v[184:187], v[78:81]
	v_mfma_f32_16x16x32_bf16 v[74:77], v[200:203], v[184:187], v[74:77]
	v_mfma_f32_16x16x32_bf16 v[134:137], v[196:199], v[150:153], v[134:137]
	v_mfma_f32_16x16x32_bf16 v[130:133], v[204:207], v[150:153], v[130:133]
	v_mfma_f32_16x16x32_bf16 v[118:121], v[196:199], v[158:161], v[118:121]
	v_mfma_f32_16x16x32_bf16 v[114:117], v[204:207], v[158:161], v[114:117]
	v_mfma_f32_16x16x32_bf16 v[102:105], v[196:199], v[180:183], v[102:105]
	v_mfma_f32_16x16x32_bf16 v[98:101], v[204:207], v[180:183], v[98:101]
	v_mfma_f32_16x16x32_bf16 v[78:81], v[196:199], v[188:191], v[78:81]
	v_mfma_f32_16x16x32_bf16 v[74:77], v[204:207], v[188:191], v[74:77]
	s_barrier
	ds_read_b128 v[146:149], v227 offset:49152
	ds_read_b128 v[150:153], v227 offset:50176
	ds_read_b128 v[154:157], v227 offset:51200
	ds_read_b128 v[158:161], v227 offset:52224
	ds_read_b128 v[162:165], v227 offset:53248
	ds_read_b128 v[180:183], v227 offset:54272
	ds_read_b128 v[184:187], v227 offset:55296
	ds_read_b128 v[188:191], v227 offset:56320
	global_load_lds_dwordx4 v[208:209], off
	v_lshl_add_u64 v[208:209], v[232:233], 0, s[86:87]
	s_mov_b32 m0, s60
	s_nop 0
	global_load_lds_dwordx4 v[208:209], off
	s_waitcnt lgkmcnt(0)
	s_barrier
; #define PG8_STAGE(bufoff, gbase, voff) do { _Pragma("unroll") for (int _i = 0; _i < 2; ++_i) \
;         __builtin_amdgcn_global_load_lds((const unsigned*)((const char*)(gbase) + (voff)[_i]), (LAS unsigned*)(lds + (bufoff) + ldsw + _i * 8192), 16, 0, 0); } while (0)
; #define PG8_MMA(ai, bj, At, Bt) do { __builtin_amdgcn_s_setprio(1); _Pragma("unroll") for (int m = 0; m < 4; ++m) _Pragma("unroll") for (int n = 0; n < 2; ++n) _Pragma("unroll") for (int k = 0; k < 2; ++k) \
;         acc[ai][bj][m][n] = __builtin_amdgcn_mfma_f32_16x16x32_bf16(Bt[n][k], At[m][k], acc[ai][bj][m][n], 0, 0, 0); __builtin_amdgcn_s_setprio(0); } while (0)
; #define PG8_WAIT_V(n) asm volatile("s_waitcnt vmcnt(" #n ")" ::: "memory")
; #define PG8_WAIT_L(n) asm volatile("s_waitcnt lgkmcnt(" #n ")" ::: "memory")
; #define PG8_BAR __builtin_amdgcn_s_barrier()
; #define PG8_SCHED __builtin_amdgcn_sched_barrier(0)
; template <class Epi>
; __device__ __forceinline__ void gemm_phase(LAS unsigned char* lds, const Gemm g, const Epi& E) {
;     ...
;             PG8_BAR; PG8_WAIT_L(0); PG8_MMA(1, 0, At, B0); PG8_BAR; PG8_SCHED;
;             PG8_STAGE(PG8_SB(1, 1), b3 + hstepB, voffB);
;             PG8_WAIT_V(6); PG8_BAR; PG8_MMA(1, 1, At, B1); PG8_BAR;
;     __device__ __forceinline__ void operator()(const AccT& acc, const Unit& u, int wr, int wc, int fr, int fq) const {
;     ...
;         const int row0 = mapA.src(u.pm) * 256 + wr * 64 + fr, col0 = u.pn * 256 + wc * 32 + 8 * fq;
;         const int hd = u.pn >> 1;
;         f32x4 gw[2][2]; f32x2 st[2][4];
; #pragma unroll
;         for (int bj = 0; bj < 2; ++bj) { gw[bj][0] = *(const f32x4*)(gnw + col0 + bj * 128); gw[bj][1] = *(const f32x4*)(gnw + col0 + bj * 128 + 4); }
; #pragma unroll
;         for (int ai = 0; ai < 2; ++ai)
; #pragma unroll
;             for (int m = 0; m < 4; ++m) st[ai][m] = ST[(size_t)(row0 + ai * 128 + m * 16) * 4 + hd];
; #pragma unroll
;         for (int ai = 0; ai < 2; ++ai) {
;             u32x4 yv[4][2];
; #pragma unroll
;             for (int m = 0; m < 4; ++m)
; #pragma unroll
;                 for (int bj = 0; bj < 2; ++bj) yv[m][bj] = *(const u32x4*)(Y + (size_t)(row0 + ai * 128 + m * 16) * 2048 + col0 + bj * 128);
	v_mfma_f32_16x16x32_bf16 v[62:65], v[66:69], v[146:149], v[62:65]
	v_mfma_f32_16x16x32_bf16 v[58:61], v[82:85], v[146:149], v[58:61]
	v_mfma_f32_16x16x32_bf16 v[46:49], v[66:69], v[154:157], v[46:49]
	v_mfma_f32_16x16x32_bf16 v[42:45], v[82:85], v[154:157], v[42:45]
	v_mfma_f32_16x16x32_bf16 v[30:33], v[66:69], v[162:165], v[30:33]
	v_mfma_f32_16x16x32_bf16 v[26:29], v[82:85], v[162:165], v[26:29]
	v_mfma_f32_16x16x32_bf16 v[14:17], v[66:69], v[184:187], v[14:17]
	v_mfma_f32_16x16x32_bf16 v[10:13], v[82:85], v[184:187], v[10:13]
	v_mfma_f32_16x16x32_bf16 v[62:65], v[70:73], v[150:153], v[62:65]
	v_mfma_f32_16x16x32_bf16 v[58:61], v[86:89], v[150:153], v[58:61]
	v_mfma_f32_16x16x32_bf16 v[46:49], v[70:73], v[158:161], v[46:49]
	v_mfma_f32_16x16x32_bf16 v[42:45], v[86:89], v[158:161], v[42:45]
	v_mfma_f32_16x16x32_bf16 v[30:33], v[70:73], v[180:183], v[30:33]
	v_mfma_f32_16x16x32_bf16 v[26:29], v[86:89], v[180:183], v[26:29]
	v_mfma_f32_16x16x32_bf16 v[14:17], v[70:73], v[188:191], v[14:17]
	v_mfma_f32_16x16x32_bf16 v[10:13], v[86:89], v[188:191], v[10:13]
	s_barrier
	s_add_u32 s16, s16, 0x40080
	s_addc_u32 s17, s17, 0
	s_add_i32 s28, s28, s18
	v_lshl_add_u64 v[66:67], s[16:17], 0, v[170:171]
	s_mov_b32 m0, s28
	s_nop 0
	global_load_lds_dwordx4 v[66:67], off
	v_lshl_add_u64 v[66:67], s[16:17], 0, v[166:167]
	s_add_i32 m0, s28, 0x2000
	s_nop 0
	global_load_lds_dwordx4 v[66:67], off
	s_add_i32 s65, s65, 2
	s_add_u32 s14, s14, 0x100
	s_addc_u32 s15, s15, 0
	s_add_u32 s9, s9, 0x100
	s_addc_u32 s53, s53, 0
	s_cmp_gt_u32 s65, 13
	s_waitcnt vmcnt(6)
	s_barrier
	v_mfma_f32_16x16x32_bf16 v[54:57], v[192:195], v[146:149], v[54:57]
	v_mfma_f32_16x16x32_bf16 v[50:53], v[200:203], v[146:149], v[50:53]
	v_mfma_f32_16x16x32_bf16 v[38:41], v[192:195], v[154:157], v[38:41]
	v_mfma_f32_16x16x32_bf16 v[34:37], v[200:203], v[154:157], v[34:37]
	v_mfma_f32_16x16x32_bf16 v[22:25], v[192:195], v[162:165], v[22:25]
	v_mfma_f32_16x16x32_bf16 v[18:21], v[200:203], v[162:165], v[18:21]
	v_mfma_f32_16x16x32_bf16 v[6:9], v[192:195], v[184:187], v[6:9]
	v_mfma_f32_16x16x32_bf16 v[2:5], v[200:203], v[184:187], v[2:5]
	v_mfma_f32_16x16x32_bf16 v[54:57], v[196:199], v[150:153], v[54:57]
	v_mfma_f32_16x16x32_bf16 v[50:53], v[204:207], v[150:153], v[50:53]
	v_mfma_f32_16x16x32_bf16 v[38:41], v[196:199], v[158:161], v[38:41]
	v_mfma_f32_16x16x32_bf16 v[34:37], v[204:207], v[158:161], v[34:37]
	v_mfma_f32_16x16x32_bf16 v[22:25], v[196:199], v[180:183], v[22:25]
	v_mfma_f32_16x16x32_bf16 v[18:21], v[204:207], v[180:183], v[18:21]
	v_mfma_f32_16x16x32_bf16 v[6:9], v[196:199], v[188:191], v[6:9]
	v_mfma_f32_16x16x32_bf16 v[2:5], v[204:207], v[188:191], v[2:5]
	s_barrier
	s_cbranch_scc0 .LBB0_475
	v_readlane_b32 s9, v255, 27
	s_cmp_ge_i32 s52, s9
	s_cselect_b32 s9, s25, 0
	s_lshl_b32 s14, s12, 8
	v_mov_b32_e32 v148, v225
	v_mov_b32_e32 v66, v1
	s_add_i32 s9, s52, s9
	s_or_b32 s14, s14, s58
	s_lshl_b32 s9, s9, 8
	v_lshl_add_u32 v146, v66, 3, s14
	s_ashr_i32 s14, s12, 1
	s_add_i32 s9, s9, s50
	s_ashr_i32 s15, s14, 31
	v_add_u32_e32 v148, s9, v148
	s_lshl_b64 s[14:15], s[14:15], 3
	s_add_u32 s14, s26, s14
	v_ashrrev_i32_e32 v149, 31, v148
	v_add_u32_e32 v152, 16, v148
	v_add_u32_e32 v156, 32, v148
	v_add_u32_e32 v202, 48, v148
	v_ashrrev_i32_e32 v147, 31, v146
	s_addc_u32 s15, s27, s15
	v_lshlrev_b64 v[150:151], 5, v[148:149]
	v_ashrrev_i32_e32 v153, 31, v152
	v_ashrrev_i32_e32 v157, 31, v156
	v_ashrrev_i32_e32 v203, 31, v202
	v_add_u32_e32 v190, 0x80, v148
	v_lshl_add_u64 v[70:71], v[146:147], 2, s[6:7]
	v_lshl_add_u64 v[150:151], s[14:15], 0, v[150:151]
	v_lshlrev_b64 v[154:155], 5, v[152:153]
	v_lshlrev_b64 v[158:159], 5, v[156:157]
	v_lshlrev_b64 v[160:161], 5, v[202:203]
	v_ashrrev_i32_e32 v191, 31, v190
	v_add_u32_e32 v192, 0x90, v148
	v_add_u32_e32 v194, 0xa0, v148
	v_add_u32_e32 v196, 0xb0, v148
	v_lshlrev_b64 v[182:183], 1, v[146:147]
	global_load_dwordx4 v[82:85], v[70:71], off offset:16
	global_load_dwordx4 v[86:89], v[70:71], off
	global_load_dwordx4 v[66:69], v[70:71], off offset:528
	s_nop 0
	global_load_dwordx4 v[70:73], v[70:71], off offset:512
	v_lshl_add_u64 v[154:155], s[14:15], 0, v[154:155]
	v_lshl_add_u64 v[158:159], s[14:15], 0, v[158:159]
	v_lshl_add_u64 v[160:161], s[14:15], 0, v[160:161]
	global_load_dwordx2 v[240:241], v[150:151], off
	global_load_dwordx2 v[208:209], v[154:155], off
	global_load_dwordx2 v[204:205], v[158:159], off
	global_load_dwordx2 v[200:201], v[160:161], off
	v_lshlrev_b64 v[150:151], 5, v[190:191]
	v_ashrrev_i32_e32 v193, 31, v192
	v_ashrrev_i32_e32 v195, 31, v194
	v_ashrrev_i32_e32 v197, 31, v196
	v_lshl_add_u64 v[198:199], s[38:39], 0, v[182:183]
	v_lshlrev_b64 v[242:243], 12, v[148:149]
	v_lshl_add_u64 v[150:151], s[14:15], 0, v[150:151]
	v_lshlrev_b64 v[154:155], 5, v[192:193]
	v_lshlrev_b64 v[158:159], 5, v[194:195]
	v_lshlrev_b64 v[160:161], 5, v[196:197]
	v_lshl_add_u64 v[146:147], v[198:199], 0, v[242:243]
	v_lshlrev_b64 v[244:245], 12, v[152:153]
	v_lshl_add_u64 v[154:155], s[14:15], 0, v[154:155]
	v_lshl_add_u64 v[158:159], s[14:15], 0, v[158:159]
	v_lshl_add_u64 v[160:161], s[14:15], 0, v[160:161]
	global_load_dwordx2 v[188:189], v[150:151], off
	global_load_dwordx2 v[186:187], v[154:155], off
	global_load_dwordx2 v[184:185], v[158:159], off
	global_load_dwordx2 v[180:181], v[160:161], off
	global_load_dwordx4 v[228:231], v[146:147], off
	global_load_dwordx4 v[232:235], v[146:147], off offset:256
	v_lshl_add_u64 v[146:147], v[198:199], 0, v[244:245]
	v_lshlrev_b64 v[206:207], 12, v[156:157]
	global_load_dwordx4 v[236:239], v[146:147], off
	global_load_dwordx4 v[162:165], v[146:147], off offset:256
	v_lshl_add_u64 v[146:147], v[198:199], 0, v[206:207]
	v_lshlrev_b64 v[202:203], 12, v[202:203]
	global_load_dwordx4 v[158:161], v[146:147], off
	global_load_dwordx4 v[154:157], v[146:147], off offset:256
	v_lshl_add_u64 v[146:147], v[198:199], 0, v[202:203]
	global_load_dwordx4 v[150:153], v[146:147], off
	s_nop 0
	global_load_dwordx4 v[146:149], v[146:147], off offset:256
	s_waitcnt vmcnt(0)
; __device__ __forceinline__ unsigned cvt_pk_bf16(float lo, float hi) { unsigned r; asm("v_cvt_pk_bf16_f32 %0, %1, %2" : "=v"(r) : "v"(lo), "v"(hi)); return r; }
; __device__ __forceinline__ float bf_lo(unsigned u) { return __uint_as_float(u << 16); }
; __device__ __forceinline__ float bf_hi(unsigned u) { return __uint_as_float(u & 0xffff0000u); }
;     __device__ __forceinline__ void operator()(const AccT& acc, const Unit& u, int wr, int wc, int fr, int fq) const {
;     ...
;                 const float mu = st[ai][m][0], rs = st[ai][m][1];
; #pragma unroll
;                 for (int bj = 0; bj < 2; ++bj) { const f32x4 v0 = acc[ai][bj][m][0], v1 = acc[ai][bj][m][1]; const u32x4 yw = yv[m][bj];
;                     const f32x4 y0 = (f32x4){bf_lo(yw.x), bf_hi(yw.x), bf_lo(yw.y), bf_hi(yw.y)}, y1 = (f32x4){bf_lo(yw.z), bf_hi(yw.z), bf_lo(yw.w), bf_hi(yw.w)};
;                     const f32x4 n0 = (y0 - mu) * rs * gw[bj][0], n1 = (y1 - mu) * rs * gw[bj][1];
;                     const f32x4 s0 = silu4(v0) * n0, s1 = silu4(v1) * n1;
;                     u32x4 w; w.x = cvt_pk_bf16(s0[0], s0[1]); w.y = cvt_pk_bf16(s0[2], s0[3]); w.z = cvt_pk_bf16(s1[0], s1[1]); w.w = cvt_pk_bf16(s1[2], s1[3]);
;                     *(u32x4*)(rowp + bj * 128) = w; } }
	v_lshlrev_b32_e32 v246, 16, v228
	v_and_b32_e32 v228, 0xffff0000, v228
	v_lshlrev_b32_e32 v247, 16, v229
	v_and_b32_e32 v248, 0xffff0000, v229
	v_lshlrev_b32_e32 v249, 16, v230
	v_and_b32_e32 v250, 0xffff0000, v230
	v_lshlrev_b32_e32 v251, 16, v231
	v_and_b32_e32 v252, 0xffff0000, v231
	v_sub_f32_e32 v229, v228, v240
	v_sub_f32_e32 v228, v246, v240
	v_sub_f32_e32 v231, v248, v240
	v_sub_f32_e32 v230, v247, v240
	v_sub_f32_e32 v247, v250, v240
	v_sub_f32_e32 v246, v249, v240
	v_sub_f32_e32 v249, v252, v240
	v_sub_f32_e32 v248, v251, v240
	v_mul_f32_e32 v250, 0xbfb8aa3b, v142
	v_mul_f32_e32 v251, 0xbfb8aa3b, v143
	v_mul_f32_e32 v252, 0xbfb8aa3b, v144
	v_mul_f32_e32 v253, 0xbfb8aa3b, v145
	v_exp_f32_e32 v250, v250
	v_exp_f32_e32 v251, v251
	v_exp_f32_e32 v252, v252
	v_exp_f32_e32 v253, v253
	v_add_f32_e32 v250, 1.0, v250
	v_add_f32_e32 v251, 1.0, v251
	v_add_f32_e32 v252, 1.0, v252
	v_add_f32_e32 v253, 1.0, v253
	v_rcp_f32_e32 v250, v250
	v_rcp_f32_e32 v251, v251
	v_rcp_f32_e32 v252, v252
	v_rcp_f32_e32 v253, v253
	v_pk_mul_f32 v[228:229], v[240:241], v[228:229] op_sel:[1,0]
	v_pk_mul_f32 v[142:143], v[142:143], v[250:251]
	v_mul_f32_e32 v250, 0xbfb8aa3b, v138
	v_pk_mul_f32 v[144:145], v[144:145], v[252:253]
	v_mul_f32_e32 v251, 0xbfb8aa3b, v139
	v_mul_f32_e32 v252, 0xbfb8aa3b, v140
	v_mul_f32_e32 v253, 0xbfb8aa3b, v141
	v_exp_f32_e32 v250, v250
	v_exp_f32_e32 v251, v251
	v_exp_f32_e32 v252, v252
	v_exp_f32_e32 v253, v253
	v_add_f32_e32 v250, 1.0, v250
	v_add_f32_e32 v251, 1.0, v251
	v_add_f32_e32 v252, 1.0, v252
	v_add_f32_e32 v253, 1.0, v253
	v_rcp_f32_e32 v250, v250
	v_rcp_f32_e32 v251, v251
	v_rcp_f32_e32 v252, v252
	v_rcp_f32_e32 v253, v253
	v_pk_mul_f32 v[248:249], v[240:241], v[248:249] op_sel:[1,0]
	v_pk_mul_f32 v[246:247], v[240:241], v[246:247] op_sel:[1,0]
	v_pk_mul_f32 v[230:231], v[240:241], v[230:231] op_sel:[1,0]
	v_pk_mul_f32 v[228:229], v[86:87], v[228:229]
	v_pk_mul_f32 v[246:247], v[82:83], v[246:247]
	v_pk_mul_f32 v[248:249], v[84:85], v[248:249]
	v_pk_mul_f32 v[138:139], v[138:139], v[250:251]
	v_pk_mul_f32 v[140:141], v[140:141], v[252:253]
	v_pk_mul_f32 v[230:231], v[88:89], v[230:231]
	v_pk_mul_f32 v[142:143], v[142:143], v[228:229]
	v_pk_mul_f32 v[228:229], v[140:141], v[248:249]
	v_pk_mul_f32 v[140:141], v[138:139], v[246:247]
	v_pk_mul_f32 v[144:145], v[144:145], v[230:231]
	v_cvt_pk_bf16_f32 v140, v140, v141
	v_cvt_pk_bf16_f32 v141, v228, v229
	v_mul_f32_e32 v228, 0xbfb8aa3b, v134
	v_mul_f32_e32 v229, 0xbfb8aa3b, v135
	v_mul_f32_e32 v230, 0xbfb8aa3b, v136
	v_mul_f32_e32 v231, 0xbfb8aa3b, v137
	v_exp_f32_e32 v228, v228
	v_exp_f32_e32 v229, v229
	v_exp_f32_e32 v230, v230
	v_exp_f32_e32 v231, v231
	v_add_f32_e32 v228, 1.0, v228
	v_add_f32_e32 v229, 1.0, v229
	v_add_f32_e32 v230, 1.0, v230
	v_add_f32_e32 v231, 1.0, v231
	v_rcp_f32_e32 v228, v228
	v_rcp_f32_e32 v229, v229
	v_rcp_f32_e32 v230, v230
	v_rcp_f32_e32 v231, v231
	v_lshl_add_u64 v[242:243], s[34:35], 0, v[242:243]
	v_pk_mul_f32 v[134:135], v[134:135], v[228:229]
	v_mul_f32_e32 v228, 0xbfb8aa3b, v130
	v_pk_mul_f32 v[136:137], v[136:137], v[230:231]
	v_mul_f32_e32 v229, 0xbfb8aa3b, v131
	v_mul_f32_e32 v230, 0xbfb8aa3b, v132
	v_mul_f32_e32 v231, 0xbfb8aa3b, v133
	v_exp_f32_e32 v228, v228
	v_exp_f32_e32 v229, v229
	v_exp_f32_e32 v230, v230
	v_exp_f32_e32 v231, v231
	v_add_f32_e32 v228, 1.0, v228
	v_add_f32_e32 v229, 1.0, v229
	v_add_f32_e32 v230, 1.0, v230
	v_add_f32_e32 v231, 1.0, v231
	v_lshl_add_u64 v[242:243], v[242:243], 0, v[182:183]
	v_cvt_pk_bf16_f32 v138, v142, v143
	v_cvt_pk_bf16_f32 v139, v144, v145
	v_rcp_f32_e32 v228, v228
	v_rcp_f32_e32 v229, v229
	v_rcp_f32_e32 v230, v230
	v_rcp_f32_e32 v231, v231
	global_store_dwordx4 v[242:243], v[138:141], off
	v_lshlrev_b32_e32 v142, 16, v234
	v_and_b32_e32 v143, 0xffff0000, v234
	v_lshlrev_b32_e32 v138, 16, v232
	v_and_b32_e32 v139, 0xffff0000, v232
	v_lshlrev_b32_e32 v140, 16, v233
	v_and_b32_e32 v141, 0xffff0000, v233
	v_lshlrev_b32_e32 v144, 16, v235
	v_and_b32_e32 v145, 0xffff0000, v235
	v_sub_f32_e32 v139, v139, v240
	v_sub_f32_e32 v138, v138, v240
	v_sub_f32_e32 v141, v141, v240
	v_sub_f32_e32 v140, v140, v240
	v_sub_f32_e32 v143, v143, v240
	v_sub_f32_e32 v142, v142, v240
	v_sub_f32_e32 v145, v145, v240
	v_sub_f32_e32 v144, v144, v240
	v_pk_mul_f32 v[140:141], v[240:241], v[140:141] op_sel:[1,0]
	v_pk_mul_f32 v[138:139], v[240:241], v[138:139] op_sel:[1,0]
	v_pk_mul_f32 v[144:145], v[240:241], v[144:145] op_sel:[1,0]
	v_pk_mul_f32 v[142:143], v[240:241], v[142:143] op_sel:[1,0]
	v_pk_mul_f32 v[138:139], v[70:71], v[138:139]
	v_pk_mul_f32 v[140:141], v[72:73], v[140:141]
	v_pk_mul_f32 v[142:143], v[66:67], v[142:143]
	v_pk_mul_f32 v[144:145], v[68:69], v[144:145]
	v_pk_mul_f32 v[130:131], v[130:131], v[228:229]
	v_pk_mul_f32 v[132:133], v[132:133], v[230:231]
	v_pk_mul_f32 v[136:137], v[136:137], v[140:141]
	v_pk_mul_f32 v[134:135], v[134:135], v[138:139]
	v_pk_mul_f32 v[138:139], v[132:133], v[144:145]
	v_pk_mul_f32 v[132:133], v[130:131], v[142:143]
	v_mul_f32_e32 v140, 0xbfb8aa3b, v126
	v_mul_f32_e32 v141, 0xbfb8aa3b, v127
	v_mul_f32_e32 v142, 0xbfb8aa3b, v128
	v_mul_f32_e32 v143, 0xbfb8aa3b, v129
	v_exp_f32_e32 v140, v140
	v_exp_f32_e32 v141, v141
	v_exp_f32_e32 v142, v142
	v_exp_f32_e32 v143, v143
	v_add_f32_e32 v140, 1.0, v140
	v_add_f32_e32 v141, 1.0, v141
	v_add_f32_e32 v142, 1.0, v142
	v_add_f32_e32 v143, 1.0, v143
	v_rcp_f32_e32 v140, v140
	v_rcp_f32_e32 v141, v141
	v_rcp_f32_e32 v142, v142
	v_rcp_f32_e32 v143, v143
	v_cvt_pk_bf16_f32 v132, v132, v133
	v_pk_mul_f32 v[126:127], v[126:127], v[140:141]
	v_mul_f32_e32 v140, 0xbfb8aa3b, v122
	v_pk_mul_f32 v[128:129], v[128:129], v[142:143]
; __device__ __forceinline__ unsigned cvt_pk_bf16(float lo, float hi) { unsigned r; asm("v_cvt_pk_bf16_f32 %0, %1, %2" : "=v"(r) : "v"(lo), "v"(hi)); return r; }
; __device__ __forceinline__ float bf_lo(unsigned u) { return __uint_as_float(u << 16); }
; __device__ __forceinline__ float bf_hi(unsigned u) { return __uint_as_float(u & 0xffff0000u); }
;     __device__ __forceinline__ void operator()(const AccT& acc, const Unit& u, int wr, int wc, int fr, int fq) const {
;     ...
;                 const float mu = st[ai][m][0], rs = st[ai][m][1];
; #pragma unroll
;                 for (int bj = 0; bj < 2; ++bj) { const f32x4 v0 = acc[ai][bj][m][0], v1 = acc[ai][bj][m][1]; const u32x4 yw = yv[m][bj];
;                     const f32x4 y0 = (f32x4){bf_lo(yw.x), bf_hi(yw.x), bf_lo(yw.y), bf_hi(yw.y)}, y1 = (f32x4){bf_lo(yw.z), bf_hi(yw.z), bf_lo(yw.w), bf_hi(yw.w)};
;                     const f32x4 n0 = (y0 - mu) * rs * gw[bj][0], n1 = (y1 - mu) * rs * gw[bj][1];
;                     const f32x4 s0 = silu4(v0) * n0, s1 = silu4(v1) * n1;
;                     u32x4 w; w.x = cvt_pk_bf16(s0[0], s0[1]); w.y = cvt_pk_bf16(s0[2], s0[3]); w.z = cvt_pk_bf16(s1[0], s1[1]); w.w = cvt_pk_bf16(s1[2], s1[3]);
;                     *(u32x4*)(rowp + bj * 128) = w; } }
	v_mul_f32_e32 v141, 0xbfb8aa3b, v123
	v_mul_f32_e32 v142, 0xbfb8aa3b, v124
	v_mul_f32_e32 v143, 0xbfb8aa3b, v125
	v_exp_f32_e32 v140, v140
	v_exp_f32_e32 v141, v141
	v_exp_f32_e32 v142, v142
	v_exp_f32_e32 v143, v143
	v_add_f32_e32 v140, 1.0, v140
	v_add_f32_e32 v141, 1.0, v141
	v_add_f32_e32 v142, 1.0, v142
	v_add_f32_e32 v143, 1.0, v143
	v_cvt_pk_bf16_f32 v133, v138, v139
	v_rcp_f32_e32 v140, v140
	v_rcp_f32_e32 v141, v141
	v_rcp_f32_e32 v142, v142
	v_rcp_f32_e32 v143, v143
	v_cvt_pk_bf16_f32 v130, v134, v135
	v_cvt_pk_bf16_f32 v131, v136, v137
	global_store_dwordx4 v[242:243], v[130:133], off offset:256
	v_lshlrev_b32_e32 v136, 16, v238
	v_and_b32_e32 v137, 0xffff0000, v238
	v_lshlrev_b32_e32 v132, 16, v236
	v_and_b32_e32 v133, 0xffff0000, v236
	v_lshlrev_b32_e32 v138, 16, v239
	v_and_b32_e32 v139, 0xffff0000, v239
	v_lshlrev_b32_e32 v134, 16, v237
	v_and_b32_e32 v135, 0xffff0000, v237
	v_sub_f32_e32 v133, v133, v208
	v_sub_f32_e32 v132, v132, v208
	v_sub_f32_e32 v137, v137, v208
	v_sub_f32_e32 v136, v136, v208
	v_sub_f32_e32 v139, v139, v208
	v_sub_f32_e32 v138, v138, v208
	v_sub_f32_e32 v135, v135, v208
	v_sub_f32_e32 v134, v134, v208
	v_pk_mul_f32 v[132:133], v[208:209], v[132:133] op_sel:[1,0]
	v_pk_mul_f32 v[138:139], v[208:209], v[138:139] op_sel:[1,0]
	v_pk_mul_f32 v[136:137], v[208:209], v[136:137] op_sel:[1,0]
	v_pk_mul_f32 v[134:135], v[208:209], v[134:135] op_sel:[1,0]
	v_pk_mul_f32 v[132:133], v[86:87], v[132:133]
	v_pk_mul_f32 v[136:137], v[82:83], v[136:137]
	v_pk_mul_f32 v[138:139], v[84:85], v[138:139]
	v_pk_mul_f32 v[122:123], v[122:123], v[140:141]
	v_pk_mul_f32 v[124:125], v[124:125], v[142:143]
	v_pk_mul_f32 v[134:135], v[88:89], v[134:135]
	v_pk_mul_f32 v[126:127], v[126:127], v[132:133]
	v_pk_mul_f32 v[132:133], v[124:125], v[138:139]
	v_pk_mul_f32 v[124:125], v[122:123], v[136:137]
	v_pk_mul_f32 v[128:129], v[128:129], v[134:135]
	v_cvt_pk_bf16_f32 v124, v124, v125
	v_cvt_pk_bf16_f32 v125, v132, v133
	v_mul_f32_e32 v132, 0xbfb8aa3b, v118
	v_mul_f32_e32 v133, 0xbfb8aa3b, v119
	v_mul_f32_e32 v134, 0xbfb8aa3b, v120
	v_mul_f32_e32 v135, 0xbfb8aa3b, v121
	v_exp_f32_e32 v132, v132
	v_exp_f32_e32 v133, v133
	v_exp_f32_e32 v134, v134
	v_exp_f32_e32 v135, v135
	v_add_f32_e32 v132, 1.0, v132
	v_add_f32_e32 v133, 1.0, v133
	v_add_f32_e32 v134, 1.0, v134
	v_add_f32_e32 v135, 1.0, v135
	v_rcp_f32_e32 v132, v132
	v_rcp_f32_e32 v133, v133
	v_rcp_f32_e32 v134, v134
	v_rcp_f32_e32 v135, v135
	v_lshl_add_u64 v[130:131], s[34:35], 0, v[244:245]
	v_pk_mul_f32 v[118:119], v[118:119], v[132:133]
	v_mul_f32_e32 v132, 0xbfb8aa3b, v114
	v_pk_mul_f32 v[120:121], v[120:121], v[134:135]
	v_mul_f32_e32 v133, 0xbfb8aa3b, v115
	v_mul_f32_e32 v134, 0xbfb8aa3b, v116
	v_mul_f32_e32 v135, 0xbfb8aa3b, v117
	v_exp_f32_e32 v132, v132
	v_exp_f32_e32 v133, v133
	v_exp_f32_e32 v134, v134
	v_exp_f32_e32 v135, v135
	v_add_f32_e32 v132, 1.0, v132
	v_add_f32_e32 v133, 1.0, v133
	v_add_f32_e32 v134, 1.0, v134
	v_add_f32_e32 v135, 1.0, v135
	v_lshl_add_u64 v[130:131], v[130:131], 0, v[182:183]
	v_cvt_pk_bf16_f32 v122, v126, v127
	v_cvt_pk_bf16_f32 v123, v128, v129
	v_rcp_f32_e32 v132, v132
	v_rcp_f32_e32 v133, v133
	v_rcp_f32_e32 v134, v134
	v_rcp_f32_e32 v135, v135
	global_store_dwordx4 v[130:131], v[122:125], off
	v_lshlrev_b32_e32 v126, 16, v164
	v_and_b32_e32 v127, 0xffff0000, v164
	v_lshlrev_b32_e32 v122, 16, v162
	v_and_b32_e32 v123, 0xffff0000, v162
	v_lshlrev_b32_e32 v124, 16, v163
	v_and_b32_e32 v125, 0xffff0000, v163
	v_lshlrev_b32_e32 v128, 16, v165
	v_and_b32_e32 v129, 0xffff0000, v165
	v_sub_f32_e32 v123, v123, v208
	v_sub_f32_e32 v122, v122, v208
	v_sub_f32_e32 v125, v125, v208
	v_sub_f32_e32 v124, v124, v208
	v_sub_f32_e32 v127, v127, v208
	v_sub_f32_e32 v126, v126, v208
	v_sub_f32_e32 v129, v129, v208
	v_sub_f32_e32 v128, v128, v208
	v_pk_mul_f32 v[124:125], v[208:209], v[124:125] op_sel:[1,0]
	v_pk_mul_f32 v[122:123], v[208:209], v[122:123] op_sel:[1,0]
	v_pk_mul_f32 v[128:129], v[208:209], v[128:129] op_sel:[1,0]
	v_pk_mul_f32 v[126:127], v[208:209], v[126:127] op_sel:[1,0]
	v_pk_mul_f32 v[122:123], v[70:71], v[122:123]
	v_pk_mul_f32 v[124:125], v[72:73], v[124:125]
	v_pk_mul_f32 v[126:127], v[66:67], v[126:127]
	v_pk_mul_f32 v[128:129], v[68:69], v[128:129]
	v_pk_mul_f32 v[114:115], v[114:115], v[132:133]
	v_pk_mul_f32 v[116:117], v[116:117], v[134:135]
	v_pk_mul_f32 v[120:121], v[120:121], v[124:125]
	v_pk_mul_f32 v[118:119], v[118:119], v[122:123]
	v_pk_mul_f32 v[122:123], v[116:117], v[128:129]
	v_pk_mul_f32 v[116:117], v[114:115], v[126:127]
	v_mul_f32_e32 v124, 0xbfb8aa3b, v110
	v_mul_f32_e32 v125, 0xbfb8aa3b, v111
	v_mul_f32_e32 v126, 0xbfb8aa3b, v112
	v_mul_f32_e32 v127, 0xbfb8aa3b, v113
	v_exp_f32_e32 v124, v124
	v_exp_f32_e32 v125, v125
	v_exp_f32_e32 v126, v126
	v_exp_f32_e32 v127, v127
	v_add_f32_e32 v124, 1.0, v124
	v_add_f32_e32 v125, 1.0, v125
	v_add_f32_e32 v126, 1.0, v126
	v_add_f32_e32 v127, 1.0, v127
	v_rcp_f32_e32 v124, v124
	v_rcp_f32_e32 v125, v125
	v_rcp_f32_e32 v126, v126
	v_rcp_f32_e32 v127, v127
	v_cvt_pk_bf16_f32 v116, v116, v117
	v_pk_mul_f32 v[110:111], v[110:111], v[124:125]
	v_mul_f32_e32 v124, 0xbfb8aa3b, v106
	v_pk_mul_f32 v[112:113], v[112:113], v[126:127]
	v_mul_f32_e32 v125, 0xbfb8aa3b, v107
	v_mul_f32_e32 v126, 0xbfb8aa3b, v108
	v_mul_f32_e32 v127, 0xbfb8aa3b, v109
	v_exp_f32_e32 v124, v124
	v_exp_f32_e32 v125, v125
	v_exp_f32_e32 v126, v126
	v_exp_f32_e32 v127, v127
	v_add_f32_e32 v124, 1.0, v124
	v_add_f32_e32 v125, 1.0, v125
	v_add_f32_e32 v126, 1.0, v126
	v_add_f32_e32 v127, 1.0, v127
	v_cvt_pk_bf16_f32 v117, v122, v123
	v_rcp_f32_e32 v124, v124
	v_rcp_f32_e32 v125, v125
	v_rcp_f32_e32 v126, v126
; __device__ __forceinline__ unsigned cvt_pk_bf16(float lo, float hi) { unsigned r; asm("v_cvt_pk_bf16_f32 %0, %1, %2" : "=v"(r) : "v"(lo), "v"(hi)); return r; }
; __device__ __forceinline__ float bf_lo(unsigned u) { return __uint_as_float(u << 16); }
; __device__ __forceinline__ float bf_hi(unsigned u) { return __uint_as_float(u & 0xffff0000u); }
;     __device__ __forceinline__ void operator()(const AccT& acc, const Unit& u, int wr, int wc, int fr, int fq) const {
;     ...
;                 const float mu = st[ai][m][0], rs = st[ai][m][1];
; #pragma unroll
;                 for (int bj = 0; bj < 2; ++bj) { const f32x4 v0 = acc[ai][bj][m][0], v1 = acc[ai][bj][m][1]; const u32x4 yw = yv[m][bj];
;                     const f32x4 y0 = (f32x4){bf_lo(yw.x), bf_hi(yw.x), bf_lo(yw.y), bf_hi(yw.y)}, y1 = (f32x4){bf_lo(yw.z), bf_hi(yw.z), bf_lo(yw.w), bf_hi(yw.w)};
;                     const f32x4 n0 = (y0 - mu) * rs * gw[bj][0], n1 = (y1 - mu) * rs * gw[bj][1];
;                     const f32x4 s0 = silu4(v0) * n0, s1 = silu4(v1) * n1;
;                     u32x4 w; w.x = cvt_pk_bf16(s0[0], s0[1]); w.y = cvt_pk_bf16(s0[2], s0[3]); w.z = cvt_pk_bf16(s1[0], s1[1]); w.w = cvt_pk_bf16(s1[2], s1[3]);
;                     *(u32x4*)(rowp + bj * 128) = w; } }
	v_rcp_f32_e32 v127, v127
	v_cvt_pk_bf16_f32 v114, v118, v119
	v_cvt_pk_bf16_f32 v115, v120, v121
	global_store_dwordx4 v[130:131], v[114:117], off offset:256
	v_lshlrev_b32_e32 v120, 16, v160
	v_and_b32_e32 v121, 0xffff0000, v160
	v_lshlrev_b32_e32 v116, 16, v158
	v_and_b32_e32 v117, 0xffff0000, v158
	v_lshlrev_b32_e32 v122, 16, v161
	v_and_b32_e32 v123, 0xffff0000, v161
	v_lshlrev_b32_e32 v118, 16, v159
	v_and_b32_e32 v119, 0xffff0000, v159
	v_sub_f32_e32 v117, v117, v204
	v_sub_f32_e32 v116, v116, v204
	v_sub_f32_e32 v121, v121, v204
	v_sub_f32_e32 v120, v120, v204
	v_sub_f32_e32 v123, v123, v204
	v_sub_f32_e32 v122, v122, v204
	v_sub_f32_e32 v119, v119, v204
	v_sub_f32_e32 v118, v118, v204
	v_pk_mul_f32 v[116:117], v[204:205], v[116:117] op_sel:[1,0]
	v_pk_mul_f32 v[122:123], v[204:205], v[122:123] op_sel:[1,0]
	v_pk_mul_f32 v[120:121], v[204:205], v[120:121] op_sel:[1,0]
	v_pk_mul_f32 v[118:119], v[204:205], v[118:119] op_sel:[1,0]
	v_pk_mul_f32 v[116:117], v[86:87], v[116:117]
	v_pk_mul_f32 v[120:121], v[82:83], v[120:121]
	v_pk_mul_f32 v[122:123], v[84:85], v[122:123]
	v_pk_mul_f32 v[106:107], v[106:107], v[124:125]
	v_pk_mul_f32 v[108:109], v[108:109], v[126:127]
	v_pk_mul_f32 v[118:119], v[88:89], v[118:119]
	v_pk_mul_f32 v[110:111], v[110:111], v[116:117]
	v_pk_mul_f32 v[116:117], v[108:109], v[122:123]
	v_pk_mul_f32 v[108:109], v[106:107], v[120:121]
	v_pk_mul_f32 v[112:113], v[112:113], v[118:119]
	v_cvt_pk_bf16_f32 v108, v108, v109
	v_cvt_pk_bf16_f32 v109, v116, v117
	v_mul_f32_e32 v116, 0xbfb8aa3b, v102
	v_mul_f32_e32 v117, 0xbfb8aa3b, v103
	v_mul_f32_e32 v118, 0xbfb8aa3b, v104
	v_mul_f32_e32 v119, 0xbfb8aa3b, v105
	v_exp_f32_e32 v116, v116
	v_exp_f32_e32 v117, v117
	v_exp_f32_e32 v118, v118
	v_exp_f32_e32 v119, v119
	v_add_f32_e32 v116, 1.0, v116
	v_add_f32_e32 v117, 1.0, v117
	v_add_f32_e32 v118, 1.0, v118
	v_add_f32_e32 v119, 1.0, v119
	v_rcp_f32_e32 v116, v116
	v_rcp_f32_e32 v117, v117
	v_rcp_f32_e32 v118, v118
	v_rcp_f32_e32 v119, v119
	v_lshl_add_u64 v[114:115], s[34:35], 0, v[206:207]
	v_pk_mul_f32 v[102:103], v[102:103], v[116:117]
	v_mul_f32_e32 v116, 0xbfb8aa3b, v98
	v_pk_mul_f32 v[104:105], v[104:105], v[118:119]
	v_mul_f32_e32 v117, 0xbfb8aa3b, v99
	v_mul_f32_e32 v118, 0xbfb8aa3b, v100
	v_mul_f32_e32 v119, 0xbfb8aa3b, v101
	v_exp_f32_e32 v116, v116
	v_exp_f32_e32 v117, v117
	v_exp_f32_e32 v118, v118
	v_exp_f32_e32 v119, v119
	v_add_f32_e32 v116, 1.0, v116
	v_add_f32_e32 v117, 1.0, v117
	v_add_f32_e32 v118, 1.0, v118
	v_add_f32_e32 v119, 1.0, v119
	v_lshl_add_u64 v[114:115], v[114:115], 0, v[182:183]
	v_cvt_pk_bf16_f32 v106, v110, v111
	v_cvt_pk_bf16_f32 v107, v112, v113
	v_rcp_f32_e32 v116, v116
	v_rcp_f32_e32 v117, v117
	v_rcp_f32_e32 v118, v118
	v_rcp_f32_e32 v119, v119
	global_store_dwordx4 v[114:115], v[106:109], off
	v_lshlrev_b32_e32 v110, 16, v156
	v_and_b32_e32 v111, 0xffff0000, v156
	v_lshlrev_b32_e32 v106, 16, v154
	v_and_b32_e32 v107, 0xffff0000, v154
	v_lshlrev_b32_e32 v108, 16, v155
	v_and_b32_e32 v109, 0xffff0000, v155
	v_lshlrev_b32_e32 v112, 16, v157
	v_and_b32_e32 v113, 0xffff0000, v157
	v_sub_f32_e32 v107, v107, v204
	v_sub_f32_e32 v106, v106, v204
	v_sub_f32_e32 v109, v109, v204
	v_sub_f32_e32 v108, v108, v204
	v_sub_f32_e32 v111, v111, v204
	v_sub_f32_e32 v110, v110, v204
	v_sub_f32_e32 v113, v113, v204
	v_sub_f32_e32 v112, v112, v204
	v_pk_mul_f32 v[108:109], v[204:205], v[108:109] op_sel:[1,0]
	v_pk_mul_f32 v[106:107], v[204:205], v[106:107] op_sel:[1,0]
	v_pk_mul_f32 v[112:113], v[204:205], v[112:113] op_sel:[1,0]
	v_pk_mul_f32 v[110:111], v[204:205], v[110:111] op_sel:[1,0]
	v_pk_mul_f32 v[106:107], v[70:71], v[106:107]
	v_pk_mul_f32 v[108:109], v[72:73], v[108:109]
	v_pk_mul_f32 v[110:111], v[66:67], v[110:111]
	v_pk_mul_f32 v[112:113], v[68:69], v[112:113]
	v_pk_mul_f32 v[98:99], v[98:99], v[116:117]
	v_pk_mul_f32 v[100:101], v[100:101], v[118:119]
	v_pk_mul_f32 v[104:105], v[104:105], v[108:109]
	v_pk_mul_f32 v[102:103], v[102:103], v[106:107]
	v_pk_mul_f32 v[106:107], v[100:101], v[112:113]
	v_pk_mul_f32 v[100:101], v[98:99], v[110:111]
	v_mul_f32_e32 v108, 0xbfb8aa3b, v94
	v_mul_f32_e32 v109, 0xbfb8aa3b, v95
	v_mul_f32_e32 v110, 0xbfb8aa3b, v96
	v_mul_f32_e32 v111, 0xbfb8aa3b, v97
	v_exp_f32_e32 v108, v108
	v_exp_f32_e32 v109, v109
	v_exp_f32_e32 v110, v110
	v_exp_f32_e32 v111, v111
	v_add_f32_e32 v108, 1.0, v108
	v_add_f32_e32 v109, 1.0, v109
	v_add_f32_e32 v110, 1.0, v110
	v_add_f32_e32 v111, 1.0, v111
	v_rcp_f32_e32 v108, v108
	v_rcp_f32_e32 v109, v109
	v_rcp_f32_e32 v110, v110
	v_rcp_f32_e32 v111, v111
	v_cvt_pk_bf16_f32 v100, v100, v101
	v_pk_mul_f32 v[94:95], v[94:95], v[108:109]
	v_mul_f32_e32 v108, 0xbfb8aa3b, v90
	v_pk_mul_f32 v[96:97], v[96:97], v[110:111]
	v_mul_f32_e32 v109, 0xbfb8aa3b, v91
	v_mul_f32_e32 v110, 0xbfb8aa3b, v92
	v_mul_f32_e32 v111, 0xbfb8aa3b, v93
	v_exp_f32_e32 v108, v108
	v_exp_f32_e32 v109, v109
	v_exp_f32_e32 v110, v110
	v_exp_f32_e32 v111, v111
	v_add_f32_e32 v108, 1.0, v108
	v_add_f32_e32 v109, 1.0, v109
	v_add_f32_e32 v110, 1.0, v110
	v_add_f32_e32 v111, 1.0, v111
	v_cvt_pk_bf16_f32 v101, v106, v107
	v_rcp_f32_e32 v108, v108
	v_rcp_f32_e32 v109, v109
	v_rcp_f32_e32 v110, v110
	v_rcp_f32_e32 v111, v111
	v_cvt_pk_bf16_f32 v98, v102, v103
	v_cvt_pk_bf16_f32 v99, v104, v105
	global_store_dwordx4 v[114:115], v[98:101], off offset:256
	v_lshlrev_b32_e32 v104, 16, v152
	v_and_b32_e32 v105, 0xffff0000, v152
	v_lshlrev_b32_e32 v100, 16, v150
	v_and_b32_e32 v101, 0xffff0000, v150
	v_lshlrev_b32_e32 v106, 16, v153
	v_and_b32_e32 v107, 0xffff0000, v153
	v_lshlrev_b32_e32 v102, 16, v151
	v_and_b32_e32 v103, 0xffff0000, v151
	v_sub_f32_e32 v101, v101, v200
; __device__ __forceinline__ unsigned cvt_pk_bf16(float lo, float hi) { unsigned r; asm("v_cvt_pk_bf16_f32 %0, %1, %2" : "=v"(r) : "v"(lo), "v"(hi)); return r; }
; __device__ __forceinline__ float bf_lo(unsigned u) { return __uint_as_float(u << 16); }
; __device__ __forceinline__ float bf_hi(unsigned u) { return __uint_as_float(u & 0xffff0000u); }
;     __device__ __forceinline__ void operator()(const AccT& acc, const Unit& u, int wr, int wc, int fr, int fq) const {
;     ...
;             for (int m = 0; m < 4; ++m)
; #pragma unroll
;                 for (int bj = 0; bj < 2; ++bj) yv[m][bj] = *(const u32x4*)(Y + (size_t)(row0 + ai * 128 + m * 16) * 2048 + col0 + bj * 128);
;     ...
;             for (int m = 0; m < 4; ++m) { bf16_t* rowp = A2 + (size_t)(row0 + ai * 128 + m * 16) * 2048 + col0;
;                 const float mu = st[ai][m][0], rs = st[ai][m][1];
; #pragma unroll
;                 for (int bj = 0; bj < 2; ++bj) { const f32x4 v0 = acc[ai][bj][m][0], v1 = acc[ai][bj][m][1]; const u32x4 yw = yv[m][bj];
;                     const f32x4 y0 = (f32x4){bf_lo(yw.x), bf_hi(yw.x), bf_lo(yw.y), bf_hi(yw.y)}, y1 = (f32x4){bf_lo(yw.z), bf_hi(yw.z), bf_lo(yw.w), bf_hi(yw.w)};
;                     const f32x4 n0 = (y0 - mu) * rs * gw[bj][0], n1 = (y1 - mu) * rs * gw[bj][1];
;                     const f32x4 s0 = silu4(v0) * n0, s1 = silu4(v1) * n1;
;                     u32x4 w; w.x = cvt_pk_bf16(s0[0], s0[1]); w.y = cvt_pk_bf16(s0[2], s0[3]); w.z = cvt_pk_bf16(s1[0], s1[1]); w.w = cvt_pk_bf16(s1[2], s1[3]);
;                     *(u32x4*)(rowp + bj * 128) = w; } }
	v_sub_f32_e32 v100, v100, v200
	v_sub_f32_e32 v105, v105, v200
	v_sub_f32_e32 v104, v104, v200
	v_sub_f32_e32 v107, v107, v200
	v_sub_f32_e32 v106, v106, v200
	v_sub_f32_e32 v103, v103, v200
	v_sub_f32_e32 v102, v102, v200
	v_pk_mul_f32 v[100:101], v[200:201], v[100:101] op_sel:[1,0]
	v_pk_mul_f32 v[106:107], v[200:201], v[106:107] op_sel:[1,0]
	v_pk_mul_f32 v[104:105], v[200:201], v[104:105] op_sel:[1,0]
	v_pk_mul_f32 v[102:103], v[200:201], v[102:103] op_sel:[1,0]
	v_pk_mul_f32 v[100:101], v[86:87], v[100:101]
	v_pk_mul_f32 v[104:105], v[82:83], v[104:105]
	v_pk_mul_f32 v[106:107], v[84:85], v[106:107]
	v_pk_mul_f32 v[90:91], v[90:91], v[108:109]
	v_pk_mul_f32 v[92:93], v[92:93], v[110:111]
	v_pk_mul_f32 v[102:103], v[88:89], v[102:103]
	v_pk_mul_f32 v[94:95], v[94:95], v[100:101]
	v_pk_mul_f32 v[100:101], v[92:93], v[106:107]
	v_pk_mul_f32 v[92:93], v[90:91], v[104:105]
	v_pk_mul_f32 v[96:97], v[96:97], v[102:103]
	v_cvt_pk_bf16_f32 v92, v92, v93
	v_cvt_pk_bf16_f32 v93, v100, v101
	v_mul_f32_e32 v100, 0xbfb8aa3b, v78
	v_mul_f32_e32 v101, 0xbfb8aa3b, v79
	v_mul_f32_e32 v102, 0xbfb8aa3b, v80
	v_mul_f32_e32 v103, 0xbfb8aa3b, v81
	v_exp_f32_e32 v100, v100
	v_exp_f32_e32 v101, v101
	v_exp_f32_e32 v102, v102
	v_exp_f32_e32 v103, v103
	v_add_f32_e32 v100, 1.0, v100
	v_add_f32_e32 v101, 1.0, v101
	v_add_f32_e32 v102, 1.0, v102
	v_add_f32_e32 v103, 1.0, v103
	v_rcp_f32_e32 v100, v100
	v_rcp_f32_e32 v101, v101
	v_rcp_f32_e32 v102, v102
	v_rcp_f32_e32 v103, v103
	v_lshl_add_u64 v[98:99], s[34:35], 0, v[202:203]
	v_pk_mul_f32 v[78:79], v[78:79], v[100:101]
	v_mul_f32_e32 v100, 0xbfb8aa3b, v74
	v_pk_mul_f32 v[80:81], v[80:81], v[102:103]
	v_mul_f32_e32 v101, 0xbfb8aa3b, v75
	v_mul_f32_e32 v102, 0xbfb8aa3b, v76
	v_mul_f32_e32 v103, 0xbfb8aa3b, v77
	v_exp_f32_e32 v100, v100
	v_exp_f32_e32 v101, v101
	v_exp_f32_e32 v102, v102
	v_exp_f32_e32 v103, v103
	v_add_f32_e32 v100, 1.0, v100
	v_add_f32_e32 v101, 1.0, v101
	v_add_f32_e32 v102, 1.0, v102
	v_add_f32_e32 v103, 1.0, v103
	v_lshl_add_u64 v[98:99], v[98:99], 0, v[182:183]
	v_cvt_pk_bf16_f32 v90, v94, v95
	v_cvt_pk_bf16_f32 v91, v96, v97
	v_rcp_f32_e32 v100, v100
	v_rcp_f32_e32 v101, v101
	v_rcp_f32_e32 v102, v102
	v_rcp_f32_e32 v103, v103
	global_store_dwordx4 v[98:99], v[90:93], off
	v_lshlrev_b32_e32 v94, 16, v148
	v_and_b32_e32 v95, 0xffff0000, v148
	v_lshlrev_b32_e32 v90, 16, v146
	v_and_b32_e32 v91, 0xffff0000, v146
	v_lshlrev_b32_e32 v96, 16, v149
	v_and_b32_e32 v97, 0xffff0000, v149
	v_lshlrev_b32_e32 v92, 16, v147
	v_and_b32_e32 v93, 0xffff0000, v147
	v_sub_f32_e32 v91, v91, v200
	v_sub_f32_e32 v90, v90, v200
	v_sub_f32_e32 v95, v95, v200
	v_sub_f32_e32 v94, v94, v200
	v_sub_f32_e32 v97, v97, v200
	v_sub_f32_e32 v96, v96, v200
	v_sub_f32_e32 v93, v93, v200
	v_sub_f32_e32 v92, v92, v200
	v_pk_mul_f32 v[90:91], v[200:201], v[90:91] op_sel:[1,0]
	v_pk_mul_f32 v[96:97], v[200:201], v[96:97] op_sel:[1,0]
	v_pk_mul_f32 v[94:95], v[200:201], v[94:95] op_sel:[1,0]
	v_pk_mul_f32 v[92:93], v[200:201], v[92:93] op_sel:[1,0]
	v_pk_mul_f32 v[90:91], v[70:71], v[90:91]
	v_pk_mul_f32 v[94:95], v[66:67], v[94:95]
	v_pk_mul_f32 v[96:97], v[68:69], v[96:97]
	v_pk_mul_f32 v[74:75], v[74:75], v[100:101]
	v_pk_mul_f32 v[76:77], v[76:77], v[102:103]
	v_pk_mul_f32 v[92:93], v[72:73], v[92:93]
	v_pk_mul_f32 v[78:79], v[78:79], v[90:91]
	v_pk_mul_f32 v[90:91], v[76:77], v[96:97]
	v_pk_mul_f32 v[76:77], v[74:75], v[94:95]
	v_pk_mul_f32 v[80:81], v[80:81], v[92:93]
	v_cvt_pk_bf16_f32 v74, v78, v79
	v_cvt_pk_bf16_f32 v76, v76, v77
	v_cvt_pk_bf16_f32 v77, v90, v91
	s_nop 0
	v_cvt_pk_bf16_f32 v75, v80, v81
	global_store_dwordx4 v[98:99], v[74:77], off offset:256
	v_lshlrev_b64 v[118:119], 12, v[190:191]
	s_nop 0
	v_lshl_add_u64 v[74:75], v[198:199], 0, v[118:119]
	v_lshlrev_b64 v[120:121], 12, v[192:193]
	global_load_dwordx4 v[106:109], v[74:75], off
	global_load_dwordx4 v[110:113], v[74:75], off offset:256
	v_lshl_add_u64 v[74:75], v[198:199], 0, v[120:121]
	v_lshlrev_b64 v[104:105], 12, v[194:195]
	global_load_dwordx4 v[114:117], v[74:75], off
	global_load_dwordx4 v[98:101], v[74:75], off offset:256
	v_lshl_add_u64 v[74:75], v[198:199], 0, v[104:105]
	v_lshlrev_b64 v[102:103], 12, v[196:197]
	global_load_dwordx4 v[94:97], v[74:75], off
	global_load_dwordx4 v[90:93], v[74:75], off offset:256
	v_lshl_add_u64 v[74:75], v[198:199], 0, v[102:103]
	global_load_dwordx4 v[78:81], v[74:75], off
	s_nop 0
	global_load_dwordx4 v[74:77], v[74:75], off offset:256
	s_waitcnt vmcnt(0)
; __device__ __forceinline__ unsigned cvt_pk_bf16(float lo, float hi) { unsigned r; asm("v_cvt_pk_bf16_f32 %0, %1, %2" : "=v"(r) : "v"(lo), "v"(hi)); return r; }
; __device__ __forceinline__ float bf_lo(unsigned u) { return __uint_as_float(u << 16); }
; __device__ __forceinline__ float bf_hi(unsigned u) { return __uint_as_float(u & 0xffff0000u); }
;     __device__ __forceinline__ void operator()(const AccT& acc, const Unit& u, int wr, int wc, int fr, int fq) const {
;     ...
;                 const float mu = st[ai][m][0], rs = st[ai][m][1];
; #pragma unroll
;                 for (int bj = 0; bj < 2; ++bj) { const f32x4 v0 = acc[ai][bj][m][0], v1 = acc[ai][bj][m][1]; const u32x4 yw = yv[m][bj];
;                     const f32x4 y0 = (f32x4){bf_lo(yw.x), bf_hi(yw.x), bf_lo(yw.y), bf_hi(yw.y)}, y1 = (f32x4){bf_lo(yw.z), bf_hi(yw.z), bf_lo(yw.w), bf_hi(yw.w)};
;                     const f32x4 n0 = (y0 - mu) * rs * gw[bj][0], n1 = (y1 - mu) * rs * gw[bj][1];
;                     const f32x4 s0 = silu4(v0) * n0, s1 = silu4(v1) * n1;
;                     u32x4 w; w.x = cvt_pk_bf16(s0[0], s0[1]); w.y = cvt_pk_bf16(s0[2], s0[3]); w.z = cvt_pk_bf16(s1[0], s1[1]); w.w = cvt_pk_bf16(s1[2], s1[3]);
;                     *(u32x4*)(rowp + bj * 128) = w; } }
	v_lshlrev_b32_e32 v122, 16, v106
	v_and_b32_e32 v106, 0xffff0000, v106
	v_lshlrev_b32_e32 v123, 16, v107
	v_and_b32_e32 v124, 0xffff0000, v107
	v_lshlrev_b32_e32 v125, 16, v108
	v_and_b32_e32 v126, 0xffff0000, v108
	v_lshlrev_b32_e32 v127, 16, v109
	v_and_b32_e32 v128, 0xffff0000, v109
	v_sub_f32_e32 v107, v106, v188
	v_sub_f32_e32 v106, v122, v188
	v_sub_f32_e32 v109, v124, v188
	v_sub_f32_e32 v108, v123, v188
	v_sub_f32_e32 v123, v126, v188
	v_sub_f32_e32 v122, v125, v188
	v_sub_f32_e32 v125, v128, v188
	v_sub_f32_e32 v124, v127, v188
	v_mul_f32_e32 v126, 0xbfb8aa3b, v62
	v_mul_f32_e32 v127, 0xbfb8aa3b, v63
	v_mul_f32_e32 v128, 0xbfb8aa3b, v64
	v_mul_f32_e32 v129, 0xbfb8aa3b, v65
	v_exp_f32_e32 v126, v126
	v_exp_f32_e32 v127, v127
	v_exp_f32_e32 v128, v128
	v_exp_f32_e32 v129, v129
	v_add_f32_e32 v126, 1.0, v126
	v_add_f32_e32 v127, 1.0, v127
	v_add_f32_e32 v128, 1.0, v128
	v_add_f32_e32 v129, 1.0, v129
	v_rcp_f32_e32 v126, v126
	v_rcp_f32_e32 v127, v127
	v_rcp_f32_e32 v128, v128
	v_rcp_f32_e32 v129, v129
	v_pk_mul_f32 v[106:107], v[188:189], v[106:107] op_sel:[1,0]
	v_pk_mul_f32 v[62:63], v[62:63], v[126:127]
	v_mul_f32_e32 v126, 0xbfb8aa3b, v58
	v_pk_mul_f32 v[64:65], v[64:65], v[128:129]
	v_mul_f32_e32 v127, 0xbfb8aa3b, v59
	v_mul_f32_e32 v128, 0xbfb8aa3b, v60
	v_mul_f32_e32 v129, 0xbfb8aa3b, v61
	v_exp_f32_e32 v126, v126
	v_exp_f32_e32 v127, v127
	v_exp_f32_e32 v128, v128
	v_exp_f32_e32 v129, v129
	v_add_f32_e32 v126, 1.0, v126
	v_add_f32_e32 v127, 1.0, v127
	v_add_f32_e32 v128, 1.0, v128
	v_add_f32_e32 v129, 1.0, v129
	v_rcp_f32_e32 v126, v126
	v_rcp_f32_e32 v127, v127
	v_rcp_f32_e32 v128, v128
	v_rcp_f32_e32 v129, v129
	v_pk_mul_f32 v[124:125], v[188:189], v[124:125] op_sel:[1,0]
	v_pk_mul_f32 v[122:123], v[188:189], v[122:123] op_sel:[1,0]
	v_pk_mul_f32 v[108:109], v[188:189], v[108:109] op_sel:[1,0]
	v_pk_mul_f32 v[106:107], v[86:87], v[106:107]
	v_pk_mul_f32 v[122:123], v[82:83], v[122:123]
	v_pk_mul_f32 v[124:125], v[84:85], v[124:125]
	v_pk_mul_f32 v[58:59], v[58:59], v[126:127]
	v_pk_mul_f32 v[60:61], v[60:61], v[128:129]
	v_pk_mul_f32 v[108:109], v[88:89], v[108:109]
	v_pk_mul_f32 v[62:63], v[62:63], v[106:107]
	v_pk_mul_f32 v[106:107], v[60:61], v[124:125]
	v_pk_mul_f32 v[60:61], v[58:59], v[122:123]
	v_pk_mul_f32 v[64:65], v[64:65], v[108:109]
	v_cvt_pk_bf16_f32 v60, v60, v61
	v_cvt_pk_bf16_f32 v61, v106, v107
	v_mul_f32_e32 v106, 0xbfb8aa3b, v54
	v_mul_f32_e32 v107, 0xbfb8aa3b, v55
	v_mul_f32_e32 v108, 0xbfb8aa3b, v56
	v_mul_f32_e32 v109, 0xbfb8aa3b, v57
	v_exp_f32_e32 v106, v106
	v_exp_f32_e32 v107, v107
	v_exp_f32_e32 v108, v108
	v_exp_f32_e32 v109, v109
	v_add_f32_e32 v106, 1.0, v106
	v_add_f32_e32 v107, 1.0, v107
	v_add_f32_e32 v108, 1.0, v108
	v_add_f32_e32 v109, 1.0, v109
	v_rcp_f32_e32 v106, v106
	v_rcp_f32_e32 v107, v107
	v_rcp_f32_e32 v108, v108
	v_rcp_f32_e32 v109, v109
	v_lshl_add_u64 v[118:119], s[34:35], 0, v[118:119]
	v_pk_mul_f32 v[54:55], v[54:55], v[106:107]
	v_mul_f32_e32 v106, 0xbfb8aa3b, v50
	v_pk_mul_f32 v[56:57], v[56:57], v[108:109]
	v_mul_f32_e32 v107, 0xbfb8aa3b, v51
	v_mul_f32_e32 v108, 0xbfb8aa3b, v52
	v_mul_f32_e32 v109, 0xbfb8aa3b, v53
	v_exp_f32_e32 v106, v106
	v_exp_f32_e32 v107, v107
	v_exp_f32_e32 v108, v108
	v_exp_f32_e32 v109, v109
	v_add_f32_e32 v106, 1.0, v106
	v_add_f32_e32 v107, 1.0, v107
	v_add_f32_e32 v108, 1.0, v108
	v_add_f32_e32 v109, 1.0, v109
	v_lshl_add_u64 v[118:119], v[118:119], 0, v[182:183]
	v_cvt_pk_bf16_f32 v58, v62, v63
	v_cvt_pk_bf16_f32 v59, v64, v65
	v_rcp_f32_e32 v106, v106
	v_rcp_f32_e32 v107, v107
	v_rcp_f32_e32 v108, v108
	v_rcp_f32_e32 v109, v109
	global_store_dwordx4 v[118:119], v[58:61], off
	v_lshlrev_b32_e32 v62, 16, v112
	v_and_b32_e32 v63, 0xffff0000, v112
	v_lshlrev_b32_e32 v58, 16, v110
	v_and_b32_e32 v59, 0xffff0000, v110
	v_lshlrev_b32_e32 v60, 16, v111
	v_and_b32_e32 v61, 0xffff0000, v111
	v_lshlrev_b32_e32 v64, 16, v113
	v_and_b32_e32 v65, 0xffff0000, v113
	v_sub_f32_e32 v59, v59, v188
	v_sub_f32_e32 v58, v58, v188
	v_sub_f32_e32 v61, v61, v188
	v_sub_f32_e32 v60, v60, v188
	v_sub_f32_e32 v63, v63, v188
	v_sub_f32_e32 v62, v62, v188
	v_sub_f32_e32 v65, v65, v188
	v_sub_f32_e32 v64, v64, v188
	v_pk_mul_f32 v[60:61], v[188:189], v[60:61] op_sel:[1,0]
	v_pk_mul_f32 v[58:59], v[188:189], v[58:59] op_sel:[1,0]
	v_pk_mul_f32 v[64:65], v[188:189], v[64:65] op_sel:[1,0]
	v_pk_mul_f32 v[62:63], v[188:189], v[62:63] op_sel:[1,0]
	v_pk_mul_f32 v[58:59], v[70:71], v[58:59]
	v_pk_mul_f32 v[60:61], v[72:73], v[60:61]
	v_pk_mul_f32 v[62:63], v[66:67], v[62:63]
	v_pk_mul_f32 v[64:65], v[68:69], v[64:65]
	v_pk_mul_f32 v[50:51], v[50:51], v[106:107]
	v_pk_mul_f32 v[52:53], v[52:53], v[108:109]
	v_pk_mul_f32 v[56:57], v[56:57], v[60:61]
	v_pk_mul_f32 v[54:55], v[54:55], v[58:59]
	v_pk_mul_f32 v[58:59], v[52:53], v[64:65]
	v_pk_mul_f32 v[52:53], v[50:51], v[62:63]
	v_mul_f32_e32 v60, 0xbfb8aa3b, v46
	v_mul_f32_e32 v61, 0xbfb8aa3b, v47
	v_mul_f32_e32 v62, 0xbfb8aa3b, v48
	v_mul_f32_e32 v63, 0xbfb8aa3b, v49
	v_exp_f32_e32 v60, v60
	v_exp_f32_e32 v61, v61
	v_exp_f32_e32 v62, v62
	v_exp_f32_e32 v63, v63
	v_add_f32_e32 v60, 1.0, v60
	v_add_f32_e32 v61, 1.0, v61
	v_add_f32_e32 v62, 1.0, v62
	v_add_f32_e32 v63, 1.0, v63
	v_rcp_f32_e32 v60, v60
	v_rcp_f32_e32 v61, v61
	v_rcp_f32_e32 v62, v62
	v_rcp_f32_e32 v63, v63
	v_cvt_pk_bf16_f32 v52, v52, v53
	v_pk_mul_f32 v[46:47], v[46:47], v[60:61]
	v_mul_f32_e32 v60, 0xbfb8aa3b, v42
	v_pk_mul_f32 v[48:49], v[48:49], v[62:63]
	v_mul_f32_e32 v61, 0xbfb8aa3b, v43
	v_mul_f32_e32 v62, 0xbfb8aa3b, v44
	v_mul_f32_e32 v63, 0xbfb8aa3b, v45
	v_exp_f32_e32 v60, v60
	v_exp_f32_e32 v61, v61
	v_exp_f32_e32 v62, v62
	v_exp_f32_e32 v63, v63
; __device__ __forceinline__ unsigned cvt_pk_bf16(float lo, float hi) { unsigned r; asm("v_cvt_pk_bf16_f32 %0, %1, %2" : "=v"(r) : "v"(lo), "v"(hi)); return r; }
; __device__ __forceinline__ float bf_lo(unsigned u) { return __uint_as_float(u << 16); }
; __device__ __forceinline__ float bf_hi(unsigned u) { return __uint_as_float(u & 0xffff0000u); }
;     __device__ __forceinline__ void operator()(const AccT& acc, const Unit& u, int wr, int wc, int fr, int fq) const {
;     ...
;                 const float mu = st[ai][m][0], rs = st[ai][m][1];
; #pragma unroll
;                 for (int bj = 0; bj < 2; ++bj) { const f32x4 v0 = acc[ai][bj][m][0], v1 = acc[ai][bj][m][1]; const u32x4 yw = yv[m][bj];
;                     const f32x4 y0 = (f32x4){bf_lo(yw.x), bf_hi(yw.x), bf_lo(yw.y), bf_hi(yw.y)}, y1 = (f32x4){bf_lo(yw.z), bf_hi(yw.z), bf_lo(yw.w), bf_hi(yw.w)};
;                     const f32x4 n0 = (y0 - mu) * rs * gw[bj][0], n1 = (y1 - mu) * rs * gw[bj][1];
;                     const f32x4 s0 = silu4(v0) * n0, s1 = silu4(v1) * n1;
;                     u32x4 w; w.x = cvt_pk_bf16(s0[0], s0[1]); w.y = cvt_pk_bf16(s0[2], s0[3]); w.z = cvt_pk_bf16(s1[0], s1[1]); w.w = cvt_pk_bf16(s1[2], s1[3]);
;                     *(u32x4*)(rowp + bj * 128) = w; } }
	v_add_f32_e32 v60, 1.0, v60
	v_add_f32_e32 v61, 1.0, v61
	v_add_f32_e32 v62, 1.0, v62
	v_add_f32_e32 v63, 1.0, v63
	v_cvt_pk_bf16_f32 v53, v58, v59
	v_rcp_f32_e32 v60, v60
	v_rcp_f32_e32 v61, v61
	v_rcp_f32_e32 v62, v62
	v_rcp_f32_e32 v63, v63
	v_cvt_pk_bf16_f32 v50, v54, v55
	v_cvt_pk_bf16_f32 v51, v56, v57
	global_store_dwordx4 v[118:119], v[50:53], off offset:256
	v_lshlrev_b32_e32 v56, 16, v116
	v_and_b32_e32 v57, 0xffff0000, v116
	v_lshlrev_b32_e32 v52, 16, v114
	v_and_b32_e32 v53, 0xffff0000, v114
	v_lshlrev_b32_e32 v58, 16, v117
	v_and_b32_e32 v59, 0xffff0000, v117
	v_lshlrev_b32_e32 v54, 16, v115
	v_and_b32_e32 v55, 0xffff0000, v115
	v_sub_f32_e32 v53, v53, v186
	v_sub_f32_e32 v52, v52, v186
	v_sub_f32_e32 v57, v57, v186
	v_sub_f32_e32 v56, v56, v186
	v_sub_f32_e32 v59, v59, v186
	v_sub_f32_e32 v58, v58, v186
	v_sub_f32_e32 v55, v55, v186
	v_sub_f32_e32 v54, v54, v186
	v_pk_mul_f32 v[52:53], v[186:187], v[52:53] op_sel:[1,0]
	v_pk_mul_f32 v[58:59], v[186:187], v[58:59] op_sel:[1,0]
	v_pk_mul_f32 v[56:57], v[186:187], v[56:57] op_sel:[1,0]
	v_pk_mul_f32 v[54:55], v[186:187], v[54:55] op_sel:[1,0]
	v_pk_mul_f32 v[52:53], v[86:87], v[52:53]
	v_pk_mul_f32 v[56:57], v[82:83], v[56:57]
	v_pk_mul_f32 v[58:59], v[84:85], v[58:59]
	v_pk_mul_f32 v[42:43], v[42:43], v[60:61]
	v_pk_mul_f32 v[44:45], v[44:45], v[62:63]
	v_pk_mul_f32 v[54:55], v[88:89], v[54:55]
	v_pk_mul_f32 v[46:47], v[46:47], v[52:53]
	v_pk_mul_f32 v[52:53], v[44:45], v[58:59]
	v_pk_mul_f32 v[44:45], v[42:43], v[56:57]
	v_pk_mul_f32 v[48:49], v[48:49], v[54:55]
	v_cvt_pk_bf16_f32 v44, v44, v45
	v_cvt_pk_bf16_f32 v45, v52, v53
	v_mul_f32_e32 v52, 0xbfb8aa3b, v38
	v_mul_f32_e32 v53, 0xbfb8aa3b, v39
	v_mul_f32_e32 v54, 0xbfb8aa3b, v40
	v_mul_f32_e32 v55, 0xbfb8aa3b, v41
	v_exp_f32_e32 v52, v52
	v_exp_f32_e32 v53, v53
	v_exp_f32_e32 v54, v54
	v_exp_f32_e32 v55, v55
	v_add_f32_e32 v52, 1.0, v52
	v_add_f32_e32 v53, 1.0, v53
	v_add_f32_e32 v54, 1.0, v54
	v_add_f32_e32 v55, 1.0, v55
	v_rcp_f32_e32 v52, v52
	v_rcp_f32_e32 v53, v53
	v_rcp_f32_e32 v54, v54
	v_rcp_f32_e32 v55, v55
	v_lshl_add_u64 v[50:51], s[34:35], 0, v[120:121]
	v_pk_mul_f32 v[38:39], v[38:39], v[52:53]
	v_mul_f32_e32 v52, 0xbfb8aa3b, v34
	v_pk_mul_f32 v[40:41], v[40:41], v[54:55]
	v_mul_f32_e32 v53, 0xbfb8aa3b, v35
	v_mul_f32_e32 v54, 0xbfb8aa3b, v36
	v_mul_f32_e32 v55, 0xbfb8aa3b, v37
	v_exp_f32_e32 v52, v52
	v_exp_f32_e32 v53, v53
	v_exp_f32_e32 v54, v54
	v_exp_f32_e32 v55, v55
	v_add_f32_e32 v52, 1.0, v52
	v_add_f32_e32 v53, 1.0, v53
	v_add_f32_e32 v54, 1.0, v54
	v_add_f32_e32 v55, 1.0, v55
	v_lshl_add_u64 v[50:51], v[50:51], 0, v[182:183]
	v_cvt_pk_bf16_f32 v42, v46, v47
	v_cvt_pk_bf16_f32 v43, v48, v49
	v_rcp_f32_e32 v52, v52
	v_rcp_f32_e32 v53, v53
	v_rcp_f32_e32 v54, v54
	v_rcp_f32_e32 v55, v55
	global_store_dwordx4 v[50:51], v[42:45], off
	v_lshlrev_b32_e32 v46, 16, v100
	v_and_b32_e32 v47, 0xffff0000, v100
	v_lshlrev_b32_e32 v42, 16, v98
	v_and_b32_e32 v43, 0xffff0000, v98
	v_lshlrev_b32_e32 v44, 16, v99
	v_and_b32_e32 v45, 0xffff0000, v99
	v_lshlrev_b32_e32 v48, 16, v101
	v_and_b32_e32 v49, 0xffff0000, v101
	v_sub_f32_e32 v43, v43, v186
	v_sub_f32_e32 v42, v42, v186
	v_sub_f32_e32 v45, v45, v186
	v_sub_f32_e32 v44, v44, v186
	v_sub_f32_e32 v47, v47, v186
	v_sub_f32_e32 v46, v46, v186
	v_sub_f32_e32 v49, v49, v186
	v_sub_f32_e32 v48, v48, v186
	v_pk_mul_f32 v[44:45], v[186:187], v[44:45] op_sel:[1,0]
	v_pk_mul_f32 v[42:43], v[186:187], v[42:43] op_sel:[1,0]
	v_pk_mul_f32 v[48:49], v[186:187], v[48:49] op_sel:[1,0]
	v_pk_mul_f32 v[46:47], v[186:187], v[46:47] op_sel:[1,0]
	v_pk_mul_f32 v[42:43], v[70:71], v[42:43]
	v_pk_mul_f32 v[44:45], v[72:73], v[44:45]
	v_pk_mul_f32 v[46:47], v[66:67], v[46:47]
	v_pk_mul_f32 v[48:49], v[68:69], v[48:49]
	v_pk_mul_f32 v[34:35], v[34:35], v[52:53]
	v_pk_mul_f32 v[36:37], v[36:37], v[54:55]
	v_pk_mul_f32 v[40:41], v[40:41], v[44:45]
	v_pk_mul_f32 v[38:39], v[38:39], v[42:43]
	v_pk_mul_f32 v[42:43], v[36:37], v[48:49]
	v_pk_mul_f32 v[36:37], v[34:35], v[46:47]
	v_mul_f32_e32 v44, 0xbfb8aa3b, v30
	v_mul_f32_e32 v45, 0xbfb8aa3b, v31
	v_mul_f32_e32 v46, 0xbfb8aa3b, v32
	v_mul_f32_e32 v47, 0xbfb8aa3b, v33
	v_exp_f32_e32 v44, v44
	v_exp_f32_e32 v45, v45
	v_exp_f32_e32 v46, v46
	v_exp_f32_e32 v47, v47
	v_add_f32_e32 v44, 1.0, v44
	v_add_f32_e32 v45, 1.0, v45
	v_add_f32_e32 v46, 1.0, v46
	v_add_f32_e32 v47, 1.0, v47
	v_rcp_f32_e32 v44, v44
	v_rcp_f32_e32 v45, v45
	v_rcp_f32_e32 v46, v46
	v_rcp_f32_e32 v47, v47
	v_cvt_pk_bf16_f32 v36, v36, v37
	v_pk_mul_f32 v[30:31], v[30:31], v[44:45]
	v_mul_f32_e32 v44, 0xbfb8aa3b, v26
	v_pk_mul_f32 v[32:33], v[32:33], v[46:47]
	v_mul_f32_e32 v45, 0xbfb8aa3b, v27
	v_mul_f32_e32 v46, 0xbfb8aa3b, v28
	v_mul_f32_e32 v47, 0xbfb8aa3b, v29
	v_exp_f32_e32 v44, v44
	v_exp_f32_e32 v45, v45
	v_exp_f32_e32 v46, v46
	v_exp_f32_e32 v47, v47
	v_add_f32_e32 v44, 1.0, v44
	v_add_f32_e32 v45, 1.0, v45
	v_add_f32_e32 v46, 1.0, v46
	v_add_f32_e32 v47, 1.0, v47
	v_cvt_pk_bf16_f32 v37, v42, v43
	v_rcp_f32_e32 v44, v44
	v_rcp_f32_e32 v45, v45
	v_rcp_f32_e32 v46, v46
	v_rcp_f32_e32 v47, v47
	v_cvt_pk_bf16_f32 v34, v38, v39
	v_cvt_pk_bf16_f32 v35, v40, v41
	global_store_dwordx4 v[50:51], v[34:37], off offset:256
	v_lshlrev_b32_e32 v40, 16, v96
	v_and_b32_e32 v41, 0xffff0000, v96
	v_lshlrev_b32_e32 v36, 16, v94
	v_and_b32_e32 v37, 0xffff0000, v94
	v_lshlrev_b32_e32 v42, 16, v97
	v_and_b32_e32 v43, 0xffff0000, v97
	v_lshlrev_b32_e32 v38, 16, v95
	v_and_b32_e32 v39, 0xffff0000, v95
	v_sub_f32_e32 v37, v37, v184
	v_sub_f32_e32 v36, v36, v184
	v_sub_f32_e32 v41, v41, v184
	v_sub_f32_e32 v40, v40, v184
	v_sub_f32_e32 v43, v43, v184
	v_sub_f32_e32 v42, v42, v184
; __device__ __forceinline__ unsigned cvt_pk_bf16(float lo, float hi) { unsigned r; asm("v_cvt_pk_bf16_f32 %0, %1, %2" : "=v"(r) : "v"(lo), "v"(hi)); return r; }
; __device__ __forceinline__ float bf_lo(unsigned u) { return __uint_as_float(u << 16); }
; __device__ __forceinline__ float bf_hi(unsigned u) { return __uint_as_float(u & 0xffff0000u); }
;     __device__ __forceinline__ void operator()(const AccT& acc, const Unit& u, int wr, int wc, int fr, int fq) const {
;     ...
;             for (int m = 0; m < 4; ++m) { bf16_t* rowp = A2 + (size_t)(row0 + ai * 128 + m * 16) * 2048 + col0;
;                 const float mu = st[ai][m][0], rs = st[ai][m][1];
; #pragma unroll
;                 for (int bj = 0; bj < 2; ++bj) { const f32x4 v0 = acc[ai][bj][m][0], v1 = acc[ai][bj][m][1]; const u32x4 yw = yv[m][bj];
;                     const f32x4 y0 = (f32x4){bf_lo(yw.x), bf_hi(yw.x), bf_lo(yw.y), bf_hi(yw.y)}, y1 = (f32x4){bf_lo(yw.z), bf_hi(yw.z), bf_lo(yw.w), bf_hi(yw.w)};
;                     const f32x4 n0 = (y0 - mu) * rs * gw[bj][0], n1 = (y1 - mu) * rs * gw[bj][1];
;                     const f32x4 s0 = silu4(v0) * n0, s1 = silu4(v1) * n1;
;                     u32x4 w; w.x = cvt_pk_bf16(s0[0], s0[1]); w.y = cvt_pk_bf16(s0[2], s0[3]); w.z = cvt_pk_bf16(s1[0], s1[1]); w.w = cvt_pk_bf16(s1[2], s1[3]);
;                     *(u32x4*)(rowp + bj * 128) = w; } }
	v_sub_f32_e32 v39, v39, v184
	v_sub_f32_e32 v38, v38, v184
	v_pk_mul_f32 v[36:37], v[184:185], v[36:37] op_sel:[1,0]
	v_pk_mul_f32 v[42:43], v[184:185], v[42:43] op_sel:[1,0]
	v_pk_mul_f32 v[40:41], v[184:185], v[40:41] op_sel:[1,0]
	v_pk_mul_f32 v[38:39], v[184:185], v[38:39] op_sel:[1,0]
	v_pk_mul_f32 v[36:37], v[86:87], v[36:37]
	v_pk_mul_f32 v[40:41], v[82:83], v[40:41]
	v_pk_mul_f32 v[42:43], v[84:85], v[42:43]
	v_pk_mul_f32 v[26:27], v[26:27], v[44:45]
	v_pk_mul_f32 v[28:29], v[28:29], v[46:47]
	v_pk_mul_f32 v[38:39], v[88:89], v[38:39]
	v_pk_mul_f32 v[30:31], v[30:31], v[36:37]
	v_pk_mul_f32 v[36:37], v[28:29], v[42:43]
	v_pk_mul_f32 v[28:29], v[26:27], v[40:41]
	v_pk_mul_f32 v[32:33], v[32:33], v[38:39]
	v_cvt_pk_bf16_f32 v28, v28, v29
	v_cvt_pk_bf16_f32 v29, v36, v37
	v_mul_f32_e32 v36, 0xbfb8aa3b, v22
	v_mul_f32_e32 v37, 0xbfb8aa3b, v23
	v_mul_f32_e32 v38, 0xbfb8aa3b, v24
	v_mul_f32_e32 v39, 0xbfb8aa3b, v25
	v_exp_f32_e32 v36, v36
	v_exp_f32_e32 v37, v37
	v_exp_f32_e32 v38, v38
	v_exp_f32_e32 v39, v39
	v_add_f32_e32 v36, 1.0, v36
	v_add_f32_e32 v37, 1.0, v37
	v_add_f32_e32 v38, 1.0, v38
	v_add_f32_e32 v39, 1.0, v39
	v_rcp_f32_e32 v36, v36
	v_rcp_f32_e32 v37, v37
	v_rcp_f32_e32 v38, v38
	v_rcp_f32_e32 v39, v39
	v_lshl_add_u64 v[34:35], s[34:35], 0, v[104:105]
	v_pk_mul_f32 v[22:23], v[22:23], v[36:37]
	v_mul_f32_e32 v36, 0xbfb8aa3b, v18
	v_pk_mul_f32 v[24:25], v[24:25], v[38:39]
	v_mul_f32_e32 v37, 0xbfb8aa3b, v19
	v_mul_f32_e32 v38, 0xbfb8aa3b, v20
	v_mul_f32_e32 v39, 0xbfb8aa3b, v21
	v_exp_f32_e32 v36, v36
	v_exp_f32_e32 v37, v37
	v_exp_f32_e32 v38, v38
	v_exp_f32_e32 v39, v39
	v_add_f32_e32 v36, 1.0, v36
	v_add_f32_e32 v37, 1.0, v37
	v_add_f32_e32 v38, 1.0, v38
	v_add_f32_e32 v39, 1.0, v39
	v_lshl_add_u64 v[34:35], v[34:35], 0, v[182:183]
	v_cvt_pk_bf16_f32 v26, v30, v31
	v_cvt_pk_bf16_f32 v27, v32, v33
	v_rcp_f32_e32 v36, v36
	v_rcp_f32_e32 v37, v37
	v_rcp_f32_e32 v38, v38
	v_rcp_f32_e32 v39, v39
	global_store_dwordx4 v[34:35], v[26:29], off
	v_lshlrev_b32_e32 v30, 16, v92
	v_and_b32_e32 v31, 0xffff0000, v92
	v_lshlrev_b32_e32 v26, 16, v90
	v_and_b32_e32 v27, 0xffff0000, v90
	v_lshlrev_b32_e32 v28, 16, v91
	v_and_b32_e32 v29, 0xffff0000, v91
	v_lshlrev_b32_e32 v32, 16, v93
	v_and_b32_e32 v33, 0xffff0000, v93
	v_sub_f32_e32 v27, v27, v184
	v_sub_f32_e32 v26, v26, v184
	v_sub_f32_e32 v29, v29, v184
	v_sub_f32_e32 v28, v28, v184
	v_sub_f32_e32 v31, v31, v184
	v_sub_f32_e32 v30, v30, v184
	v_sub_f32_e32 v33, v33, v184
	v_sub_f32_e32 v32, v32, v184
	v_pk_mul_f32 v[28:29], v[184:185], v[28:29] op_sel:[1,0]
	v_pk_mul_f32 v[26:27], v[184:185], v[26:27] op_sel:[1,0]
	v_pk_mul_f32 v[32:33], v[184:185], v[32:33] op_sel:[1,0]
	v_pk_mul_f32 v[30:31], v[184:185], v[30:31] op_sel:[1,0]
	v_pk_mul_f32 v[26:27], v[70:71], v[26:27]
	v_pk_mul_f32 v[28:29], v[72:73], v[28:29]
	v_pk_mul_f32 v[30:31], v[66:67], v[30:31]
	v_pk_mul_f32 v[32:33], v[68:69], v[32:33]
	v_pk_mul_f32 v[18:19], v[18:19], v[36:37]
	v_pk_mul_f32 v[20:21], v[20:21], v[38:39]
	v_pk_mul_f32 v[24:25], v[24:25], v[28:29]
	v_pk_mul_f32 v[22:23], v[22:23], v[26:27]
	v_pk_mul_f32 v[26:27], v[20:21], v[32:33]
	v_pk_mul_f32 v[20:21], v[18:19], v[30:31]
	v_mul_f32_e32 v28, 0xbfb8aa3b, v14
	v_mul_f32_e32 v29, 0xbfb8aa3b, v15
	v_mul_f32_e32 v30, 0xbfb8aa3b, v16
	v_mul_f32_e32 v31, 0xbfb8aa3b, v17
	v_exp_f32_e32 v28, v28
	v_exp_f32_e32 v29, v29
	v_exp_f32_e32 v30, v30
	v_exp_f32_e32 v31, v31
	v_add_f32_e32 v28, 1.0, v28
	v_add_f32_e32 v29, 1.0, v29
	v_add_f32_e32 v30, 1.0, v30
	v_add_f32_e32 v31, 1.0, v31
	v_rcp_f32_e32 v28, v28
	v_rcp_f32_e32 v29, v29
	v_rcp_f32_e32 v30, v30
	v_rcp_f32_e32 v31, v31
	v_cvt_pk_bf16_f32 v20, v20, v21
	v_pk_mul_f32 v[14:15], v[14:15], v[28:29]
	v_mul_f32_e32 v28, 0xbfb8aa3b, v10
	v_pk_mul_f32 v[16:17], v[16:17], v[30:31]
	v_mul_f32_e32 v29, 0xbfb8aa3b, v11
	v_mul_f32_e32 v30, 0xbfb8aa3b, v12
	v_mul_f32_e32 v31, 0xbfb8aa3b, v13
	v_exp_f32_e32 v28, v28
	v_exp_f32_e32 v29, v29
	v_exp_f32_e32 v30, v30
	v_exp_f32_e32 v31, v31
	v_add_f32_e32 v28, 1.0, v28
	v_add_f32_e32 v29, 1.0, v29
	v_add_f32_e32 v30, 1.0, v30
	v_add_f32_e32 v31, 1.0, v31
	v_cvt_pk_bf16_f32 v21, v26, v27
	v_rcp_f32_e32 v28, v28
	v_rcp_f32_e32 v29, v29
; __device__ __forceinline__ unsigned cvt_pk_bf16(float lo, float hi) { unsigned r; asm("v_cvt_pk_bf16_f32 %0, %1, %2" : "=v"(r) : "v"(lo), "v"(hi)); return r; }
; __device__ __forceinline__ float bf_lo(unsigned u) { return __uint_as_float(u << 16); }
; __device__ __forceinline__ float bf_hi(unsigned u) { return __uint_as_float(u & 0xffff0000u); }
; #define PG8_WAIT_V(n) asm volatile("s_waitcnt vmcnt(" #n ")" ::: "memory")
; #define PG8_BAR __builtin_amdgcn_s_barrier()
; template <class Epi>
; __device__ __forceinline__ void gemm_phase(LAS unsigned char* lds, const Gemm g, const Epi& E) {
;     ...
;         if (!has_next) break;
; #pragma unroll
;         for (int a = 0; a < 2; ++a)
; #pragma unroll
;             for (int b = 0; b < 2; ++b)
; #pragma unroll
;                 for (int m = 0; m < 4; ++m)
; #pragma unroll
;                     for (int n = 0; n < 2; ++n) acc[a][b][m][n] = (f32x4){0.f, 0.f, 0.f, 0.f};
;         cur = nxt; cA = nA; cB = nB; ++ui;
;     }
;     PG8_WAIT_V(0);
;     if (wr == 0) PG8_BAR;
;     PG8_BAR;
;     __device__ __forceinline__ void operator()(const AccT& acc, const Unit& u, int wr, int wc, int fr, int fq) const {
;     ...
;             for (int m = 0; m < 4; ++m) { bf16_t* rowp = A2 + (size_t)(row0 + ai * 128 + m * 16) * 2048 + col0;
;                 const float mu = st[ai][m][0], rs = st[ai][m][1];
; #pragma unroll
;                 for (int bj = 0; bj < 2; ++bj) { const f32x4 v0 = acc[ai][bj][m][0], v1 = acc[ai][bj][m][1]; const u32x4 yw = yv[m][bj];
;                     const f32x4 y0 = (f32x4){bf_lo(yw.x), bf_hi(yw.x), bf_lo(yw.y), bf_hi(yw.y)}, y1 = (f32x4){bf_lo(yw.z), bf_hi(yw.z), bf_lo(yw.w), bf_hi(yw.w)};
;                     const f32x4 n0 = (y0 - mu) * rs * gw[bj][0], n1 = (y1 - mu) * rs * gw[bj][1];
;                     const f32x4 s0 = silu4(v0) * n0, s1 = silu4(v1) * n1;
;                     u32x4 w; w.x = cvt_pk_bf16(s0[0], s0[1]); w.y = cvt_pk_bf16(s0[2], s0[3]); w.z = cvt_pk_bf16(s1[0], s1[1]); w.w = cvt_pk_bf16(s1[2], s1[3]);
;                     *(u32x4*)(rowp + bj * 128) = w; } }
	v_rcp_f32_e32 v30, v30
	v_rcp_f32_e32 v31, v31
	v_cvt_pk_bf16_f32 v18, v22, v23
	v_cvt_pk_bf16_f32 v19, v24, v25
	global_store_dwordx4 v[34:35], v[18:21], off offset:256
	v_lshlrev_b32_e32 v24, 16, v80
	v_and_b32_e32 v25, 0xffff0000, v80
	v_lshlrev_b32_e32 v20, 16, v78
	v_and_b32_e32 v21, 0xffff0000, v78
	v_lshlrev_b32_e32 v26, 16, v81
	v_and_b32_e32 v27, 0xffff0000, v81
	v_lshlrev_b32_e32 v22, 16, v79
	v_and_b32_e32 v23, 0xffff0000, v79
	v_sub_f32_e32 v21, v21, v180
	v_sub_f32_e32 v20, v20, v180
	v_sub_f32_e32 v25, v25, v180
	v_sub_f32_e32 v24, v24, v180
	v_sub_f32_e32 v27, v27, v180
	v_sub_f32_e32 v26, v26, v180
	v_sub_f32_e32 v23, v23, v180
	v_sub_f32_e32 v22, v22, v180
	v_pk_mul_f32 v[20:21], v[180:181], v[20:21] op_sel:[1,0]
	v_pk_mul_f32 v[26:27], v[180:181], v[26:27] op_sel:[1,0]
	v_pk_mul_f32 v[24:25], v[180:181], v[24:25] op_sel:[1,0]
	v_pk_mul_f32 v[22:23], v[180:181], v[22:23] op_sel:[1,0]
	v_pk_mul_f32 v[20:21], v[86:87], v[20:21]
	v_pk_mul_f32 v[24:25], v[82:83], v[24:25]
	v_pk_mul_f32 v[26:27], v[84:85], v[26:27]
	v_pk_mul_f32 v[10:11], v[10:11], v[28:29]
	v_pk_mul_f32 v[12:13], v[12:13], v[30:31]
	v_pk_mul_f32 v[22:23], v[88:89], v[22:23]
	v_pk_mul_f32 v[14:15], v[14:15], v[20:21]
	v_pk_mul_f32 v[20:21], v[12:13], v[26:27]
	v_pk_mul_f32 v[12:13], v[10:11], v[24:25]
	v_pk_mul_f32 v[16:17], v[16:17], v[22:23]
	v_cvt_pk_bf16_f32 v12, v12, v13
	v_cvt_pk_bf16_f32 v13, v20, v21
	v_mul_f32_e32 v20, 0xbfb8aa3b, v6
	v_mul_f32_e32 v21, 0xbfb8aa3b, v7
	v_mul_f32_e32 v22, 0xbfb8aa3b, v8
	v_mul_f32_e32 v23, 0xbfb8aa3b, v9
	v_exp_f32_e32 v20, v20
	v_exp_f32_e32 v21, v21
	v_exp_f32_e32 v22, v22
	v_exp_f32_e32 v23, v23
	v_add_f32_e32 v20, 1.0, v20
	v_add_f32_e32 v21, 1.0, v21
	v_add_f32_e32 v22, 1.0, v22
	v_add_f32_e32 v23, 1.0, v23
	v_rcp_f32_e32 v20, v20
	v_rcp_f32_e32 v21, v21
	v_rcp_f32_e32 v22, v22
	v_rcp_f32_e32 v23, v23
	v_lshl_add_u64 v[18:19], s[34:35], 0, v[102:103]
	v_pk_mul_f32 v[6:7], v[6:7], v[20:21]
	v_mul_f32_e32 v20, 0xbfb8aa3b, v2
	v_pk_mul_f32 v[8:9], v[8:9], v[22:23]
	v_mul_f32_e32 v21, 0xbfb8aa3b, v3
	v_mul_f32_e32 v22, 0xbfb8aa3b, v4
	v_mul_f32_e32 v23, 0xbfb8aa3b, v5
	v_exp_f32_e32 v20, v20
	v_exp_f32_e32 v21, v21
	v_exp_f32_e32 v22, v22
	v_exp_f32_e32 v23, v23
	v_add_f32_e32 v20, 1.0, v20
	v_add_f32_e32 v21, 1.0, v21
	v_add_f32_e32 v22, 1.0, v22
	v_add_f32_e32 v23, 1.0, v23
	v_lshl_add_u64 v[18:19], v[18:19], 0, v[182:183]
	v_cvt_pk_bf16_f32 v10, v14, v15
	v_cvt_pk_bf16_f32 v11, v16, v17
	v_rcp_f32_e32 v20, v20
	v_rcp_f32_e32 v21, v21
	v_rcp_f32_e32 v22, v22
	v_rcp_f32_e32 v23, v23
	global_store_dwordx4 v[18:19], v[10:13], off
	v_lshlrev_b32_e32 v14, 16, v76
	v_and_b32_e32 v15, 0xffff0000, v76
	v_lshlrev_b32_e32 v10, 16, v74
	v_and_b32_e32 v11, 0xffff0000, v74
	v_lshlrev_b32_e32 v16, 16, v77
	v_and_b32_e32 v17, 0xffff0000, v77
	v_lshlrev_b32_e32 v12, 16, v75
	v_and_b32_e32 v13, 0xffff0000, v75
	v_sub_f32_e32 v11, v11, v180
	v_sub_f32_e32 v10, v10, v180
	v_sub_f32_e32 v15, v15, v180
	v_sub_f32_e32 v14, v14, v180
	v_sub_f32_e32 v17, v17, v180
	v_sub_f32_e32 v16, v16, v180
	v_sub_f32_e32 v13, v13, v180
	v_sub_f32_e32 v12, v12, v180
	v_pk_mul_f32 v[10:11], v[180:181], v[10:11] op_sel:[1,0]
	v_pk_mul_f32 v[16:17], v[180:181], v[16:17] op_sel:[1,0]
	v_pk_mul_f32 v[14:15], v[180:181], v[14:15] op_sel:[1,0]
	v_pk_mul_f32 v[12:13], v[180:181], v[12:13] op_sel:[1,0]
	v_pk_mul_f32 v[10:11], v[70:71], v[10:11]
	v_pk_mul_f32 v[14:15], v[66:67], v[14:15]
	v_pk_mul_f32 v[16:17], v[68:69], v[16:17]
	v_pk_mul_f32 v[2:3], v[2:3], v[20:21]
	v_pk_mul_f32 v[4:5], v[4:5], v[22:23]
	v_pk_mul_f32 v[12:13], v[72:73], v[12:13]
	v_pk_mul_f32 v[6:7], v[6:7], v[10:11]
	v_pk_mul_f32 v[10:11], v[4:5], v[16:17]
	v_pk_mul_f32 v[4:5], v[2:3], v[14:15]
	v_pk_mul_f32 v[8:9], v[8:9], v[12:13]
	v_cvt_pk_bf16_f32 v2, v6, v7
	v_cvt_pk_bf16_f32 v4, v4, v5
	v_cvt_pk_bf16_f32 v5, v10, v11
	s_nop 0
	v_cvt_pk_bf16_f32 v3, v8, v9
	global_store_dwordx4 v[18:19], v[2:5], off offset:256
	s_and_b64 vcc, exec, s[2:3]
	s_mov_b32 s12, s8
	s_mov_b32 s52, s64
	s_mov_b64 s[16:17], s[4:5]
	s_mov_b64 s[14:15], s[10:11]
	s_cbranch_vccz .LBB0_470
	s_waitcnt vmcnt(0)
	s_cmpk_gt_u32 s1, 0xff
	s_cbranch_scc1 .LBB0_479
	s_barrier

; #define PG8_STAGE(bufoff, gbase, voff) do { _Pragma("unroll") for (int _i = 0; _i < 2; ++_i) \
;         __builtin_amdgcn_global_load_lds((const unsigned*)((const char*)(gbase) + (voff)[_i]), (LAS unsigned*)(lds + (bufoff) + ldsw + _i * 8192), 16, 0, 0); } while (0)
; #define PG8_LDA(dst, b, h) do { _Pragma("unroll") for (int m = 0; m < 4; ++m) _Pragma("unroll") for (int k = 0; k < 2; ++k) dst[m][k] = *(const LAS bf16x8*)(lds + PG8_SA(b, h) + aoff + m * 2048 + k * 1024); } while (0)
; #define PG8_LDB(dst, b, h) do { _Pragma("unroll") for (int n = 0; n < 2; ++n) _Pragma("unroll") for (int k = 0; k < 2; ++k) dst[n][k] = *(const LAS bf16x8*)(lds + PG8_SB(b, h) + boff + n * 2048 + k * 1024); } while (0)
; #define PG8_MMA(ai, bj, At, Bt) do { __builtin_amdgcn_s_setprio(1); _Pragma("unroll") for (int m = 0; m < 4; ++m) _Pragma("unroll") for (int n = 0; n < 2; ++n) _Pragma("unroll") for (int k = 0; k < 2; ++k) \
;         acc[ai][bj][m][n] = __builtin_amdgcn_mfma_f32_16x16x32_bf16(Bt[n][k], At[m][k], acc[ai][bj][m][n], 0, 0, 0); __builtin_amdgcn_s_setprio(0); } while (0)
; #define PG8_WAIT_L(n) asm volatile("s_waitcnt lgkmcnt(" #n ")" ::: "memory")
; #define PG8_BAR __builtin_amdgcn_s_barrier()
; #define PG8_SCHED __builtin_amdgcn_sched_barrier(0)
; template <class Epi>
; __device__ __forceinline__ void gemm_phase(LAS unsigned char* lds, const Gemm g, const Epi& E) {
;     ...
;             PG8_LDB(B0, 0, 0); PG8_SCHED; PG8_LDA(At, 0, 0); PG8_STAGE(PG8_SA(1, 1), a1 + hstepA, voffA);
;             PG8_WAIT_L(8); PG8_BAR; PG8_WAIT_L(0); PG8_MMA(0, 0, At, B0); PG8_BAR; PG8_SCHED;
;             PG8_LDB(B1, 0, 1); PG8_STAGE(PG8_SB(0, 0), b2, voffB);
;             PG8_BAR; PG8_WAIT_L(0); PG8_MMA(0, 1, At, B1); PG8_BAR;
;             PG8_LDA(At, 0, 1); PG8_STAGE(PG8_SA(0, 0), a2, voffA);
;             PG8_BAR; PG8_WAIT_L(0); PG8_MMA(1, 0, At, B0); PG8_BAR; PG8_SCHED;
.LBB0_495:
	s_add_u32 s14, s12, 0xfff80080
	s_addc_u32 s15, s13, -1
	s_add_i32 s66, 0, 0x10000
	v_add_u32_e32 v142, s66, v159
	ds_read_b128 v[130:133], v142
	ds_read_b128 v[134:137], v142 offset:1024
	ds_read_b128 v[138:141], v142 offset:2048
	ds_read_b128 v[142:145], v142 offset:3072
	s_cmp_eq_u32 s65, 28
	s_cselect_b32 s17, s9, s15
	s_cselect_b32 s16, s8, s14
	s_cselect_b32 s15, s5, s64
	s_cselect_b32 s14, s4, s7
	v_lshl_add_u64 v[192:193], s[12:13], 0, v[150:151]
	s_add_i32 m0, s11, 0xc000
	ds_read_b128 v[154:157], v160
	ds_read_b128 v[162:165], v160 offset:1024
	ds_read_b128 v[166:169], v160 offset:2048
	ds_read_b128 v[170:173], v160 offset:3072
	ds_read_b128 v[174:177], v160 offset:4096
	ds_read_b128 v[180:183], v160 offset:5120
	ds_read_b128 v[184:187], v160 offset:6144
	ds_read_b128 v[188:191], v160 offset:7168
	global_load_lds_dwordx4 v[192:193], off
	v_lshl_add_u64 v[192:193], s[12:13], 0, v[152:153]
	s_add_i32 m0, s11, 0xe000
	s_nop 0
	global_load_lds_dwordx4 v[192:193], off
	s_waitcnt lgkmcnt(0)
	s_barrier
	v_mfma_f32_16x16x32_bf16 v[126:129], v[130:133], v[154:157], v[126:129]
	v_mfma_f32_16x16x32_bf16 v[122:125], v[138:141], v[154:157], v[122:125]
	v_mfma_f32_16x16x32_bf16 v[114:117], v[130:133], v[166:169], v[114:117]
	v_mfma_f32_16x16x32_bf16 v[106:109], v[138:141], v[166:169], v[106:109]
	v_mfma_f32_16x16x32_bf16 v[102:105], v[130:133], v[174:177], v[102:105]
	v_mfma_f32_16x16x32_bf16 v[90:93], v[138:141], v[174:177], v[90:93]
	v_mfma_f32_16x16x32_bf16 v[86:89], v[130:133], v[184:187], v[86:89]
	v_mfma_f32_16x16x32_bf16 v[74:77], v[138:141], v[184:187], v[74:77]
	v_mfma_f32_16x16x32_bf16 v[126:129], v[134:137], v[162:165], v[126:129]
	v_mfma_f32_16x16x32_bf16 v[122:125], v[142:145], v[162:165], v[122:125]
	v_mfma_f32_16x16x32_bf16 v[114:117], v[134:137], v[170:173], v[114:117]
	v_mfma_f32_16x16x32_bf16 v[106:109], v[142:145], v[170:173], v[106:109]
	v_mfma_f32_16x16x32_bf16 v[102:105], v[134:137], v[180:183], v[102:105]
	v_mfma_f32_16x16x32_bf16 v[90:93], v[142:145], v[180:183], v[90:93]
	v_mfma_f32_16x16x32_bf16 v[86:89], v[134:137], v[188:191], v[86:89]
	v_mfma_f32_16x16x32_bf16 v[74:77], v[142:145], v[188:191], v[74:77]
	s_barrier
	s_add_i32 s68, 0, 0x14000
	s_add_i32 s66, s66, s25
	v_add_u32_e32 v161, s68, v159
	v_lshl_add_u64 v[208:209], s[14:15], 0, v[148:149]
	s_mov_b32 m0, s66
	ds_read_b128 v[192:195], v161
	ds_read_b128 v[196:199], v161 offset:1024
	ds_read_b128 v[200:203], v161 offset:2048
	ds_read_b128 v[204:207], v161 offset:3072
	global_load_lds_dwordx4 v[208:209], off
	v_lshl_add_u64 v[226:227], s[14:15], 0, v[146:147]
	s_add_i32 m0, s66, 0x2000
	s_nop 0
	global_load_lds_dwordx4 v[226:227], off
	s_nop 1
	s_mov_b32 m0, s11
	v_lshl_add_u64 v[228:229], s[16:17], 0, v[148:149]
	s_waitcnt lgkmcnt(0)
	s_barrier
	v_mfma_f32_16x16x32_bf16 v[118:121], v[192:195], v[154:157], v[118:121]
	v_mfma_f32_16x16x32_bf16 v[110:113], v[200:203], v[154:157], v[110:113]
	v_mfma_f32_16x16x32_bf16 v[98:101], v[192:195], v[166:169], v[98:101]
	v_mfma_f32_16x16x32_bf16 v[94:97], v[200:203], v[166:169], v[94:97]
	v_mfma_f32_16x16x32_bf16 v[82:85], v[192:195], v[174:177], v[82:85]
	v_mfma_f32_16x16x32_bf16 v[78:81], v[200:203], v[174:177], v[78:81]
	v_mfma_f32_16x16x32_bf16 v[70:73], v[192:195], v[184:187], v[70:73]
	v_mfma_f32_16x16x32_bf16 v[66:69], v[200:203], v[184:187], v[66:69]
	v_mfma_f32_16x16x32_bf16 v[118:121], v[196:199], v[162:165], v[118:121]
	v_mfma_f32_16x16x32_bf16 v[110:113], v[204:207], v[162:165], v[110:113]
	v_mfma_f32_16x16x32_bf16 v[98:101], v[196:199], v[170:173], v[98:101]
	v_mfma_f32_16x16x32_bf16 v[94:97], v[204:207], v[170:173], v[94:97]
	v_mfma_f32_16x16x32_bf16 v[82:85], v[196:199], v[180:183], v[82:85]
	v_mfma_f32_16x16x32_bf16 v[78:81], v[204:207], v[180:183], v[78:81]
	v_mfma_f32_16x16x32_bf16 v[70:73], v[196:199], v[188:191], v[70:73]
	v_mfma_f32_16x16x32_bf16 v[66:69], v[204:207], v[188:191], v[66:69]
	s_barrier
	ds_read_b128 v[154:157], v160 offset:16384
	ds_read_b128 v[162:165], v160 offset:17408
	ds_read_b128 v[166:169], v160 offset:18432
	ds_read_b128 v[170:173], v160 offset:19456
	ds_read_b128 v[174:177], v160 offset:20480
	ds_read_b128 v[180:183], v160 offset:21504
	ds_read_b128 v[184:187], v160 offset:22528
	ds_read_b128 v[188:191], v160 offset:23552
	global_load_lds_dwordx4 v[228:229], off
	v_lshl_add_u64 v[230:231], s[16:17], 0, v[146:147]
	s_mov_b32 m0, s31
	s_nop 0
	global_load_lds_dwordx4 v[230:231], off
	s_waitcnt lgkmcnt(0)
	s_barrier
	v_mfma_f32_16x16x32_bf16 v[62:65], v[130:133], v[154:157], v[62:65]
	v_mfma_f32_16x16x32_bf16 v[58:61], v[138:141], v[154:157], v[58:61]
	v_mfma_f32_16x16x32_bf16 v[54:57], v[130:133], v[166:169], v[54:57]
	v_mfma_f32_16x16x32_bf16 v[42:45], v[138:141], v[166:169], v[42:45]
	v_mfma_f32_16x16x32_bf16 v[38:41], v[130:133], v[174:177], v[38:41]
	v_mfma_f32_16x16x32_bf16 v[26:29], v[138:141], v[174:177], v[26:29]
	v_mfma_f32_16x16x32_bf16 v[22:25], v[130:133], v[184:187], v[22:25]
	v_mfma_f32_16x16x32_bf16 v[10:13], v[138:141], v[184:187], v[10:13]
	v_mfma_f32_16x16x32_bf16 v[62:65], v[134:137], v[162:165], v[62:65]
	v_mfma_f32_16x16x32_bf16 v[58:61], v[142:145], v[162:165], v[58:61]
	v_mfma_f32_16x16x32_bf16 v[54:57], v[134:137], v[170:173], v[54:57]
	v_mfma_f32_16x16x32_bf16 v[42:45], v[142:145], v[170:173], v[42:45]
	v_mfma_f32_16x16x32_bf16 v[38:41], v[134:137], v[180:183], v[38:41]
	v_mfma_f32_16x16x32_bf16 v[26:29], v[142:145], v[180:183], v[26:29]
	v_mfma_f32_16x16x32_bf16 v[22:25], v[134:137], v[188:191], v[22:25]
	v_mfma_f32_16x16x32_bf16 v[10:13], v[142:145], v[188:191], v[10:13]
	s_barrier
; #define PG8_STAGE(bufoff, gbase, voff) do { _Pragma("unroll") for (int _i = 0; _i < 2; ++_i) \
;         __builtin_amdgcn_global_load_lds((const unsigned*)((const char*)(gbase) + (voff)[_i]), (LAS unsigned*)(lds + (bufoff) + ldsw + _i * 8192), 16, 0, 0); } while (0)
; #define PG8_LDA(dst, b, h) do { _Pragma("unroll") for (int m = 0; m < 4; ++m) _Pragma("unroll") for (int k = 0; k < 2; ++k) dst[m][k] = *(const LAS bf16x8*)(lds + PG8_SA(b, h) + aoff + m * 2048 + k * 1024); } while (0)
; #define PG8_LDB(dst, b, h) do { _Pragma("unroll") for (int n = 0; n < 2; ++n) _Pragma("unroll") for (int k = 0; k < 2; ++k) dst[n][k] = *(const LAS bf16x8*)(lds + PG8_SB(b, h) + boff + n * 2048 + k * 1024); } while (0)
; #define PG8_MMA(ai, bj, At, Bt) do { __builtin_amdgcn_s_setprio(1); _Pragma("unroll") for (int m = 0; m < 4; ++m) _Pragma("unroll") for (int n = 0; n < 2; ++n) _Pragma("unroll") for (int k = 0; k < 2; ++k) \
;         acc[ai][bj][m][n] = __builtin_amdgcn_mfma_f32_16x16x32_bf16(Bt[n][k], At[m][k], acc[ai][bj][m][n], 0, 0, 0); __builtin_amdgcn_s_setprio(0); } while (0)
; #define PG8_WAIT_V(n) asm volatile("s_waitcnt vmcnt(" #n ")" ::: "memory")
; #define PG8_WAIT_L(n) asm volatile("s_waitcnt lgkmcnt(" #n ")" ::: "memory")
; #define PG8_BAR __builtin_amdgcn_s_barrier()
; #define PG8_SCHED __builtin_amdgcn_sched_barrier(0)
; template <class Epi>
; __device__ __forceinline__ void gemm_phase(LAS unsigned char* lds, const Gemm g, const Epi& E) {
;     ...
;             PG8_STAGE(PG8_SB(0, 1), b2 + hstepB, voffB);
;             PG8_WAIT_V(6); PG8_BAR; PG8_MMA(1, 1, At, B1); PG8_BAR;
;             PG8_LDB(B0, 1, 0); PG8_SCHED; PG8_LDA(At, 1, 0); PG8_STAGE(PG8_SA(0, 1), a2 + hstepA, voffA);
;             PG8_WAIT_L(8); PG8_BAR; PG8_WAIT_L(0); PG8_MMA(0, 0, At, B0); PG8_BAR; PG8_SCHED;
;             PG8_LDB(B1, 1, 1); PG8_STAGE(PG8_SB(1, 0), b3, voffB);
;             PG8_BAR; PG8_WAIT_L(0); PG8_MMA(0, 1, At, B1); PG8_BAR;
;             PG8_LDA(At, 1, 1); PG8_STAGE(PG8_SA(1, 0), a3, voffA);
;             PG8_BAR; PG8_WAIT_L(0); PG8_MMA(1, 0, At, B0); PG8_BAR; PG8_SCHED;
	s_add_u32 s66, s14, 0x80000
	s_addc_u32 s67, s15, 0
	s_add_i32 s68, s68, s25
	v_lshl_add_u64 v[130:131], s[66:67], 0, v[148:149]
	s_mov_b32 m0, s68
	s_nop 0
	global_load_lds_dwordx4 v[130:131], off
	v_lshl_add_u64 v[130:131], s[66:67], 0, v[146:147]
	s_add_i32 m0, s68, 0x2000
	s_nop 0
	global_load_lds_dwordx4 v[130:131], off
	s_add_i32 s66, 0, 0x18000
	v_add_u32_e32 v142, s66, v159
	s_waitcnt vmcnt(6)
	s_barrier
	v_mfma_f32_16x16x32_bf16 v[50:53], v[192:195], v[154:157], v[50:53]
	v_mfma_f32_16x16x32_bf16 v[46:49], v[200:203], v[154:157], v[46:49]
	v_mfma_f32_16x16x32_bf16 v[34:37], v[192:195], v[166:169], v[34:37]
	v_mfma_f32_16x16x32_bf16 v[30:33], v[200:203], v[166:169], v[30:33]
	v_mfma_f32_16x16x32_bf16 v[18:21], v[192:195], v[174:177], v[18:21]
	v_mfma_f32_16x16x32_bf16 v[14:17], v[200:203], v[174:177], v[14:17]
	v_mfma_f32_16x16x32_bf16 v[6:9], v[192:195], v[184:187], v[6:9]
	v_mfma_f32_16x16x32_bf16 v[2:5], v[200:203], v[184:187], v[2:5]
	v_mfma_f32_16x16x32_bf16 v[50:53], v[196:199], v[162:165], v[50:53]
	v_mfma_f32_16x16x32_bf16 v[46:49], v[204:207], v[162:165], v[46:49]
	v_mfma_f32_16x16x32_bf16 v[34:37], v[196:199], v[170:173], v[34:37]
	v_mfma_f32_16x16x32_bf16 v[30:33], v[204:207], v[170:173], v[30:33]
	v_mfma_f32_16x16x32_bf16 v[18:21], v[196:199], v[180:183], v[18:21]
	v_mfma_f32_16x16x32_bf16 v[14:17], v[204:207], v[180:183], v[14:17]
	v_mfma_f32_16x16x32_bf16 v[6:9], v[196:199], v[188:191], v[6:9]
	v_mfma_f32_16x16x32_bf16 v[2:5], v[204:207], v[188:191], v[2:5]
	s_barrier
	ds_read_b128 v[130:133], v142
	ds_read_b128 v[134:137], v142 offset:1024
	ds_read_b128 v[138:141], v142 offset:2048
	ds_read_b128 v[142:145], v142 offset:3072
	s_add_u32 s16, s16, 0x80000
	s_addc_u32 s17, s17, 0
	s_mov_b32 m0, s36
	v_lshl_add_u64 v[192:193], s[16:17], 0, v[148:149]
	ds_read_b128 v[154:157], v160 offset:32768
	ds_read_b128 v[162:165], v160 offset:33792
	ds_read_b128 v[166:169], v160 offset:34816
	ds_read_b128 v[170:173], v160 offset:35840
	ds_read_b128 v[174:177], v160 offset:36864
	ds_read_b128 v[180:183], v160 offset:37888
	ds_read_b128 v[184:187], v160 offset:38912
	ds_read_b128 v[188:191], v160 offset:39936
	global_load_lds_dwordx4 v[192:193], off
	v_lshl_add_u64 v[192:193], s[16:17], 0, v[146:147]
	s_mov_b32 m0, s44
	s_nop 0
	global_load_lds_dwordx4 v[192:193], off
	s_waitcnt lgkmcnt(0)
	s_barrier
	v_mfma_f32_16x16x32_bf16 v[126:129], v[130:133], v[154:157], v[126:129]
	v_mfma_f32_16x16x32_bf16 v[122:125], v[138:141], v[154:157], v[122:125]
	v_mfma_f32_16x16x32_bf16 v[114:117], v[130:133], v[166:169], v[114:117]
	v_mfma_f32_16x16x32_bf16 v[106:109], v[138:141], v[166:169], v[106:109]
	v_mfma_f32_16x16x32_bf16 v[102:105], v[130:133], v[174:177], v[102:105]
	v_mfma_f32_16x16x32_bf16 v[90:93], v[138:141], v[174:177], v[90:93]
	v_mfma_f32_16x16x32_bf16 v[86:89], v[130:133], v[184:187], v[86:89]
	v_mfma_f32_16x16x32_bf16 v[74:77], v[138:141], v[184:187], v[74:77]
	v_mfma_f32_16x16x32_bf16 v[126:129], v[134:137], v[162:165], v[126:129]
	v_mfma_f32_16x16x32_bf16 v[122:125], v[142:145], v[162:165], v[122:125]
	v_mfma_f32_16x16x32_bf16 v[114:117], v[134:137], v[170:173], v[114:117]
	v_mfma_f32_16x16x32_bf16 v[106:109], v[142:145], v[170:173], v[106:109]
	v_mfma_f32_16x16x32_bf16 v[102:105], v[134:137], v[180:183], v[102:105]
	v_mfma_f32_16x16x32_bf16 v[90:93], v[142:145], v[180:183], v[90:93]
	v_mfma_f32_16x16x32_bf16 v[86:89], v[134:137], v[188:191], v[86:89]
	v_mfma_f32_16x16x32_bf16 v[74:77], v[142:145], v[188:191], v[74:77]
	s_barrier
	s_add_i32 s16, 0, 0x1c000
	s_add_i32 s17, s66, s25
	v_add_u32_e32 v161, s16, v159
	v_lshl_add_u64 v[208:209], v[208:209], 0, s[86:87]
	s_mov_b32 m0, s17
	ds_read_b128 v[192:195], v161
	ds_read_b128 v[196:199], v161 offset:1024
	ds_read_b128 v[200:203], v161 offset:2048
	ds_read_b128 v[204:207], v161 offset:3072
	global_load_lds_dwordx4 v[208:209], off
	v_lshl_add_u64 v[208:209], v[226:227], 0, s[86:87]
	s_add_i32 m0, s17, 0x2000
	s_nop 0
	global_load_lds_dwordx4 v[208:209], off
	s_nop 1
	s_mov_b32 m0, s53
	v_lshl_add_u64 v[208:209], v[228:229], 0, s[86:87]
	s_waitcnt lgkmcnt(0)
	s_barrier
	v_mfma_f32_16x16x32_bf16 v[118:121], v[192:195], v[154:157], v[118:121]
	v_mfma_f32_16x16x32_bf16 v[110:113], v[200:203], v[154:157], v[110:113]
	v_mfma_f32_16x16x32_bf16 v[98:101], v[192:195], v[166:169], v[98:101]
	v_mfma_f32_16x16x32_bf16 v[94:97], v[200:203], v[166:169], v[94:97]
	v_mfma_f32_16x16x32_bf16 v[82:85], v[192:195], v[174:177], v[82:85]
	v_mfma_f32_16x16x32_bf16 v[78:81], v[200:203], v[174:177], v[78:81]
	v_mfma_f32_16x16x32_bf16 v[70:73], v[192:195], v[184:187], v[70:73]
	v_mfma_f32_16x16x32_bf16 v[66:69], v[200:203], v[184:187], v[66:69]
	v_mfma_f32_16x16x32_bf16 v[118:121], v[196:199], v[162:165], v[118:121]
	v_mfma_f32_16x16x32_bf16 v[110:113], v[204:207], v[162:165], v[110:113]
	v_mfma_f32_16x16x32_bf16 v[98:101], v[196:199], v[170:173], v[98:101]
	v_mfma_f32_16x16x32_bf16 v[94:97], v[204:207], v[170:173], v[94:97]
	v_mfma_f32_16x16x32_bf16 v[82:85], v[196:199], v[180:183], v[82:85]
	v_mfma_f32_16x16x32_bf16 v[78:81], v[204:207], v[180:183], v[78:81]
	v_mfma_f32_16x16x32_bf16 v[70:73], v[196:199], v[188:191], v[70:73]
	v_mfma_f32_16x16x32_bf16 v[66:69], v[204:207], v[188:191], v[66:69]
	s_barrier
	ds_read_b128 v[154:157], v160 offset:49152
	ds_read_b128 v[162:165], v160 offset:50176
	ds_read_b128 v[166:169], v160 offset:51200
	ds_read_b128 v[170:173], v160 offset:52224
	ds_read_b128 v[174:177], v160 offset:53248
	ds_read_b128 v[180:183], v160 offset:54272
	ds_read_b128 v[184:187], v160 offset:55296
	ds_read_b128 v[188:191], v160 offset:56320
	global_load_lds_dwordx4 v[208:209], off
	v_lshl_add_u64 v[208:209], v[230:231], 0, s[86:87]
	s_mov_b32 m0, s58
	s_nop 0
	global_load_lds_dwordx4 v[208:209], off
	s_waitcnt lgkmcnt(0)
	s_barrier
; #define PG8_STAGE(bufoff, gbase, voff) do { _Pragma("unroll") for (int _i = 0; _i < 2; ++_i) \
;         __builtin_amdgcn_global_load_lds((const unsigned*)((const char*)(gbase) + (voff)[_i]), (LAS unsigned*)(lds + (bufoff) + ldsw + _i * 8192), 16, 0, 0); } while (0)
; #define PG8_MMA(ai, bj, At, Bt) do { __builtin_amdgcn_s_setprio(1); _Pragma("unroll") for (int m = 0; m < 4; ++m) _Pragma("unroll") for (int n = 0; n < 2; ++n) _Pragma("unroll") for (int k = 0; k < 2; ++k) \
;         acc[ai][bj][m][n] = __builtin_amdgcn_mfma_f32_16x16x32_bf16(Bt[n][k], At[m][k], acc[ai][bj][m][n], 0, 0, 0); __builtin_amdgcn_s_setprio(0); } while (0)
; #define PG8_WAIT_V(n) asm volatile("s_waitcnt vmcnt(" #n ")" ::: "memory")
; #define PG8_BAR __builtin_amdgcn_s_barrier()
; template <class Epi>
; __device__ __forceinline__ void gemm_phase(LAS unsigned char* lds, const Gemm g, const Epi& E) {
;     ...
;             PG8_STAGE(PG8_SB(1, 1), b3 + hstepB, voffB);
;             PG8_WAIT_V(6); PG8_BAR; PG8_MMA(1, 1, At, B1); PG8_BAR;
;     __device__ __forceinline__ void operator()(const AccT& acc, const Unit& u, int wr, int wc, int fr, int fq) const {
;     ...
;         const int gpm = mapA.src(u.pm);
;         const int mb = gpm < 32 ? 32 : (gpm - 32) >> 3;
;         const int row0 = gpm * 256 + wr * 64 + fr, col0 = u.pn * 256 + wc * 32 + 4 * fq;
;         const float* gp = modl + ((size_t)mb * 6 + gi) * 1024;
;         f32x4 gv[2][2];
; #pragma unroll
;         for (int bj = 0; bj < 2; ++bj)
; #pragma unroll
;             for (int n = 0; n < 2; ++n) { gv[bj][n] = *(const f32x4*)(gp + col0 + bj * 128 + n * 16); if (scale) gv[bj][n] = gv[bj][n] * *(const f32x4*)(scale + col0 + bj * 128 + n * 16); }
;         const float* sbase = (gpm < 32 ? Xc : Xl) + (size_t)row0 * 1024 + col0;
; #pragma unroll
;         for (int ai = 0; ai < 2; ++ai) {
;             f32x4 xo[4][2][2];
; #pragma unroll
;             for (int m = 0; m < 4; ++m)
; #pragma unroll
;                 for (int bj = 0; bj < 2; ++bj)
; #pragma unroll
;                     for (int n = 0; n < 2; ++n) xo[m][bj][n] = *(const f32x4*)(sbase + (size_t)(ai * 128 + m * 16) * 1024 + bj * 128 + n * 16);
	v_mfma_f32_16x16x32_bf16 v[62:65], v[130:133], v[154:157], v[62:65]
	v_mfma_f32_16x16x32_bf16 v[58:61], v[138:141], v[154:157], v[58:61]
	v_mfma_f32_16x16x32_bf16 v[54:57], v[130:133], v[166:169], v[54:57]
	v_mfma_f32_16x16x32_bf16 v[42:45], v[138:141], v[166:169], v[42:45]
	v_mfma_f32_16x16x32_bf16 v[38:41], v[130:133], v[174:177], v[38:41]
	v_mfma_f32_16x16x32_bf16 v[26:29], v[138:141], v[174:177], v[26:29]
	v_mfma_f32_16x16x32_bf16 v[22:25], v[130:133], v[184:187], v[22:25]
	v_mfma_f32_16x16x32_bf16 v[10:13], v[138:141], v[184:187], v[10:13]
	v_mfma_f32_16x16x32_bf16 v[62:65], v[134:137], v[162:165], v[62:65]
	v_mfma_f32_16x16x32_bf16 v[58:61], v[142:145], v[162:165], v[58:61]
	v_mfma_f32_16x16x32_bf16 v[54:57], v[134:137], v[170:173], v[54:57]
	v_mfma_f32_16x16x32_bf16 v[42:45], v[142:145], v[170:173], v[42:45]
	v_mfma_f32_16x16x32_bf16 v[38:41], v[134:137], v[180:183], v[38:41]
	v_mfma_f32_16x16x32_bf16 v[26:29], v[142:145], v[180:183], v[26:29]
	v_mfma_f32_16x16x32_bf16 v[22:25], v[134:137], v[188:191], v[22:25]
	v_mfma_f32_16x16x32_bf16 v[10:13], v[142:145], v[188:191], v[10:13]
	s_barrier
	s_add_u32 s14, s14, 0x80080
	s_addc_u32 s15, s15, 0
	s_add_i32 s16, s16, s25
	v_lshl_add_u64 v[130:131], s[14:15], 0, v[148:149]
	s_mov_b32 m0, s16
	s_nop 0
	global_load_lds_dwordx4 v[130:131], off
	v_lshl_add_u64 v[130:131], s[14:15], 0, v[146:147]
	s_add_i32 m0, s16, 0x2000
	s_nop 0
	global_load_lds_dwordx4 v[130:131], off
	s_add_i32 s65, s65, 2
	s_add_u32 s12, s12, 0x100
	s_addc_u32 s13, s13, 0
	s_add_u32 s7, s7, 0x100
	s_addc_u32 s64, s64, 0
	s_cmp_gt_u32 s65, 29
	s_waitcnt vmcnt(6)
	s_barrier
	v_mfma_f32_16x16x32_bf16 v[50:53], v[192:195], v[154:157], v[50:53]
	v_mfma_f32_16x16x32_bf16 v[46:49], v[200:203], v[154:157], v[46:49]
	v_mfma_f32_16x16x32_bf16 v[34:37], v[192:195], v[166:169], v[34:37]
	v_mfma_f32_16x16x32_bf16 v[30:33], v[200:203], v[166:169], v[30:33]
	v_mfma_f32_16x16x32_bf16 v[18:21], v[192:195], v[174:177], v[18:21]
	v_mfma_f32_16x16x32_bf16 v[14:17], v[200:203], v[174:177], v[14:17]
	v_mfma_f32_16x16x32_bf16 v[6:9], v[192:195], v[184:187], v[6:9]
	v_mfma_f32_16x16x32_bf16 v[2:5], v[200:203], v[184:187], v[2:5]
	v_mfma_f32_16x16x32_bf16 v[50:53], v[196:199], v[162:165], v[50:53]
	v_mfma_f32_16x16x32_bf16 v[46:49], v[204:207], v[162:165], v[46:49]
	v_mfma_f32_16x16x32_bf16 v[34:37], v[196:199], v[170:173], v[34:37]
	v_mfma_f32_16x16x32_bf16 v[30:33], v[204:207], v[170:173], v[30:33]
	v_mfma_f32_16x16x32_bf16 v[18:21], v[196:199], v[180:183], v[18:21]
	v_mfma_f32_16x16x32_bf16 v[14:17], v[204:207], v[180:183], v[14:17]
	v_mfma_f32_16x16x32_bf16 v[6:9], v[196:199], v[188:191], v[6:9]
	v_mfma_f32_16x16x32_bf16 v[2:5], v[204:207], v[188:191], v[2:5]
	s_barrier
	s_cbranch_scc0 .LBB0_495
	v_readlane_b32 s7, v255, 27
	s_cmp_ge_i32 s61, s7
	s_cselect_b32 s7, s29, 0
	s_add_i32 s7, s61, s7
	s_cmp_lt_i32 s7, 32
	v_mov_b32_e32 v156, v158
	v_mov_b32_e32 v130, v1
	s_cselect_b64 s[12:13], -1, 0
	s_sub_i32 s14, s7, 32
	s_lshl_b32 s10, s10, 8
	s_ashr_i32 s14, s14, 3
	s_or_b32 s10, s10, s52
	v_lshl_add_u32 v130, v130, 2, s10
	s_mul_i32 s10, s14, 6
	s_and_b64 s[14:15], s[12:13], exec
	s_cselect_b32 s14, 0xc0, s10
	s_ashr_i32 s15, s14, 31
	s_lshl_b64 s[14:15], s[14:15], 12
	s_add_u32 s14, s88, s14
	s_addc_u32 s15, s89, s15
	s_lshl_b32 s7, s7, 8
	s_add_i32 s7, s7, s50
	v_ashrrev_i32_e32 v131, 31, v130
	v_add_u32_e32 v156, s7, v156
	s_and_b64 s[12:13], s[12:13], exec
	v_readlane_b32 s7, v255, 16
	v_readlane_b32 s10, v255, 18
	v_lshlrev_b64 v[154:155], 2, v[130:131]
	s_cselect_b32 s13, s7, s10
	v_readlane_b32 s7, v255, 17
	v_readlane_b32 s10, v255, 19
	v_ashrrev_i32_e32 v157, 31, v156
	v_lshl_add_u64 v[130:131], s[14:15], 0, v[154:155]
	s_mov_b64 s[14:15], 0x2000
	s_cselect_b32 s12, s7, s10
	v_lshlrev_b64 v[208:209], 12, v[156:157]
	v_lshl_add_u64 v[132:133], v[130:131], 0, s[14:15]
	v_add_co_u32_e32 v130, vcc, s71, v130
	v_lshl_add_u64 v[156:157], s[12:13], 0, v[208:209]
	s_nop 0
	v_addc_co_u32_e32 v131, vcc, 0, v131, vcc
	v_lshl_add_u64 v[156:157], v[156:157], 0, v[154:155]
	v_add_co_u32_e32 v192, vcc, s45, v156
	global_load_dwordx4 v[138:141], v[132:133], off offset:64
	global_load_dwordx4 v[134:137], v[132:133], off offset:512
	global_load_dwordx4 v[142:145], v[130:131], off
	s_nop 0
	global_load_dwordx4 v[130:133], v[132:133], off offset:576
	v_addc_co_u32_e32 v193, vcc, 0, v157, vcc
	v_add_co_u32_e32 v226, vcc, s19, v156
	global_load_dwordx4 v[162:165], v[156:157], off
	global_load_dwordx4 v[166:169], v[156:157], off offset:64
	global_load_dwordx4 v[170:173], v[156:157], off offset:512
	global_load_dwordx4 v[174:177], v[156:157], off offset:576
	v_addc_co_u32_e32 v227, vcc, 0, v157, vcc
	v_add_co_u32_e32 v242, vcc, s69, v156
	global_load_dwordx4 v[180:183], v[192:193], off
	global_load_dwordx4 v[184:187], v[192:193], off offset:64
	global_load_dwordx4 v[188:191], v[192:193], off offset:512
	s_nop 0
	global_load_dwordx4 v[192:195], v[192:193], off offset:576
	v_addc_co_u32_e32 v243, vcc, 0, v157, vcc
	global_load_dwordx4 v[196:199], v[226:227], off
	global_load_dwordx4 v[200:203], v[226:227], off offset:64
	global_load_dwordx4 v[204:207], v[226:227], off offset:512
	s_nop 0
	global_load_dwordx4 v[226:229], v[226:227], off offset:576
	s_nop 0
	global_load_dwordx4 v[230:233], v[242:243], off
	global_load_dwordx4 v[234:237], v[242:243], off offset:64
	global_load_dwordx4 v[238:241], v[242:243], off offset:512
	s_nop 0
	global_load_dwordx4 v[242:245], v[242:243], off offset:576
	v_readlane_b32 s12, v254, 0
	v_readlane_b32 s13, v254, 1
	s_waitcnt vmcnt(0)
;     __device__ __forceinline__ void operator()(const AccT& acc, const Unit& u, int wr, int wc, int fr, int fq) const {
;     ...
;                     for (int n = 0; n < 2; ++n) xo[m][bj][n] = *(const f32x4*)(sbase + (size_t)(ai * 128 + m * 16) * 1024 + bj * 128 + n * 16);
;             __builtin_amdgcn_sched_barrier(0);
; #pragma unroll
;             for (int m = 0; m < 4; ++m) { float* rowp = X + (size_t)(row0 + ai * 128 + m * 16) * 1024 + col0;
; #pragma unroll
;                 for (int bj = 0; bj < 2; ++bj)
; #pragma unroll
;                     for (int n = 0; n < 2; ++n) *(f32x4*)(rowp + bj * 128 + n * 16) = xo[m][bj][n] + gv[bj][n] * acc[ai][bj][m][n]; }
	v_pk_fma_f32 v[112:113], v[112:113], v[132:133], v[176:177]
	v_pk_fma_f32 v[110:111], v[110:111], v[130:131], v[174:175]
	v_lshl_add_u64 v[208:209], s[12:13], 0, v[208:209]
	v_lshl_add_u64 v[154:155], v[208:209], 0, v[154:155]
	v_pk_fma_f32 v[120:121], v[120:121], v[136:137], v[172:173]
	v_pk_fma_f32 v[118:119], v[118:119], v[134:135], v[170:171]
	global_store_dwordx4 v[154:155], v[110:113], off offset:576
	global_store_dwordx4 v[154:155], v[118:121], off offset:512
	v_pk_fma_f32 v[100:101], v[100:101], v[136:137], v[190:191]
	v_pk_fma_f32 v[110:111], v[114:115], v[142:143], v[180:181]
	v_add_co_u32_e32 v114, vcc, s45, v154
	v_lshl_add_u64 v[118:119], v[154:155], 0, s[84:85]
	s_nop 0
	v_addc_co_u32_e32 v115, vcc, 0, v155, vcc
	v_pk_fma_f32 v[98:99], v[98:99], v[134:135], v[188:189]
	global_store_dwordx4 v[118:119], v[98:101], off offset:512
	v_pk_fma_f32 v[84:85], v[84:85], v[136:137], v[206:207]
	v_pk_fma_f32 v[82:83], v[82:83], v[134:135], v[204:205]
	v_add_co_u32_e32 v100, vcc, s19, v154
	v_lshl_add_u64 v[98:99], v[154:155], 0, s[82:83]
	s_nop 0
	v_addc_co_u32_e32 v101, vcc, 0, v155, vcc
	v_pk_fma_f32 v[96:97], v[96:97], v[132:133], v[194:195]
	v_pk_fma_f32 v[94:95], v[94:95], v[130:131], v[192:193]
	global_store_dwordx4 v[98:99], v[82:85], off offset:512
	v_pk_fma_f32 v[80:81], v[80:81], v[132:133], v[228:229]
	v_pk_fma_f32 v[78:79], v[78:79], v[130:131], v[226:227]
	s_mov_b64 s[12:13], 0x30000
	v_add_co_u32_e32 v84, vcc, s69, v154
	v_pk_fma_f32 v[128:129], v[128:129], v[144:145], v[164:165]
	v_pk_fma_f32 v[126:127], v[126:127], v[142:143], v[162:163]
	v_pk_fma_f32 v[124:125], v[124:125], v[140:141], v[168:169]
	v_pk_fma_f32 v[122:123], v[122:123], v[138:139], v[166:167]
	v_pk_fma_f32 v[112:113], v[116:117], v[144:145], v[182:183]
	v_pk_fma_f32 v[108:109], v[108:109], v[140:141], v[186:187]
	v_pk_fma_f32 v[106:107], v[106:107], v[138:139], v[184:185]
	global_store_dwordx4 v[118:119], v[94:97], off offset:576
	v_pk_fma_f32 v[92:93], v[92:93], v[140:141], v[202:203]
	v_pk_fma_f32 v[90:91], v[90:91], v[138:139], v[200:201]
	v_pk_fma_f32 v[96:97], v[104:105], v[144:145], v[198:199]
	v_pk_fma_f32 v[94:95], v[102:103], v[142:143], v[196:197]
	global_store_dwordx4 v[98:99], v[78:81], off offset:576
	v_lshl_add_u64 v[82:83], v[154:155], 0, s[12:13]
	v_addc_co_u32_e32 v85, vcc, 0, v155, vcc
	v_pk_fma_f32 v[80:81], v[88:89], v[144:145], v[232:233]
	v_pk_fma_f32 v[78:79], v[86:87], v[142:143], v[230:231]
	v_pk_fma_f32 v[76:77], v[76:77], v[140:141], v[236:237]
	v_pk_fma_f32 v[74:75], v[74:75], v[138:139], v[234:235]
	v_pk_fma_f32 v[72:73], v[72:73], v[136:137], v[240:241]
	v_pk_fma_f32 v[70:71], v[70:71], v[134:135], v[238:239]
	v_pk_fma_f32 v[68:69], v[68:69], v[132:133], v[244:245]
	v_pk_fma_f32 v[66:67], v[66:67], v[130:131], v[242:243]
	global_store_dwordx4 v[154:155], v[126:129], off
	global_store_dwordx4 v[154:155], v[122:125], off offset:64
	global_store_dwordx4 v[114:115], v[110:113], off
	global_store_dwordx4 v[118:119], v[106:109], off offset:64
	global_store_dwordx4 v[100:101], v[94:97], off
	global_store_dwordx4 v[98:99], v[90:93], off offset:64
	global_store_dwordx4 v[84:85], v[78:81], off
	global_store_dwordx4 v[82:83], v[74:77], off offset:64
	global_store_dwordx4 v[82:83], v[70:73], off offset:512
	global_store_dwordx4 v[82:83], v[66:69], off offset:576
	s_mov_b32 s7, 0x80000
	v_add_co_u32_e32 v78, vcc, s7, v156
	s_mov_b32 s10, 0x90000
	s_nop 0
	v_addc_co_u32_e32 v79, vcc, 0, v157, vcc
	v_add_co_u32_e32 v94, vcc, s10, v156
	s_mov_b32 s12, 0xa0000
	s_nop 0
	v_addc_co_u32_e32 v95, vcc, 0, v157, vcc
	v_add_co_u32_e32 v110, vcc, s12, v156
	s_mov_b32 s13, 0xb0000
	s_nop 0
	v_addc_co_u32_e32 v111, vcc, 0, v157, vcc
	v_add_co_u32_e32 v126, vcc, s13, v156
	global_load_dwordx4 v[66:69], v[78:79], off
	global_load_dwordx4 v[70:73], v[78:79], off offset:64
	global_load_dwordx4 v[74:77], v[78:79], off offset:512
	s_nop 0
	global_load_dwordx4 v[78:81], v[78:79], off offset:576
	v_addc_co_u32_e32 v127, vcc, 0, v157, vcc
	global_load_dwordx4 v[82:85], v[94:95], off
	global_load_dwordx4 v[86:89], v[94:95], off offset:64
	global_load_dwordx4 v[90:93], v[94:95], off offset:512
	s_nop 0
	global_load_dwordx4 v[94:97], v[94:95], off offset:576
	s_nop 0
	global_load_dwordx4 v[98:101], v[110:111], off
	global_load_dwordx4 v[102:105], v[110:111], off offset:64
	global_load_dwordx4 v[106:109], v[110:111], off offset:512
	s_nop 0
	global_load_dwordx4 v[110:113], v[110:111], off offset:576
	s_nop 0
	global_load_dwordx4 v[114:117], v[126:127], off
	global_load_dwordx4 v[118:121], v[126:127], off offset:64
	global_load_dwordx4 v[122:125], v[126:127], off offset:512
	s_nop 0
	global_load_dwordx4 v[126:129], v[126:127], off offset:576
	s_mov_b64 s[14:15], 0x80000
	s_waitcnt vmcnt(0)
; #define PG8_WAIT_V(n) asm volatile("s_waitcnt vmcnt(" #n ")" ::: "memory")
; #define PG8_BAR __builtin_amdgcn_s_barrier()
; template <class Epi>
; __device__ __forceinline__ void gemm_phase(LAS unsigned char* lds, const Gemm g, const Epi& E) {
;     ...
;         E(acc, cur, wr, wc, fr, fq);
;         if (!has_next) break;
; #pragma unroll
;         for (int a = 0; a < 2; ++a)
; #pragma unroll
;             for (int b = 0; b < 2; ++b)
; #pragma unroll
;                 for (int m = 0; m < 4; ++m)
; #pragma unroll
;                     for (int n = 0; n < 2; ++n) acc[a][b][m][n] = (f32x4){0.f, 0.f, 0.f, 0.f};
;         cur = nxt; cA = nA; cB = nB; ++ui;
;     }
;     PG8_WAIT_V(0);
;     if (wr == 0) PG8_BAR;
;     PG8_BAR;
;     __device__ __forceinline__ void operator()(const AccT& acc, const Unit& u, int wr, int wc, int fr, int fq) const {
;     ...
;                     for (int n = 0; n < 2; ++n) xo[m][bj][n] = *(const f32x4*)(sbase + (size_t)(ai * 128 + m * 16) * 1024 + bj * 128 + n * 16);
;             __builtin_amdgcn_sched_barrier(0);
; #pragma unroll
;             for (int m = 0; m < 4; ++m) { float* rowp = X + (size_t)(row0 + ai * 128 + m * 16) * 1024 + col0;
; #pragma unroll
;                 for (int bj = 0; bj < 2; ++bj)
; #pragma unroll
;                     for (int n = 0; n < 2; ++n) *(f32x4*)(rowp + bj * 128 + n * 16) = xo[m][bj][n] + gv[bj][n] * acc[ai][bj][m][n]; }
	v_pk_fma_f32 v[62:63], v[62:63], v[142:143], v[66:67]
	v_add_co_u32_e32 v66, vcc, s7, v154
	v_lshl_add_u64 v[156:157], v[154:155], 0, s[14:15]
	s_nop 0
	v_addc_co_u32_e32 v67, vcc, 0, v155, vcc
	v_pk_fma_f32 v[52:53], v[52:53], v[136:137], v[76:77]
	v_pk_fma_f32 v[50:51], v[50:51], v[134:135], v[74:75]
	global_store_dwordx4 v[156:157], v[50:53], off offset:512
	s_mov_b64 s[14:15], 0x90000
	v_pk_fma_f32 v[36:37], v[36:37], v[136:137], v[92:93]
	v_add_co_u32_e32 v52, vcc, s10, v154
	v_lshl_add_u64 v[50:51], v[154:155], 0, s[14:15]
	s_nop 0
	v_addc_co_u32_e32 v53, vcc, 0, v155, vcc
	v_pk_fma_f32 v[34:35], v[34:35], v[134:135], v[90:91]
	global_store_dwordx4 v[50:51], v[34:37], off offset:512
	s_mov_b64 s[14:15], 0xa0000
	v_pk_fma_f32 v[20:21], v[20:21], v[136:137], v[108:109]
	v_add_co_u32_e32 v36, vcc, s12, v154
	v_lshl_add_u64 v[34:35], v[154:155], 0, s[14:15]
	s_nop 0
	v_addc_co_u32_e32 v37, vcc, 0, v155, vcc
	v_pk_fma_f32 v[18:19], v[18:19], v[134:135], v[106:107]
	v_pk_fma_f32 v[48:49], v[48:49], v[132:133], v[80:81]
	v_pk_fma_f32 v[46:47], v[46:47], v[130:131], v[78:79]
	v_pk_fma_f32 v[32:33], v[32:33], v[132:133], v[96:97]
	v_pk_fma_f32 v[30:31], v[30:31], v[130:131], v[94:95]
	global_store_dwordx4 v[34:35], v[18:21], off offset:512
	v_pk_fma_f32 v[16:17], v[16:17], v[132:133], v[112:113]
	v_pk_fma_f32 v[14:15], v[14:15], v[130:131], v[110:111]
	s_mov_b64 s[14:15], 0xb0000
	v_add_co_u32_e32 v20, vcc, s13, v154
	v_pk_fma_f32 v[64:65], v[64:65], v[144:145], v[68:69]
	v_pk_fma_f32 v[60:61], v[60:61], v[140:141], v[72:73]
	v_pk_fma_f32 v[58:59], v[58:59], v[138:139], v[70:71]
	global_store_dwordx4 v[156:157], v[46:49], off offset:576
	v_pk_fma_f32 v[44:45], v[44:45], v[140:141], v[88:89]
	v_pk_fma_f32 v[42:43], v[42:43], v[138:139], v[86:87]
	v_pk_fma_f32 v[48:49], v[56:57], v[144:145], v[84:85]
	v_pk_fma_f32 v[46:47], v[54:55], v[142:143], v[82:83]
	global_store_dwordx4 v[50:51], v[30:33], off offset:576
	v_pk_fma_f32 v[28:29], v[28:29], v[140:141], v[104:105]
	v_pk_fma_f32 v[26:27], v[26:27], v[138:139], v[102:103]
	v_pk_fma_f32 v[32:33], v[40:41], v[144:145], v[100:101]
	v_pk_fma_f32 v[30:31], v[38:39], v[142:143], v[98:99]
	global_store_dwordx4 v[34:35], v[14:17], off offset:576
	v_lshl_add_u64 v[18:19], v[154:155], 0, s[14:15]
	v_addc_co_u32_e32 v21, vcc, 0, v155, vcc
	v_pk_fma_f32 v[16:17], v[24:25], v[144:145], v[116:117]
	v_pk_fma_f32 v[14:15], v[22:23], v[142:143], v[114:115]
	v_pk_fma_f32 v[12:13], v[12:13], v[140:141], v[120:121]
	v_pk_fma_f32 v[10:11], v[10:11], v[138:139], v[118:119]
	v_pk_fma_f32 v[8:9], v[8:9], v[136:137], v[124:125]
	v_pk_fma_f32 v[6:7], v[6:7], v[134:135], v[122:123]
	v_pk_fma_f32 v[4:5], v[4:5], v[132:133], v[128:129]
	v_pk_fma_f32 v[2:3], v[2:3], v[130:131], v[126:127]
	global_store_dwordx4 v[66:67], v[62:65], off
	global_store_dwordx4 v[156:157], v[58:61], off offset:64
	global_store_dwordx4 v[52:53], v[46:49], off
	global_store_dwordx4 v[50:51], v[42:45], off offset:64
	global_store_dwordx4 v[36:37], v[30:33], off
	global_store_dwordx4 v[34:35], v[26:29], off offset:64
	global_store_dwordx4 v[20:21], v[14:17], off
	global_store_dwordx4 v[18:19], v[10:13], off offset:64
	global_store_dwordx4 v[18:19], v[6:9], off offset:512
	global_store_dwordx4 v[18:19], v[2:5], off offset:576
	s_and_b64 vcc, exec, s[2:3]
	s_mov_b32 s10, s6
	s_mov_b32 s61, s60
	s_mov_b64 s[14:15], s[4:5]
	s_mov_b64 s[12:13], s[8:9]
	s_cbranch_vccz .LBB0_490
	s_waitcnt vmcnt(0)
	s_cmpk_gt_u32 s1, 0xff
	s_cbranch_scc1 .LBB0_499
	s_barrier

; #define PG8_STAGE(bufoff, gbase, voff) do { _Pragma("unroll") for (int _i = 0; _i < 2; ++_i) \
;         __builtin_amdgcn_global_load_lds((const unsigned*)((const char*)(gbase) + (voff)[_i]), (LAS unsigned*)(lds + (bufoff) + ldsw + _i * 8192), 16, 0, 0); } while (0)
; #define PG8_LDA(dst, b, h) do { _Pragma("unroll") for (int m = 0; m < 4; ++m) _Pragma("unroll") for (int k = 0; k < 2; ++k) dst[m][k] = *(const LAS bf16x8*)(lds + PG8_SA(b, h) + aoff + m * 2048 + k * 1024); } while (0)
; #define PG8_LDB(dst, b, h) do { _Pragma("unroll") for (int n = 0; n < 2; ++n) _Pragma("unroll") for (int k = 0; k < 2; ++k) dst[n][k] = *(const LAS bf16x8*)(lds + PG8_SB(b, h) + boff + n * 2048 + k * 1024); } while (0)
; #define PG8_MMA(ai, bj, At, Bt) do { __builtin_amdgcn_s_setprio(1); _Pragma("unroll") for (int m = 0; m < 4; ++m) _Pragma("unroll") for (int n = 0; n < 2; ++n) _Pragma("unroll") for (int k = 0; k < 2; ++k) \
;         acc[ai][bj][m][n] = __builtin_amdgcn_mfma_f32_16x16x32_bf16(Bt[n][k], At[m][k], acc[ai][bj][m][n], 0, 0, 0); __builtin_amdgcn_s_setprio(0); } while (0)
; #define PG8_WAIT_L(n) asm volatile("s_waitcnt lgkmcnt(" #n ")" ::: "memory")
; #define PG8_BAR __builtin_amdgcn_s_barrier()
; #define PG8_SCHED __builtin_amdgcn_sched_barrier(0)
; template <class Epi>
; __device__ __forceinline__ void gemm_phase(LAS unsigned char* lds, const Gemm g, const Epi& E) {
;     ...
;             PG8_LDB(B0, 0, 0); PG8_SCHED; PG8_LDA(At, 0, 0); PG8_STAGE(PG8_SA(1, 1), a1 + hstepA, voffA);
;             PG8_WAIT_L(8); PG8_BAR; PG8_WAIT_L(0); PG8_MMA(0, 0, At, B0); PG8_BAR; PG8_SCHED;
;             PG8_LDB(B1, 0, 1); PG8_STAGE(PG8_SB(0, 0), b2, voffB);
;             PG8_BAR; PG8_WAIT_L(0); PG8_MMA(0, 1, At, B1); PG8_BAR;
;             PG8_LDA(At, 0, 1); PG8_STAGE(PG8_SA(0, 0), a2, voffA);
;             PG8_BAR; PG8_WAIT_L(0); PG8_MMA(1, 0, At, B0); PG8_BAR; PG8_SCHED;
.LBB0_525:
	s_add_u32 s14, s12, 0xfffc0080
	s_addc_u32 s15, s13, -1
	s_add_i32 s26, 0, 0x10000
	v_add_u32_e32 v149, s26, v147
	ds_read_b128 v[142:145], v149
	ds_read_b128 v[150:153], v149 offset:1024
	ds_read_b128 v[154:157], v149 offset:2048
	ds_read_b128 v[158:161], v149 offset:3072
	s_cmp_eq_u32 s66, 12
	s_cselect_b32 s17, s9, s15
	s_cselect_b32 s16, s8, s14
	s_cselect_b32 s15, s5, s65
	s_cselect_b32 s14, s4, s7
	v_lshl_add_u64 v[196:197], s[12:13], 0, v[138:139]
	s_add_i32 m0, s11, 0xc000
	ds_read_b128 v[162:165], v148
	ds_read_b128 v[166:169], v148 offset:1024
	ds_read_b128 v[170:173], v148 offset:2048
	ds_read_b128 v[174:177], v148 offset:3072
	ds_read_b128 v[180:183], v148 offset:4096
	ds_read_b128 v[184:187], v148 offset:5120
	ds_read_b128 v[188:191], v148 offset:6144
	ds_read_b128 v[192:195], v148 offset:7168
	global_load_lds_dwordx4 v[196:197], off
	v_lshl_add_u64 v[196:197], s[12:13], 0, v[140:141]
	s_add_i32 m0, s11, 0xe000
	s_nop 0
	global_load_lds_dwordx4 v[196:197], off
	s_waitcnt lgkmcnt(0)
	s_barrier
	v_mfma_f32_16x16x32_bf16 v[126:129], v[142:145], v[162:165], v[126:129]
	v_mfma_f32_16x16x32_bf16 v[118:121], v[154:157], v[162:165], v[118:121]
	v_mfma_f32_16x16x32_bf16 v[110:113], v[142:145], v[170:173], v[110:113]
	v_mfma_f32_16x16x32_bf16 v[102:105], v[154:157], v[170:173], v[102:105]
	v_mfma_f32_16x16x32_bf16 v[94:97], v[142:145], v[180:183], v[94:97]
	v_mfma_f32_16x16x32_bf16 v[86:89], v[154:157], v[180:183], v[86:89]
	v_mfma_f32_16x16x32_bf16 v[78:81], v[142:145], v[188:191], v[78:81]
	v_mfma_f32_16x16x32_bf16 v[70:73], v[154:157], v[188:191], v[70:73]
	v_mfma_f32_16x16x32_bf16 v[126:129], v[150:153], v[166:169], v[126:129]
	v_mfma_f32_16x16x32_bf16 v[118:121], v[158:161], v[166:169], v[118:121]
	v_mfma_f32_16x16x32_bf16 v[110:113], v[150:153], v[174:177], v[110:113]
	v_mfma_f32_16x16x32_bf16 v[102:105], v[158:161], v[174:177], v[102:105]
	v_mfma_f32_16x16x32_bf16 v[94:97], v[150:153], v[184:187], v[94:97]
	v_mfma_f32_16x16x32_bf16 v[86:89], v[158:161], v[184:187], v[86:89]
	v_mfma_f32_16x16x32_bf16 v[78:81], v[150:153], v[192:195], v[78:81]
	v_mfma_f32_16x16x32_bf16 v[70:73], v[158:161], v[192:195], v[70:73]
	s_barrier
	s_add_i32 s27, 0, 0x14000
	s_add_i32 s26, s26, s25
	v_add_u32_e32 v149, s27, v147
	v_lshl_add_u64 v[208:209], s[14:15], 0, v[134:135]
	s_mov_b32 m0, s26
	ds_read_b128 v[196:199], v149
	ds_read_b128 v[200:203], v149 offset:1024
	ds_read_b128 v[204:207], v149 offset:2048
	ds_read_b128 v[226:229], v149 offset:3072
	global_load_lds_dwordx4 v[208:209], off
	v_lshl_add_u64 v[230:231], s[14:15], 0, v[130:131]
	s_add_i32 m0, s26, 0x2000
	s_nop 0
	global_load_lds_dwordx4 v[230:231], off
	s_nop 1
	s_mov_b32 m0, s11
	v_lshl_add_u64 v[232:233], s[16:17], 0, v[136:137]
	s_waitcnt lgkmcnt(0)
	s_barrier
	v_mfma_f32_16x16x32_bf16 v[122:125], v[196:199], v[162:165], v[122:125]
	v_mfma_f32_16x16x32_bf16 v[114:117], v[204:207], v[162:165], v[114:117]
	v_mfma_f32_16x16x32_bf16 v[106:109], v[196:199], v[170:173], v[106:109]
	v_mfma_f32_16x16x32_bf16 v[98:101], v[204:207], v[170:173], v[98:101]
	v_mfma_f32_16x16x32_bf16 v[90:93], v[196:199], v[180:183], v[90:93]
	v_mfma_f32_16x16x32_bf16 v[82:85], v[204:207], v[180:183], v[82:85]
	v_mfma_f32_16x16x32_bf16 v[74:77], v[196:199], v[188:191], v[74:77]
	v_mfma_f32_16x16x32_bf16 v[66:69], v[204:207], v[188:191], v[66:69]
	v_mfma_f32_16x16x32_bf16 v[122:125], v[200:203], v[166:169], v[122:125]
	v_mfma_f32_16x16x32_bf16 v[114:117], v[226:229], v[166:169], v[114:117]
	v_mfma_f32_16x16x32_bf16 v[106:109], v[200:203], v[174:177], v[106:109]
	v_mfma_f32_16x16x32_bf16 v[98:101], v[226:229], v[174:177], v[98:101]
	v_mfma_f32_16x16x32_bf16 v[90:93], v[200:203], v[184:187], v[90:93]
	v_mfma_f32_16x16x32_bf16 v[82:85], v[226:229], v[184:187], v[82:85]
	v_mfma_f32_16x16x32_bf16 v[74:77], v[200:203], v[192:195], v[74:77]
	v_mfma_f32_16x16x32_bf16 v[66:69], v[226:229], v[192:195], v[66:69]
	s_barrier
	ds_read_b128 v[162:165], v148 offset:16384
	ds_read_b128 v[166:169], v148 offset:17408
	ds_read_b128 v[170:173], v148 offset:18432
	ds_read_b128 v[174:177], v148 offset:19456
	ds_read_b128 v[180:183], v148 offset:20480
	ds_read_b128 v[184:187], v148 offset:21504
	ds_read_b128 v[188:191], v148 offset:22528
	ds_read_b128 v[192:195], v148 offset:23552
	global_load_lds_dwordx4 v[232:233], off
	v_lshl_add_u64 v[234:235], s[16:17], 0, v[132:133]
	s_mov_b32 m0, s36
	s_nop 0
	global_load_lds_dwordx4 v[234:235], off
	s_waitcnt lgkmcnt(0)
	s_barrier
	v_mfma_f32_16x16x32_bf16 v[62:65], v[142:145], v[162:165], v[62:65]
	v_mfma_f32_16x16x32_bf16 v[54:57], v[154:157], v[162:165], v[54:57]
	v_mfma_f32_16x16x32_bf16 v[46:49], v[142:145], v[170:173], v[46:49]
	v_mfma_f32_16x16x32_bf16 v[38:41], v[154:157], v[170:173], v[38:41]
	v_mfma_f32_16x16x32_bf16 v[30:33], v[142:145], v[180:183], v[30:33]
	v_mfma_f32_16x16x32_bf16 v[22:25], v[154:157], v[180:183], v[22:25]
	v_mfma_f32_16x16x32_bf16 v[14:17], v[142:145], v[188:191], v[14:17]
	v_mfma_f32_16x16x32_bf16 v[6:9], v[154:157], v[188:191], v[6:9]
	v_mfma_f32_16x16x32_bf16 v[62:65], v[150:153], v[166:169], v[62:65]
	v_mfma_f32_16x16x32_bf16 v[54:57], v[158:161], v[166:169], v[54:57]
	v_mfma_f32_16x16x32_bf16 v[46:49], v[150:153], v[174:177], v[46:49]
	v_mfma_f32_16x16x32_bf16 v[38:41], v[158:161], v[174:177], v[38:41]
	v_mfma_f32_16x16x32_bf16 v[30:33], v[150:153], v[184:187], v[30:33]
	v_mfma_f32_16x16x32_bf16 v[22:25], v[158:161], v[184:187], v[22:25]
	v_mfma_f32_16x16x32_bf16 v[14:17], v[150:153], v[192:195], v[14:17]
	v_mfma_f32_16x16x32_bf16 v[6:9], v[158:161], v[192:195], v[6:9]
	s_barrier
; #define PG8_STAGE(bufoff, gbase, voff) do { _Pragma("unroll") for (int _i = 0; _i < 2; ++_i) \
;         __builtin_amdgcn_global_load_lds((const unsigned*)((const char*)(gbase) + (voff)[_i]), (LAS unsigned*)(lds + (bufoff) + ldsw + _i * 8192), 16, 0, 0); } while (0)
; #define PG8_LDA(dst, b, h) do { _Pragma("unroll") for (int m = 0; m < 4; ++m) _Pragma("unroll") for (int k = 0; k < 2; ++k) dst[m][k] = *(const LAS bf16x8*)(lds + PG8_SA(b, h) + aoff + m * 2048 + k * 1024); } while (0)
; #define PG8_LDB(dst, b, h) do { _Pragma("unroll") for (int n = 0; n < 2; ++n) _Pragma("unroll") for (int k = 0; k < 2; ++k) dst[n][k] = *(const LAS bf16x8*)(lds + PG8_SB(b, h) + boff + n * 2048 + k * 1024); } while (0)
; #define PG8_MMA(ai, bj, At, Bt) do { __builtin_amdgcn_s_setprio(1); _Pragma("unroll") for (int m = 0; m < 4; ++m) _Pragma("unroll") for (int n = 0; n < 2; ++n) _Pragma("unroll") for (int k = 0; k < 2; ++k) \
;         acc[ai][bj][m][n] = __builtin_amdgcn_mfma_f32_16x16x32_bf16(Bt[n][k], At[m][k], acc[ai][bj][m][n], 0, 0, 0); __builtin_amdgcn_s_setprio(0); } while (0)
; #define PG8_WAIT_V(n) asm volatile("s_waitcnt vmcnt(" #n ")" ::: "memory")
; #define PG8_WAIT_L(n) asm volatile("s_waitcnt lgkmcnt(" #n ")" ::: "memory")
; #define PG8_BAR __builtin_amdgcn_s_barrier()
; #define PG8_SCHED __builtin_amdgcn_sched_barrier(0)
; template <class Epi>
; __device__ __forceinline__ void gemm_phase(LAS unsigned char* lds, const Gemm g, const Epi& E) {
;     ...
;             PG8_STAGE(PG8_SB(0, 1), b2 + hstepB, voffB);
;             PG8_WAIT_V(6); PG8_BAR; PG8_MMA(1, 1, At, B1); PG8_BAR;
;             PG8_LDB(B0, 1, 0); PG8_SCHED; PG8_LDA(At, 1, 0); PG8_STAGE(PG8_SA(0, 1), a2 + hstepA, voffA);
;             PG8_WAIT_L(8); PG8_BAR; PG8_WAIT_L(0); PG8_MMA(0, 0, At, B0); PG8_BAR; PG8_SCHED;
;             PG8_LDB(B1, 1, 1); PG8_STAGE(PG8_SB(1, 0), b3, voffB);
;             PG8_BAR; PG8_WAIT_L(0); PG8_MMA(0, 1, At, B1); PG8_BAR;
;             PG8_LDA(At, 1, 1); PG8_STAGE(PG8_SA(1, 0), a3, voffA);
;             PG8_BAR; PG8_WAIT_L(0); PG8_MMA(1, 0, At, B0); PG8_BAR; PG8_SCHED;
	s_add_u32 s68, s14, 0x40000
	s_addc_u32 s69, s15, 0
	s_add_i32 s26, s27, s25
	v_lshl_add_u64 v[142:143], s[68:69], 0, v[134:135]
	s_mov_b32 m0, s26
	s_nop 0
	global_load_lds_dwordx4 v[142:143], off
	v_lshl_add_u64 v[142:143], s[68:69], 0, v[130:131]
	s_add_i32 m0, s26, 0x2000
	s_nop 0
	global_load_lds_dwordx4 v[142:143], off
	s_add_i32 s26, 0, 0x18000
	v_add_u32_e32 v149, s26, v147
	s_waitcnt vmcnt(6)
	s_barrier
	v_mfma_f32_16x16x32_bf16 v[58:61], v[196:199], v[162:165], v[58:61]
	v_mfma_f32_16x16x32_bf16 v[50:53], v[204:207], v[162:165], v[50:53]
	v_mfma_f32_16x16x32_bf16 v[42:45], v[196:199], v[170:173], v[42:45]
	v_mfma_f32_16x16x32_bf16 v[34:37], v[204:207], v[170:173], v[34:37]
	v_mfma_f32_16x16x32_bf16 v[26:29], v[196:199], v[180:183], v[26:29]
	v_mfma_f32_16x16x32_bf16 v[18:21], v[204:207], v[180:183], v[18:21]
	v_mfma_f32_16x16x32_bf16 v[10:13], v[196:199], v[188:191], v[10:13]
	v_mfma_f32_16x16x32_bf16 v[2:5], v[204:207], v[188:191], v[2:5]
	v_mfma_f32_16x16x32_bf16 v[58:61], v[200:203], v[166:169], v[58:61]
	v_mfma_f32_16x16x32_bf16 v[50:53], v[226:229], v[166:169], v[50:53]
	v_mfma_f32_16x16x32_bf16 v[42:45], v[200:203], v[174:177], v[42:45]
	v_mfma_f32_16x16x32_bf16 v[34:37], v[226:229], v[174:177], v[34:37]
	v_mfma_f32_16x16x32_bf16 v[26:29], v[200:203], v[184:187], v[26:29]
	v_mfma_f32_16x16x32_bf16 v[18:21], v[226:229], v[184:187], v[18:21]
	v_mfma_f32_16x16x32_bf16 v[10:13], v[200:203], v[192:195], v[10:13]
	v_mfma_f32_16x16x32_bf16 v[2:5], v[226:229], v[192:195], v[2:5]
	s_barrier
	ds_read_b128 v[142:145], v149
	ds_read_b128 v[150:153], v149 offset:1024
	ds_read_b128 v[154:157], v149 offset:2048
	ds_read_b128 v[158:161], v149 offset:3072
	s_add_u32 s16, s16, 0x40000
	s_addc_u32 s17, s17, 0
	s_mov_b32 m0, s44
	v_lshl_add_u64 v[196:197], s[16:17], 0, v[136:137]
	ds_read_b128 v[162:165], v148 offset:32768
	ds_read_b128 v[166:169], v148 offset:33792
	ds_read_b128 v[170:173], v148 offset:34816
	ds_read_b128 v[174:177], v148 offset:35840
	ds_read_b128 v[180:183], v148 offset:36864
	ds_read_b128 v[184:187], v148 offset:37888
	ds_read_b128 v[188:191], v148 offset:38912
	ds_read_b128 v[192:195], v148 offset:39936
	global_load_lds_dwordx4 v[196:197], off
	v_lshl_add_u64 v[196:197], s[16:17], 0, v[132:133]
	s_mov_b32 m0, s50
	s_nop 0
	global_load_lds_dwordx4 v[196:197], off
	s_waitcnt lgkmcnt(0)
	s_barrier
	v_mfma_f32_16x16x32_bf16 v[126:129], v[142:145], v[162:165], v[126:129]
	v_mfma_f32_16x16x32_bf16 v[118:121], v[154:157], v[162:165], v[118:121]
	v_mfma_f32_16x16x32_bf16 v[110:113], v[142:145], v[170:173], v[110:113]
	v_mfma_f32_16x16x32_bf16 v[102:105], v[154:157], v[170:173], v[102:105]
	v_mfma_f32_16x16x32_bf16 v[94:97], v[142:145], v[180:183], v[94:97]
	v_mfma_f32_16x16x32_bf16 v[86:89], v[154:157], v[180:183], v[86:89]
	v_mfma_f32_16x16x32_bf16 v[78:81], v[142:145], v[188:191], v[78:81]
	v_mfma_f32_16x16x32_bf16 v[70:73], v[154:157], v[188:191], v[70:73]
	v_mfma_f32_16x16x32_bf16 v[126:129], v[150:153], v[166:169], v[126:129]
	v_mfma_f32_16x16x32_bf16 v[118:121], v[158:161], v[166:169], v[118:121]
	v_mfma_f32_16x16x32_bf16 v[110:113], v[150:153], v[174:177], v[110:113]
	v_mfma_f32_16x16x32_bf16 v[102:105], v[158:161], v[174:177], v[102:105]
	v_mfma_f32_16x16x32_bf16 v[94:97], v[150:153], v[184:187], v[94:97]
	v_mfma_f32_16x16x32_bf16 v[86:89], v[158:161], v[184:187], v[86:89]
	v_mfma_f32_16x16x32_bf16 v[78:81], v[150:153], v[192:195], v[78:81]
	v_mfma_f32_16x16x32_bf16 v[70:73], v[158:161], v[192:195], v[70:73]
	s_barrier
	s_add_i32 s16, 0, 0x1c000
	s_add_i32 s17, s26, s25
	v_add_u32_e32 v149, s16, v147
	v_lshl_add_u64 v[208:209], v[208:209], 0, s[86:87]
	s_mov_b32 m0, s17
	ds_read_b128 v[196:199], v149
	ds_read_b128 v[200:203], v149 offset:1024
	ds_read_b128 v[204:207], v149 offset:2048
	ds_read_b128 v[226:229], v149 offset:3072
	global_load_lds_dwordx4 v[208:209], off
	v_lshl_add_u64 v[208:209], v[230:231], 0, s[86:87]
	s_add_i32 m0, s17, 0x2000
	s_nop 0
	global_load_lds_dwordx4 v[208:209], off
	s_nop 1
	s_mov_b32 m0, s58
	v_lshl_add_u64 v[208:209], v[232:233], 0, s[86:87]
	s_waitcnt lgkmcnt(0)
	s_barrier
	v_mfma_f32_16x16x32_bf16 v[122:125], v[196:199], v[162:165], v[122:125]
	v_mfma_f32_16x16x32_bf16 v[114:117], v[204:207], v[162:165], v[114:117]
	v_mfma_f32_16x16x32_bf16 v[106:109], v[196:199], v[170:173], v[106:109]
	v_mfma_f32_16x16x32_bf16 v[98:101], v[204:207], v[170:173], v[98:101]
	v_mfma_f32_16x16x32_bf16 v[90:93], v[196:199], v[180:183], v[90:93]
	v_mfma_f32_16x16x32_bf16 v[82:85], v[204:207], v[180:183], v[82:85]
	v_mfma_f32_16x16x32_bf16 v[74:77], v[196:199], v[188:191], v[74:77]
	v_mfma_f32_16x16x32_bf16 v[66:69], v[204:207], v[188:191], v[66:69]
	v_mfma_f32_16x16x32_bf16 v[122:125], v[200:203], v[166:169], v[122:125]
	v_mfma_f32_16x16x32_bf16 v[114:117], v[226:229], v[166:169], v[114:117]
	v_mfma_f32_16x16x32_bf16 v[106:109], v[200:203], v[174:177], v[106:109]
	v_mfma_f32_16x16x32_bf16 v[98:101], v[226:229], v[174:177], v[98:101]
	v_mfma_f32_16x16x32_bf16 v[90:93], v[200:203], v[184:187], v[90:93]
	v_mfma_f32_16x16x32_bf16 v[82:85], v[226:229], v[184:187], v[82:85]
	v_mfma_f32_16x16x32_bf16 v[74:77], v[200:203], v[192:195], v[74:77]
	v_mfma_f32_16x16x32_bf16 v[66:69], v[226:229], v[192:195], v[66:69]
	s_barrier
	ds_read_b128 v[162:165], v148 offset:49152
	ds_read_b128 v[166:169], v148 offset:50176
	ds_read_b128 v[170:173], v148 offset:51200
	ds_read_b128 v[174:177], v148 offset:52224
	ds_read_b128 v[180:183], v148 offset:53248
	ds_read_b128 v[184:187], v148 offset:54272
	ds_read_b128 v[188:191], v148 offset:55296
	ds_read_b128 v[192:195], v148 offset:56320
	global_load_lds_dwordx4 v[208:209], off
	v_lshl_add_u64 v[208:209], v[234:235], 0, s[86:87]
	s_mov_b32 m0, s59
	s_nop 0
	global_load_lds_dwordx4 v[208:209], off
	s_waitcnt lgkmcnt(0)
	s_barrier
; __device__ __forceinline__ unsigned cvt_pk_bf16(float lo, float hi) { unsigned r; asm("v_cvt_pk_bf16_f32 %0, %1, %2" : "=v"(r) : "v"(lo), "v"(hi)); return r; }
; #define PG8_STAGE(bufoff, gbase, voff) do { _Pragma("unroll") for (int _i = 0; _i < 2; ++_i) \
;         __builtin_amdgcn_global_load_lds((const unsigned*)((const char*)(gbase) + (voff)[_i]), (LAS unsigned*)(lds + (bufoff) + ldsw + _i * 8192), 16, 0, 0); } while (0)
; #define PG8_MMA(ai, bj, At, Bt) do { __builtin_amdgcn_s_setprio(1); _Pragma("unroll") for (int m = 0; m < 4; ++m) _Pragma("unroll") for (int n = 0; n < 2; ++n) _Pragma("unroll") for (int k = 0; k < 2; ++k) \
;         acc[ai][bj][m][n] = __builtin_amdgcn_mfma_f32_16x16x32_bf16(Bt[n][k], At[m][k], acc[ai][bj][m][n], 0, 0, 0); __builtin_amdgcn_s_setprio(0); } while (0)
; #define PG8_WAIT_V(n) asm volatile("s_waitcnt vmcnt(" #n ")" ::: "memory")
; #define PG8_BAR __builtin_amdgcn_s_barrier()
; template <class Epi>
; __device__ __forceinline__ void gemm_phase(LAS unsigned char* lds, const Gemm g, const Epi& E) {
;     ...
;             PG8_STAGE(PG8_SB(1, 1), b3 + hstepB, voffB);
;             PG8_WAIT_V(6); PG8_BAR; PG8_MMA(1, 1, At, B1); PG8_BAR;
;         }
;     __device__ __forceinline__ void operator()(const AccT& acc, const Unit& u, int wr, int wc, int fr, int fq) const {
;         asm volatile("" : "+v"(fr), "+v"(fq));
;         const int gpm = mapA.src(u.pm);
;         const int row0 = gpm * 256 + wr * 64 + fr, col0 = u.pn * 128 + wc * 32 + 8 * fq;
; #pragma unroll
;         for (int ai = 0; ai < 2; ++ai)
; #pragma unroll
;             for (int m = 0; m < 4; ++m) { bf16_t* rowp = U + (size_t)(row0 + ai * 128 + m * 16) * HID + col0;
;                 const f32x4 s0 = silu4(acc[ai][0][m][0]) * acc[ai][1][m][0], s1 = silu4(acc[ai][0][m][1]) * acc[ai][1][m][1];
;                 u32x4 w; w.x = cvt_pk_bf16(s0[0], s0[1]); w.y = cvt_pk_bf16(s0[2], s0[3]); w.z = cvt_pk_bf16(s1[0], s1[1]); w.w = cvt_pk_bf16(s1[2], s1[3]);
;                 *(u32x4*)rowp = w; }
	v_mfma_f32_16x16x32_bf16 v[62:65], v[142:145], v[162:165], v[62:65]
	v_mfma_f32_16x16x32_bf16 v[54:57], v[154:157], v[162:165], v[54:57]
	v_mfma_f32_16x16x32_bf16 v[46:49], v[142:145], v[170:173], v[46:49]
	v_mfma_f32_16x16x32_bf16 v[38:41], v[154:157], v[170:173], v[38:41]
	v_mfma_f32_16x16x32_bf16 v[30:33], v[142:145], v[180:183], v[30:33]
	v_mfma_f32_16x16x32_bf16 v[22:25], v[154:157], v[180:183], v[22:25]
	v_mfma_f32_16x16x32_bf16 v[14:17], v[142:145], v[188:191], v[14:17]
	v_mfma_f32_16x16x32_bf16 v[6:9], v[154:157], v[188:191], v[6:9]
	v_mfma_f32_16x16x32_bf16 v[62:65], v[150:153], v[166:169], v[62:65]
	v_mfma_f32_16x16x32_bf16 v[54:57], v[158:161], v[166:169], v[54:57]
	v_mfma_f32_16x16x32_bf16 v[46:49], v[150:153], v[174:177], v[46:49]
	v_mfma_f32_16x16x32_bf16 v[38:41], v[158:161], v[174:177], v[38:41]
	v_mfma_f32_16x16x32_bf16 v[30:33], v[150:153], v[184:187], v[30:33]
	v_mfma_f32_16x16x32_bf16 v[22:25], v[158:161], v[184:187], v[22:25]
	v_mfma_f32_16x16x32_bf16 v[14:17], v[150:153], v[192:195], v[14:17]
	v_mfma_f32_16x16x32_bf16 v[6:9], v[158:161], v[192:195], v[6:9]
	s_barrier
	s_add_u32 s14, s14, 0x40080
	s_addc_u32 s15, s15, 0
	s_add_i32 s16, s16, s25
	v_lshl_add_u64 v[142:143], s[14:15], 0, v[134:135]
	s_mov_b32 m0, s16
	s_nop 0
	global_load_lds_dwordx4 v[142:143], off
	v_lshl_add_u64 v[142:143], s[14:15], 0, v[130:131]
	s_add_i32 m0, s16, 0x2000
	s_nop 0
	global_load_lds_dwordx4 v[142:143], off
	s_add_i32 s66, s66, 2
	s_add_u32 s12, s12, 0x100
	s_addc_u32 s13, s13, 0
	s_add_u32 s7, s7, 0x100
	s_addc_u32 s65, s65, 0
	s_cmp_gt_u32 s66, 13
	s_waitcnt vmcnt(6)
	s_barrier
	v_mfma_f32_16x16x32_bf16 v[58:61], v[196:199], v[162:165], v[58:61]
	v_mfma_f32_16x16x32_bf16 v[50:53], v[204:207], v[162:165], v[50:53]
	v_mfma_f32_16x16x32_bf16 v[42:45], v[196:199], v[170:173], v[42:45]
	v_mfma_f32_16x16x32_bf16 v[34:37], v[204:207], v[170:173], v[34:37]
	v_mfma_f32_16x16x32_bf16 v[26:29], v[196:199], v[180:183], v[26:29]
	v_mfma_f32_16x16x32_bf16 v[18:21], v[204:207], v[180:183], v[18:21]
	v_mfma_f32_16x16x32_bf16 v[10:13], v[196:199], v[188:191], v[10:13]
	v_mfma_f32_16x16x32_bf16 v[2:5], v[204:207], v[188:191], v[2:5]
	v_mfma_f32_16x16x32_bf16 v[58:61], v[200:203], v[166:169], v[58:61]
	v_mfma_f32_16x16x32_bf16 v[50:53], v[226:229], v[166:169], v[50:53]
	v_mfma_f32_16x16x32_bf16 v[42:45], v[200:203], v[174:177], v[42:45]
	v_mfma_f32_16x16x32_bf16 v[34:37], v[226:229], v[174:177], v[34:37]
	v_mfma_f32_16x16x32_bf16 v[26:29], v[200:203], v[184:187], v[26:29]
	v_mfma_f32_16x16x32_bf16 v[18:21], v[226:229], v[184:187], v[18:21]
	v_mfma_f32_16x16x32_bf16 v[10:13], v[200:203], v[192:195], v[10:13]
	v_mfma_f32_16x16x32_bf16 v[2:5], v[226:229], v[192:195], v[2:5]
	s_barrier
	s_cbranch_scc0 .LBB0_525
	v_mul_f32_e32 v152, 0xbfb8aa3b, v126
	v_mul_f32_e32 v153, 0xbfb8aa3b, v127
	v_mul_f32_e32 v154, 0xbfb8aa3b, v128
	v_mul_f32_e32 v155, 0xbfb8aa3b, v129
	v_exp_f32_e32 v152, v152
	v_exp_f32_e32 v153, v153
	v_exp_f32_e32 v154, v154
	v_exp_f32_e32 v155, v155
	v_add_f32_e32 v152, 1.0, v152
	v_add_f32_e32 v153, 1.0, v153
	v_add_f32_e32 v154, 1.0, v154
	v_add_f32_e32 v155, 1.0, v155
	v_rcp_f32_e32 v152, v152
	v_rcp_f32_e32 v153, v153
	v_rcp_f32_e32 v154, v154
	v_rcp_f32_e32 v155, v155
	v_readlane_b32 s7, v255, 27
	v_pk_mul_f32 v[126:127], v[126:127], v[152:153]
	s_cmp_ge_i32 s64, s7
	v_pk_mul_f32 v[128:129], v[128:129], v[154:155]
	v_pk_mul_f32 v[122:123], v[126:127], v[122:123]
	v_pk_mul_f32 v[124:125], v[128:129], v[124:125]
	v_mul_f32_e32 v126, 0xbfb8aa3b, v118
	v_mul_f32_e32 v127, 0xbfb8aa3b, v119
	v_mul_f32_e32 v128, 0xbfb8aa3b, v120
	v_mul_f32_e32 v129, 0xbfb8aa3b, v121
	v_exp_f32_e32 v126, v126
	v_exp_f32_e32 v127, v127
	v_exp_f32_e32 v128, v128
	v_exp_f32_e32 v129, v129
	v_add_f32_e32 v126, 1.0, v126
	v_add_f32_e32 v127, 1.0, v127
	v_add_f32_e32 v128, 1.0, v128
	v_add_f32_e32 v129, 1.0, v129
	s_cselect_b32 s7, s31, 0
	v_rcp_f32_e32 v126, v126
	v_rcp_f32_e32 v127, v127
	v_rcp_f32_e32 v128, v128
	v_rcp_f32_e32 v129, v129
	s_add_i32 s7, s64, s7
	s_lshl_b32 s10, s10, 7
	v_mov_b32_e32 v142, v146
	v_mov_b32_e32 v143, v1
	s_lshl_b32 s7, s7, 8
	s_or_b32 s10, s10, s53
	s_add_i32 s7, s7, s52
	v_lshl_add_u32 v144, v143, 3, s10
	v_add_u32_e32 v149, s7, v142
	v_ashrrev_i32_e32 v145, 31, v144
	v_mov_b64_e32 v[142:143], s[34:35]
	s_movk_i32 s7, 0x1600
	v_pk_mul_f32 v[118:119], v[118:119], v[126:127]
	v_pk_mul_f32 v[120:121], v[120:121], v[128:129]
	v_mad_i64_i32 v[150:151], s[12:13], v149, s7, v[142:143]
	v_lshlrev_b64 v[144:145], 1, v[144:145]
	v_pk_mul_f32 v[120:121], v[120:121], v[116:117]
	v_pk_mul_f32 v[116:117], v[118:119], v[114:115]
	v_lshl_add_u64 v[150:151], v[150:151], 0, v[144:145]
	v_cvt_pk_bf16_f32 v116, v116, v117
	v_cvt_pk_bf16_f32 v117, v120, v121
	v_cvt_pk_bf16_f32 v114, v122, v123
	v_cvt_pk_bf16_f32 v115, v124, v125
	global_store_dwordx4 v[150:151], v[114:117], off
	v_mul_f32_e32 v118, 0xbfb8aa3b, v112
	v_mul_f32_e32 v119, 0xbfb8aa3b, v113
	v_mul_f32_e32 v116, 0xbfb8aa3b, v110
	v_mul_f32_e32 v117, 0xbfb8aa3b, v111
	v_exp_f32_e32 v116, v116
	v_exp_f32_e32 v117, v117
	v_exp_f32_e32 v118, v118
	v_exp_f32_e32 v119, v119
	v_add_f32_e32 v116, 1.0, v116
	v_add_f32_e32 v117, 1.0, v117
	v_add_f32_e32 v118, 1.0, v118
	v_add_f32_e32 v119, 1.0, v119
	v_rcp_f32_e32 v116, v116
	v_rcp_f32_e32 v117, v117
	v_rcp_f32_e32 v118, v118
	v_rcp_f32_e32 v119, v119
	v_add_u32_e32 v114, 16, v149
	v_pk_mul_f32 v[110:111], v[110:111], v[116:117]
	v_mad_i64_i32 v[114:115], s[12:13], v114, s7, v[142:143]
	v_pk_mul_f32 v[112:113], v[112:113], v[118:119]
	v_pk_mul_f32 v[106:107], v[110:111], v[106:107]
	v_pk_mul_f32 v[108:109], v[112:113], v[108:109]
	v_mul_f32_e32 v110, 0xbfb8aa3b, v102
; __device__ __forceinline__ unsigned cvt_pk_bf16(float lo, float hi) { unsigned r; asm("v_cvt_pk_bf16_f32 %0, %1, %2" : "=v"(r) : "v"(lo), "v"(hi)); return r; }
;     __device__ __forceinline__ void operator()(const AccT& acc, const Unit& u, int wr, int wc, int fr, int fq) const {
;     ...
;         for (int ai = 0; ai < 2; ++ai)
; #pragma unroll
;             for (int m = 0; m < 4; ++m) { bf16_t* rowp = U + (size_t)(row0 + ai * 128 + m * 16) * HID + col0;
;                 const f32x4 s0 = silu4(acc[ai][0][m][0]) * acc[ai][1][m][0], s1 = silu4(acc[ai][0][m][1]) * acc[ai][1][m][1];
;                 u32x4 w; w.x = cvt_pk_bf16(s0[0], s0[1]); w.y = cvt_pk_bf16(s0[2], s0[3]); w.z = cvt_pk_bf16(s1[0], s1[1]); w.w = cvt_pk_bf16(s1[2], s1[3]);
;                 *(u32x4*)rowp = w; }
	v_mul_f32_e32 v111, 0xbfb8aa3b, v103
	v_mul_f32_e32 v112, 0xbfb8aa3b, v104
	v_mul_f32_e32 v113, 0xbfb8aa3b, v105
	v_exp_f32_e32 v110, v110
	v_exp_f32_e32 v111, v111
	v_exp_f32_e32 v112, v112
	v_exp_f32_e32 v113, v113
	v_add_f32_e32 v110, 1.0, v110
	v_add_f32_e32 v111, 1.0, v111
	v_add_f32_e32 v112, 1.0, v112
	v_add_f32_e32 v113, 1.0, v113
	v_rcp_f32_e32 v110, v110
	v_rcp_f32_e32 v111, v111
	v_rcp_f32_e32 v112, v112
	v_rcp_f32_e32 v113, v113
	v_lshl_add_u64 v[114:115], v[114:115], 0, v[144:145]
	v_pk_mul_f32 v[102:103], v[102:103], v[110:111]
	s_and_b64 vcc, exec, s[2:3]
	v_pk_mul_f32 v[104:105], v[104:105], v[112:113]
	s_mov_b32 s10, s6
	v_pk_mul_f32 v[104:105], v[104:105], v[100:101]
	v_pk_mul_f32 v[100:101], v[102:103], v[98:99]
	v_cvt_pk_bf16_f32 v98, v106, v107
	v_cvt_pk_bf16_f32 v99, v108, v109
	v_mul_f32_e32 v102, 0xbfb8aa3b, v96
	v_cvt_pk_bf16_f32 v100, v100, v101
	v_cvt_pk_bf16_f32 v101, v104, v105
	global_store_dwordx4 v[114:115], v[98:101], off
	v_mul_f32_e32 v103, 0xbfb8aa3b, v97
	v_exp_f32_e32 v102, v102
	v_mul_f32_e32 v100, 0xbfb8aa3b, v94
	v_mul_f32_e32 v101, 0xbfb8aa3b, v95
	v_exp_f32_e32 v100, v100
	v_exp_f32_e32 v101, v101
	v_exp_f32_e32 v103, v103
	v_add_f32_e32 v102, 1.0, v102
	v_add_f32_e32 v100, 1.0, v100
	v_add_f32_e32 v101, 1.0, v101
	v_add_f32_e32 v103, 1.0, v103
	v_rcp_f32_e32 v100, v100
	v_rcp_f32_e32 v101, v101
	v_rcp_f32_e32 v102, v102
	v_rcp_f32_e32 v103, v103
	v_add_u32_e32 v98, 32, v149
	v_pk_mul_f32 v[94:95], v[94:95], v[100:101]
	v_mad_i64_i32 v[98:99], s[12:13], v98, s7, v[142:143]
	v_pk_mul_f32 v[96:97], v[96:97], v[102:103]
	v_pk_mul_f32 v[90:91], v[94:95], v[90:91]
	v_pk_mul_f32 v[92:93], v[96:97], v[92:93]
	v_mul_f32_e32 v94, 0xbfb8aa3b, v86
	v_mul_f32_e32 v95, 0xbfb8aa3b, v87
	v_mul_f32_e32 v96, 0xbfb8aa3b, v88
	v_mul_f32_e32 v97, 0xbfb8aa3b, v89
	v_exp_f32_e32 v94, v94
	v_exp_f32_e32 v95, v95
	v_exp_f32_e32 v96, v96
	v_exp_f32_e32 v97, v97
	v_add_f32_e32 v94, 1.0, v94
	v_add_f32_e32 v95, 1.0, v95
	v_add_f32_e32 v96, 1.0, v96
	v_add_f32_e32 v97, 1.0, v97
	v_rcp_f32_e32 v94, v94
	v_rcp_f32_e32 v95, v95
	v_rcp_f32_e32 v96, v96
	v_rcp_f32_e32 v97, v97
	v_lshl_add_u64 v[98:99], v[98:99], 0, v[144:145]
	v_pk_mul_f32 v[86:87], v[86:87], v[94:95]
	s_mov_b32 s64, s61
	v_pk_mul_f32 v[88:89], v[88:89], v[96:97]
	s_mov_b64 s[14:15], s[4:5]
	v_pk_mul_f32 v[88:89], v[88:89], v[84:85]
	v_pk_mul_f32 v[84:85], v[86:87], v[82:83]
	v_cvt_pk_bf16_f32 v82, v90, v91
	v_cvt_pk_bf16_f32 v83, v92, v93
	v_mul_f32_e32 v86, 0xbfb8aa3b, v80
	v_cvt_pk_bf16_f32 v84, v84, v85
	v_cvt_pk_bf16_f32 v85, v88, v89
	global_store_dwordx4 v[98:99], v[82:85], off
	v_mul_f32_e32 v87, 0xbfb8aa3b, v81
	v_exp_f32_e32 v86, v86
	v_mul_f32_e32 v84, 0xbfb8aa3b, v78
	v_mul_f32_e32 v85, 0xbfb8aa3b, v79
	v_exp_f32_e32 v84, v84
	v_exp_f32_e32 v85, v85
	v_exp_f32_e32 v87, v87
	v_add_f32_e32 v86, 1.0, v86
	v_add_f32_e32 v84, 1.0, v84
	v_add_f32_e32 v85, 1.0, v85
	v_add_f32_e32 v87, 1.0, v87
	v_rcp_f32_e32 v84, v84
	v_rcp_f32_e32 v85, v85
	v_rcp_f32_e32 v86, v86
	v_rcp_f32_e32 v87, v87
	v_add_u32_e32 v82, 48, v149
	v_pk_mul_f32 v[78:79], v[78:79], v[84:85]
	v_mad_i64_i32 v[82:83], s[12:13], v82, s7, v[142:143]
	v_pk_mul_f32 v[80:81], v[80:81], v[86:87]
	v_pk_mul_f32 v[74:75], v[78:79], v[74:75]
	v_pk_mul_f32 v[76:77], v[80:81], v[76:77]
	v_mul_f32_e32 v78, 0xbfb8aa3b, v70
	v_mul_f32_e32 v79, 0xbfb8aa3b, v71
	v_mul_f32_e32 v80, 0xbfb8aa3b, v72
	v_mul_f32_e32 v81, 0xbfb8aa3b, v73
	v_exp_f32_e32 v78, v78
	v_exp_f32_e32 v79, v79
	v_exp_f32_e32 v80, v80
	v_exp_f32_e32 v81, v81
	v_add_f32_e32 v78, 1.0, v78
	v_add_f32_e32 v79, 1.0, v79
	v_add_f32_e32 v80, 1.0, v80
	v_add_f32_e32 v81, 1.0, v81
	v_rcp_f32_e32 v78, v78
	v_rcp_f32_e32 v79, v79
	v_rcp_f32_e32 v80, v80
	v_rcp_f32_e32 v81, v81
	v_lshl_add_u64 v[82:83], v[82:83], 0, v[144:145]
	v_pk_mul_f32 v[70:71], v[70:71], v[78:79]
	s_mov_b64 s[68:69], 0x1000
	v_pk_mul_f32 v[72:73], v[72:73], v[80:81]
	s_nop 0
	v_pk_mul_f32 v[72:73], v[72:73], v[68:69]
	v_pk_mul_f32 v[68:69], v[70:71], v[66:67]
	v_cvt_pk_bf16_f32 v66, v74, v75
	v_cvt_pk_bf16_f32 v67, v76, v77
	v_mul_f32_e32 v70, 0xbfb8aa3b, v64
	v_cvt_pk_bf16_f32 v68, v68, v69
	v_cvt_pk_bf16_f32 v69, v72, v73
	global_store_dwordx4 v[82:83], v[66:69], off
	v_mul_f32_e32 v71, 0xbfb8aa3b, v65
	v_exp_f32_e32 v70, v70
	v_mul_f32_e32 v68, 0xbfb8aa3b, v62
	v_mul_f32_e32 v69, 0xbfb8aa3b, v63
	v_exp_f32_e32 v68, v68
	v_exp_f32_e32 v69, v69
	v_exp_f32_e32 v71, v71
	v_add_f32_e32 v70, 1.0, v70
	v_add_f32_e32 v68, 1.0, v68
	v_add_f32_e32 v69, 1.0, v69
	v_add_f32_e32 v71, 1.0, v71
	v_rcp_f32_e32 v68, v68
	v_rcp_f32_e32 v69, v69
	v_rcp_f32_e32 v70, v70
	v_rcp_f32_e32 v71, v71
	v_add_u32_e32 v66, 0x80, v149
	v_pk_mul_f32 v[62:63], v[62:63], v[68:69]
	v_mad_i64_i32 v[66:67], s[12:13], v66, s7, v[142:143]
	v_pk_mul_f32 v[64:65], v[64:65], v[70:71]
	v_pk_mul_f32 v[58:59], v[62:63], v[58:59]
	v_pk_mul_f32 v[60:61], v[64:65], v[60:61]
	v_mul_f32_e32 v62, 0xbfb8aa3b, v54
	v_mul_f32_e32 v63, 0xbfb8aa3b, v55
	v_mul_f32_e32 v64, 0xbfb8aa3b, v56
	v_mul_f32_e32 v65, 0xbfb8aa3b, v57
	v_exp_f32_e32 v62, v62
	v_exp_f32_e32 v63, v63
	v_exp_f32_e32 v64, v64
	v_exp_f32_e32 v65, v65
	v_add_f32_e32 v62, 1.0, v62
	v_add_f32_e32 v63, 1.0, v63
	v_add_f32_e32 v64, 1.0, v64
	v_add_f32_e32 v65, 1.0, v65
	v_rcp_f32_e32 v62, v62
	v_rcp_f32_e32 v63, v63
; __device__ __forceinline__ unsigned cvt_pk_bf16(float lo, float hi) { unsigned r; asm("v_cvt_pk_bf16_f32 %0, %1, %2" : "=v"(r) : "v"(lo), "v"(hi)); return r; }
; #define PG8_WAIT_V(n) asm volatile("s_waitcnt vmcnt(" #n ")" ::: "memory")
; #define PG8_BAR __builtin_amdgcn_s_barrier()
; template <class Epi>
; __device__ __forceinline__ void gemm_phase(LAS unsigned char* lds, const Gemm g, const Epi& E) {
;     ...
;         E(acc, cur, wr, wc, fr, fq);
;         if (!has_next) break;
; #pragma unroll
;         for (int a = 0; a < 2; ++a)
; #pragma unroll
;             for (int b = 0; b < 2; ++b)
; #pragma unroll
;                 for (int m = 0; m < 4; ++m)
; #pragma unroll
;                     for (int n = 0; n < 2; ++n) acc[a][b][m][n] = (f32x4){0.f, 0.f, 0.f, 0.f};
;         cur = nxt; cA = nA; cB = nB; ++ui;
;     }
;     PG8_WAIT_V(0);
;     if (wr == 0) PG8_BAR;
;     PG8_BAR;
;     __device__ __forceinline__ void operator()(const AccT& acc, const Unit& u, int wr, int wc, int fr, int fq) const {
;     ...
;         for (int ai = 0; ai < 2; ++ai)
; #pragma unroll
;             for (int m = 0; m < 4; ++m) { bf16_t* rowp = U + (size_t)(row0 + ai * 128 + m * 16) * HID + col0;
;                 const f32x4 s0 = silu4(acc[ai][0][m][0]) * acc[ai][1][m][0], s1 = silu4(acc[ai][0][m][1]) * acc[ai][1][m][1];
;                 u32x4 w; w.x = cvt_pk_bf16(s0[0], s0[1]); w.y = cvt_pk_bf16(s0[2], s0[3]); w.z = cvt_pk_bf16(s1[0], s1[1]); w.w = cvt_pk_bf16(s1[2], s1[3]);
;                 *(u32x4*)rowp = w; }
	v_rcp_f32_e32 v64, v64
	v_rcp_f32_e32 v65, v65
	v_lshl_add_u64 v[66:67], v[66:67], 0, v[144:145]
	v_pk_mul_f32 v[54:55], v[54:55], v[62:63]
	v_pk_mul_f32 v[56:57], v[56:57], v[64:65]
	s_nop 0
	v_pk_mul_f32 v[56:57], v[56:57], v[52:53]
	v_pk_mul_f32 v[52:53], v[54:55], v[50:51]
	v_cvt_pk_bf16_f32 v50, v58, v59
	v_cvt_pk_bf16_f32 v51, v60, v61
	v_mul_f32_e32 v54, 0xbfb8aa3b, v48
	v_cvt_pk_bf16_f32 v52, v52, v53
	v_cvt_pk_bf16_f32 v53, v56, v57
	global_store_dwordx4 v[66:67], v[50:53], off
	v_mul_f32_e32 v55, 0xbfb8aa3b, v49
	v_exp_f32_e32 v54, v54
	v_mul_f32_e32 v52, 0xbfb8aa3b, v46
	v_mul_f32_e32 v53, 0xbfb8aa3b, v47
	v_exp_f32_e32 v52, v52
	v_exp_f32_e32 v53, v53
	v_exp_f32_e32 v55, v55
	v_add_f32_e32 v54, 1.0, v54
	v_add_f32_e32 v52, 1.0, v52
	v_add_f32_e32 v53, 1.0, v53
	v_add_f32_e32 v55, 1.0, v55
	v_rcp_f32_e32 v52, v52
	v_rcp_f32_e32 v53, v53
	v_rcp_f32_e32 v54, v54
	v_rcp_f32_e32 v55, v55
	v_add_u32_e32 v50, 0x90, v149
	v_pk_mul_f32 v[46:47], v[46:47], v[52:53]
	v_mad_i64_i32 v[50:51], s[12:13], v50, s7, v[142:143]
	v_pk_mul_f32 v[48:49], v[48:49], v[54:55]
	v_pk_mul_f32 v[42:43], v[46:47], v[42:43]
	v_pk_mul_f32 v[44:45], v[48:49], v[44:45]
	v_mul_f32_e32 v46, 0xbfb8aa3b, v38
	v_mul_f32_e32 v47, 0xbfb8aa3b, v39
	v_mul_f32_e32 v48, 0xbfb8aa3b, v40
	v_mul_f32_e32 v49, 0xbfb8aa3b, v41
	v_exp_f32_e32 v46, v46
	v_exp_f32_e32 v47, v47
	v_exp_f32_e32 v48, v48
	v_exp_f32_e32 v49, v49
	v_add_f32_e32 v46, 1.0, v46
	v_add_f32_e32 v47, 1.0, v47
	v_add_f32_e32 v48, 1.0, v48
	v_add_f32_e32 v49, 1.0, v49
	v_rcp_f32_e32 v46, v46
	v_rcp_f32_e32 v47, v47
	v_rcp_f32_e32 v48, v48
	v_rcp_f32_e32 v49, v49
	v_lshl_add_u64 v[50:51], v[50:51], 0, v[144:145]
	v_pk_mul_f32 v[38:39], v[38:39], v[46:47]
	v_pk_mul_f32 v[40:41], v[40:41], v[48:49]
	s_nop 0
	v_pk_mul_f32 v[40:41], v[40:41], v[36:37]
	v_pk_mul_f32 v[36:37], v[38:39], v[34:35]
	v_cvt_pk_bf16_f32 v34, v42, v43
	v_cvt_pk_bf16_f32 v35, v44, v45
	v_mul_f32_e32 v38, 0xbfb8aa3b, v32
	v_cvt_pk_bf16_f32 v36, v36, v37
	v_cvt_pk_bf16_f32 v37, v40, v41
	global_store_dwordx4 v[50:51], v[34:37], off
	v_mul_f32_e32 v39, 0xbfb8aa3b, v33
	v_exp_f32_e32 v38, v38
	v_mul_f32_e32 v36, 0xbfb8aa3b, v30
	v_mul_f32_e32 v37, 0xbfb8aa3b, v31
	v_exp_f32_e32 v36, v36
	v_exp_f32_e32 v37, v37
	v_exp_f32_e32 v39, v39
	v_add_f32_e32 v38, 1.0, v38
	v_add_f32_e32 v36, 1.0, v36
	v_add_f32_e32 v37, 1.0, v37
	v_add_f32_e32 v39, 1.0, v39
	v_rcp_f32_e32 v36, v36
	v_rcp_f32_e32 v37, v37
	v_rcp_f32_e32 v38, v38
	v_rcp_f32_e32 v39, v39
	v_add_u32_e32 v34, 0xa0, v149
	v_pk_mul_f32 v[30:31], v[30:31], v[36:37]
	v_mad_i64_i32 v[34:35], s[12:13], v34, s7, v[142:143]
	v_pk_mul_f32 v[32:33], v[32:33], v[38:39]
	v_pk_mul_f32 v[26:27], v[30:31], v[26:27]
	v_pk_mul_f32 v[28:29], v[32:33], v[28:29]
	v_mul_f32_e32 v30, 0xbfb8aa3b, v22
	v_mul_f32_e32 v31, 0xbfb8aa3b, v23
	v_mul_f32_e32 v32, 0xbfb8aa3b, v24
	v_mul_f32_e32 v33, 0xbfb8aa3b, v25
	v_exp_f32_e32 v30, v30
	v_exp_f32_e32 v31, v31
	v_exp_f32_e32 v32, v32
	v_exp_f32_e32 v33, v33
	v_add_f32_e32 v30, 1.0, v30
	v_add_f32_e32 v31, 1.0, v31
	v_add_f32_e32 v32, 1.0, v32
	v_add_f32_e32 v33, 1.0, v33
	v_rcp_f32_e32 v30, v30
	v_rcp_f32_e32 v31, v31
	v_rcp_f32_e32 v32, v32
	v_rcp_f32_e32 v33, v33
	v_lshl_add_u64 v[34:35], v[34:35], 0, v[144:145]
	v_pk_mul_f32 v[22:23], v[22:23], v[30:31]
	v_pk_mul_f32 v[24:25], v[24:25], v[32:33]
	s_nop 0
	v_pk_mul_f32 v[24:25], v[24:25], v[20:21]
	v_pk_mul_f32 v[20:21], v[22:23], v[18:19]
	v_cvt_pk_bf16_f32 v18, v26, v27
	v_cvt_pk_bf16_f32 v19, v28, v29
	v_mul_f32_e32 v22, 0xbfb8aa3b, v16
	v_cvt_pk_bf16_f32 v20, v20, v21
	v_cvt_pk_bf16_f32 v21, v24, v25
	global_store_dwordx4 v[34:35], v[18:21], off
	v_mul_f32_e32 v23, 0xbfb8aa3b, v17
	v_exp_f32_e32 v22, v22
	v_mul_f32_e32 v20, 0xbfb8aa3b, v14
	v_mul_f32_e32 v21, 0xbfb8aa3b, v15
	v_exp_f32_e32 v20, v20
	v_exp_f32_e32 v21, v21
	v_exp_f32_e32 v23, v23
	v_add_f32_e32 v22, 1.0, v22
	v_add_f32_e32 v20, 1.0, v20
	v_add_f32_e32 v21, 1.0, v21
	v_add_f32_e32 v23, 1.0, v23
	v_rcp_f32_e32 v20, v20
	v_rcp_f32_e32 v21, v21
	v_rcp_f32_e32 v22, v22
	v_rcp_f32_e32 v23, v23
	v_add_u32_e32 v18, 0xb0, v149
	v_pk_mul_f32 v[14:15], v[14:15], v[20:21]
	v_mad_i64_i32 v[18:19], s[12:13], v18, s7, v[142:143]
	v_pk_mul_f32 v[16:17], v[16:17], v[22:23]
	v_pk_mul_f32 v[10:11], v[14:15], v[10:11]
	v_pk_mul_f32 v[12:13], v[16:17], v[12:13]
	v_mul_f32_e32 v14, 0xbfb8aa3b, v6
	v_mul_f32_e32 v15, 0xbfb8aa3b, v7
	v_mul_f32_e32 v16, 0xbfb8aa3b, v8
	v_mul_f32_e32 v17, 0xbfb8aa3b, v9
	v_exp_f32_e32 v14, v14
	v_exp_f32_e32 v15, v15
	v_exp_f32_e32 v16, v16
	v_exp_f32_e32 v17, v17
	v_add_f32_e32 v14, 1.0, v14
	v_add_f32_e32 v15, 1.0, v15
	v_add_f32_e32 v16, 1.0, v16
	v_add_f32_e32 v17, 1.0, v17
	v_rcp_f32_e32 v14, v14
	v_rcp_f32_e32 v15, v15
	v_rcp_f32_e32 v16, v16
	v_rcp_f32_e32 v17, v17
	v_lshl_add_u64 v[18:19], v[18:19], 0, v[144:145]
	v_pk_mul_f32 v[6:7], v[6:7], v[14:15]
	s_mov_b64 s[12:13], s[8:9]
	v_pk_mul_f32 v[8:9], v[8:9], v[16:17]
	s_nop 0
	v_pk_mul_f32 v[8:9], v[8:9], v[4:5]
	v_pk_mul_f32 v[4:5], v[6:7], v[2:3]
	v_cvt_pk_bf16_f32 v2, v10, v11
	v_cvt_pk_bf16_f32 v3, v12, v13
	s_nop 0
	v_cvt_pk_bf16_f32 v4, v4, v5
	v_cvt_pk_bf16_f32 v5, v8, v9
	global_store_dwordx4 v[18:19], v[2:5], off
	s_cbranch_vccz .LBB0_520
	s_waitcnt vmcnt(0)
	s_cmpk_gt_u32 s1, 0xff
	s_cbranch_scc1 .LBB0_529
	s_barrier

; #define PG8_STAGE(bufoff, gbase, voff) do { _Pragma("unroll") for (int _i = 0; _i < 2; ++_i) \
;         __builtin_amdgcn_global_load_lds((const unsigned*)((const char*)(gbase) + (voff)[_i]), (LAS unsigned*)(lds + (bufoff) + ldsw + _i * 8192), 16, 0, 0); } while (0)
; #define PG8_LDA(dst, b, h) do { _Pragma("unroll") for (int m = 0; m < 4; ++m) _Pragma("unroll") for (int k = 0; k < 2; ++k) dst[m][k] = *(const LAS bf16x8*)(lds + PG8_SA(b, h) + aoff + m * 2048 + k * 1024); } while (0)
; #define PG8_LDB(dst, b, h) do { _Pragma("unroll") for (int n = 0; n < 2; ++n) _Pragma("unroll") for (int k = 0; k < 2; ++k) dst[n][k] = *(const LAS bf16x8*)(lds + PG8_SB(b, h) + boff + n * 2048 + k * 1024); } while (0)
; #define PG8_MMA(ai, bj, At, Bt) do { __builtin_amdgcn_s_setprio(1); _Pragma("unroll") for (int m = 0; m < 4; ++m) _Pragma("unroll") for (int n = 0; n < 2; ++n) _Pragma("unroll") for (int k = 0; k < 2; ++k) \
;         acc[ai][bj][m][n] = __builtin_amdgcn_mfma_f32_16x16x32_bf16(Bt[n][k], At[m][k], acc[ai][bj][m][n], 0, 0, 0); __builtin_amdgcn_s_setprio(0); } while (0)
; #define PG8_WAIT_L(n) asm volatile("s_waitcnt lgkmcnt(" #n ")" ::: "memory")
; #define PG8_BAR __builtin_amdgcn_s_barrier()
; #define PG8_SCHED __builtin_amdgcn_sched_barrier(0)
; template <class Epi>
; __device__ __forceinline__ void gemm_phase(LAS unsigned char* lds, const Gemm g, const Epi& E) {
;     ...
;             PG8_LDB(B0, 0, 0); PG8_SCHED; PG8_LDA(At, 0, 0); PG8_STAGE(PG8_SA(1, 1), a1 + hstepA, voffA);
;             PG8_WAIT_L(8); PG8_BAR; PG8_WAIT_L(0); PG8_MMA(0, 0, At, B0); PG8_BAR; PG8_SCHED;
;             PG8_LDB(B1, 0, 1); PG8_STAGE(PG8_SB(0, 0), b2, voffB);
;             PG8_BAR; PG8_WAIT_L(0); PG8_MMA(0, 1, At, B1); PG8_BAR;
;             PG8_LDA(At, 0, 1); PG8_STAGE(PG8_SA(0, 0), a2, voffA);
;             PG8_BAR; PG8_WAIT_L(0); PG8_MMA(1, 0, At, B0); PG8_BAR; PG8_SCHED;
.LBB0_547:
	s_add_u32 s10, s8, 0x100
	s_addc_u32 s11, s9, 0
	s_add_i32 s26, 0, 0x10000
	v_add_u32_e32 v142, s26, v157
	ds_read_b128 v[130:133], v142
	ds_read_b128 v[134:137], v142 offset:1024
	ds_read_b128 v[138:141], v142 offset:2048
	ds_read_b128 v[142:145], v142 offset:3072
	s_cmp_eq_u32 s67, 40
	s_cselect_b32 s15, s5, s11
	s_cselect_b32 s14, s4, s10
	s_cselect_b32 s13, s7, s66
	s_cselect_b32 s12, s6, s65
	v_lshl_add_u64 v[154:155], s[8:9], 0, v[150:151]
	s_add_i32 m0, s29, 0xc000
	ds_read_b128 v[160:163], v158
	ds_read_b128 v[164:167], v158 offset:1024
	ds_read_b128 v[168:171], v158 offset:2048
	ds_read_b128 v[172:175], v158 offset:3072
	ds_read_b128 v[180:183], v158 offset:4096
	ds_read_b128 v[184:187], v158 offset:5120
	ds_read_b128 v[188:191], v158 offset:6144
	ds_read_b128 v[192:195], v158 offset:7168
	global_load_lds_dwordx4 v[154:155], off
	v_lshl_add_u64 v[154:155], s[8:9], 0, v[152:153]
	s_add_i32 m0, s29, 0xe000
	s_nop 0
	global_load_lds_dwordx4 v[154:155], off
	s_waitcnt lgkmcnt(0)
	s_barrier
	v_mfma_f32_16x16x32_bf16 v[126:129], v[130:133], v[160:163], v[126:129]
	v_mfma_f32_16x16x32_bf16 v[122:125], v[138:141], v[160:163], v[122:125]
	v_mfma_f32_16x16x32_bf16 v[118:121], v[130:133], v[168:171], v[118:121]
	v_mfma_f32_16x16x32_bf16 v[110:113], v[138:141], v[168:171], v[110:113]
	v_mfma_f32_16x16x32_bf16 v[102:105], v[130:133], v[180:183], v[102:105]
	v_mfma_f32_16x16x32_bf16 v[94:97], v[138:141], v[180:183], v[94:97]
	v_mfma_f32_16x16x32_bf16 v[86:89], v[130:133], v[188:191], v[86:89]
	v_mfma_f32_16x16x32_bf16 v[78:81], v[138:141], v[188:191], v[78:81]
	v_mfma_f32_16x16x32_bf16 v[126:129], v[134:137], v[164:167], v[126:129]
	v_mfma_f32_16x16x32_bf16 v[122:125], v[142:145], v[164:167], v[122:125]
	v_mfma_f32_16x16x32_bf16 v[118:121], v[134:137], v[172:175], v[118:121]
	v_mfma_f32_16x16x32_bf16 v[110:113], v[142:145], v[172:175], v[110:113]
	v_mfma_f32_16x16x32_bf16 v[102:105], v[134:137], v[184:187], v[102:105]
	v_mfma_f32_16x16x32_bf16 v[94:97], v[142:145], v[184:187], v[94:97]
	v_mfma_f32_16x16x32_bf16 v[86:89], v[134:137], v[192:195], v[86:89]
	v_mfma_f32_16x16x32_bf16 v[78:81], v[142:145], v[192:195], v[78:81]
	s_barrier
	s_add_i32 s27, 0, 0x14000
	v_add_u32_e32 v154, s27, v157
	s_add_i32 s8, s26, s18
	ds_read_b128 v[196:199], v154
	ds_read_b128 v[200:203], v154 offset:1024
	ds_read_b128 v[204:207], v154 offset:2048
	ds_read_b128 v[226:229], v154 offset:3072
	v_lshl_add_u64 v[154:155], s[12:13], 0, v[148:149]
	s_mov_b32 m0, s8
	v_lshl_add_u64 v[176:177], s[12:13], 0, v[146:147]
	global_load_lds_dwordx4 v[154:155], off
	s_add_i32 m0, s8, 0x2000
	s_nop 0
	global_load_lds_dwordx4 v[176:177], off
	s_nop 1
	s_mov_b32 m0, s29
	v_lshl_add_u64 v[208:209], s[14:15], 0, v[148:149]
	s_waitcnt lgkmcnt(0)
	s_barrier
	v_mfma_f32_16x16x32_bf16 v[114:117], v[196:199], v[160:163], v[114:117]
	v_mfma_f32_16x16x32_bf16 v[106:109], v[204:207], v[160:163], v[106:109]
	v_mfma_f32_16x16x32_bf16 v[98:101], v[196:199], v[168:171], v[98:101]
	v_mfma_f32_16x16x32_bf16 v[90:93], v[204:207], v[168:171], v[90:93]
	v_mfma_f32_16x16x32_bf16 v[82:85], v[196:199], v[180:183], v[82:85]
	v_mfma_f32_16x16x32_bf16 v[74:77], v[204:207], v[180:183], v[74:77]
	v_mfma_f32_16x16x32_bf16 v[70:73], v[196:199], v[188:191], v[70:73]
	v_mfma_f32_16x16x32_bf16 v[66:69], v[204:207], v[188:191], v[66:69]
	v_mfma_f32_16x16x32_bf16 v[114:117], v[200:203], v[164:167], v[114:117]
	v_mfma_f32_16x16x32_bf16 v[106:109], v[226:229], v[164:167], v[106:109]
	v_mfma_f32_16x16x32_bf16 v[98:101], v[200:203], v[172:175], v[98:101]
	v_mfma_f32_16x16x32_bf16 v[90:93], v[226:229], v[172:175], v[90:93]
	v_mfma_f32_16x16x32_bf16 v[82:85], v[200:203], v[184:187], v[82:85]
	v_mfma_f32_16x16x32_bf16 v[74:77], v[226:229], v[184:187], v[74:77]
	v_mfma_f32_16x16x32_bf16 v[70:73], v[200:203], v[192:195], v[70:73]
	v_mfma_f32_16x16x32_bf16 v[66:69], v[226:229], v[192:195], v[66:69]
	s_barrier
	ds_read_b128 v[160:163], v158 offset:16384
	ds_read_b128 v[164:167], v158 offset:17408
	ds_read_b128 v[168:171], v158 offset:18432
	ds_read_b128 v[172:175], v158 offset:19456
	ds_read_b128 v[180:183], v158 offset:20480
	ds_read_b128 v[184:187], v158 offset:21504
	ds_read_b128 v[188:191], v158 offset:22528
	ds_read_b128 v[192:195], v158 offset:23552
	global_load_lds_dwordx4 v[208:209], off
	v_lshl_add_u64 v[230:231], s[14:15], 0, v[146:147]
	s_mov_b32 m0, s30
	s_nop 0
	global_load_lds_dwordx4 v[230:231], off
	s_waitcnt lgkmcnt(0)
	s_barrier
	v_mfma_f32_16x16x32_bf16 v[62:65], v[130:133], v[160:163], v[62:65]
	v_mfma_f32_16x16x32_bf16 v[58:61], v[138:141], v[160:163], v[58:61]
	v_mfma_f32_16x16x32_bf16 v[54:57], v[130:133], v[168:171], v[54:57]
	v_mfma_f32_16x16x32_bf16 v[46:49], v[138:141], v[168:171], v[46:49]
	v_mfma_f32_16x16x32_bf16 v[38:41], v[130:133], v[180:183], v[38:41]
	v_mfma_f32_16x16x32_bf16 v[30:33], v[138:141], v[180:183], v[30:33]
	v_mfma_f32_16x16x32_bf16 v[22:25], v[130:133], v[188:191], v[22:25]
	v_mfma_f32_16x16x32_bf16 v[14:17], v[138:141], v[188:191], v[14:17]
	v_mfma_f32_16x16x32_bf16 v[62:65], v[134:137], v[164:167], v[62:65]
	v_mfma_f32_16x16x32_bf16 v[58:61], v[142:145], v[164:167], v[58:61]
	v_mfma_f32_16x16x32_bf16 v[54:57], v[134:137], v[172:175], v[54:57]
	v_mfma_f32_16x16x32_bf16 v[46:49], v[142:145], v[172:175], v[46:49]
	v_mfma_f32_16x16x32_bf16 v[38:41], v[134:137], v[184:187], v[38:41]
	v_mfma_f32_16x16x32_bf16 v[30:33], v[142:145], v[184:187], v[30:33]
	v_mfma_f32_16x16x32_bf16 v[22:25], v[134:137], v[192:195], v[22:25]
	v_mfma_f32_16x16x32_bf16 v[14:17], v[142:145], v[192:195], v[14:17]
	s_barrier
; #define PG8_STAGE(bufoff, gbase, voff) do { _Pragma("unroll") for (int _i = 0; _i < 2; ++_i) \
;         __builtin_amdgcn_global_load_lds((const unsigned*)((const char*)(gbase) + (voff)[_i]), (LAS unsigned*)(lds + (bufoff) + ldsw + _i * 8192), 16, 0, 0); } while (0)
; #define PG8_LDA(dst, b, h) do { _Pragma("unroll") for (int m = 0; m < 4; ++m) _Pragma("unroll") for (int k = 0; k < 2; ++k) dst[m][k] = *(const LAS bf16x8*)(lds + PG8_SA(b, h) + aoff + m * 2048 + k * 1024); } while (0)
; #define PG8_LDB(dst, b, h) do { _Pragma("unroll") for (int n = 0; n < 2; ++n) _Pragma("unroll") for (int k = 0; k < 2; ++k) dst[n][k] = *(const LAS bf16x8*)(lds + PG8_SB(b, h) + boff + n * 2048 + k * 1024); } while (0)
; #define PG8_MMA(ai, bj, At, Bt) do { __builtin_amdgcn_s_setprio(1); _Pragma("unroll") for (int m = 0; m < 4; ++m) _Pragma("unroll") for (int n = 0; n < 2; ++n) _Pragma("unroll") for (int k = 0; k < 2; ++k) \
;         acc[ai][bj][m][n] = __builtin_amdgcn_mfma_f32_16x16x32_bf16(Bt[n][k], At[m][k], acc[ai][bj][m][n], 0, 0, 0); __builtin_amdgcn_s_setprio(0); } while (0)
; #define PG8_WAIT_V(n) asm volatile("s_waitcnt vmcnt(" #n ")" ::: "memory")
; #define PG8_WAIT_L(n) asm volatile("s_waitcnt lgkmcnt(" #n ")" ::: "memory")
; #define PG8_BAR __builtin_amdgcn_s_barrier()
; #define PG8_SCHED __builtin_amdgcn_sched_barrier(0)
; template <class Epi>
; __device__ __forceinline__ void gemm_phase(LAS unsigned char* lds, const Gemm g, const Epi& E) {
;     ...
;             PG8_STAGE(PG8_SB(0, 1), b2 + hstepB, voffB);
;             PG8_WAIT_V(6); PG8_BAR; PG8_MMA(1, 1, At, B1); PG8_BAR;
;             PG8_LDB(B0, 1, 0); PG8_SCHED; PG8_LDA(At, 1, 0); PG8_STAGE(PG8_SA(0, 1), a2 + hstepA, voffA);
;             PG8_WAIT_L(8); PG8_BAR; PG8_WAIT_L(0); PG8_MMA(0, 0, At, B0); PG8_BAR; PG8_SCHED;
;             PG8_LDB(B1, 1, 1); PG8_STAGE(PG8_SB(1, 0), b3, voffB);
;             PG8_BAR; PG8_WAIT_L(0); PG8_MMA(0, 1, At, B1); PG8_BAR;
;             PG8_LDA(At, 1, 1); PG8_STAGE(PG8_SA(1, 0), a3, voffA);
;             PG8_BAR; PG8_WAIT_L(0); PG8_MMA(1, 0, At, B0); PG8_BAR; PG8_SCHED;
	s_add_u32 s8, s12, 0xb0000
	s_addc_u32 s9, s13, 0
	s_add_i32 s26, s27, s18
	v_lshl_add_u64 v[130:131], s[8:9], 0, v[148:149]
	s_mov_b32 m0, s26
	s_nop 0
	global_load_lds_dwordx4 v[130:131], off
	v_lshl_add_u64 v[130:131], s[8:9], 0, v[146:147]
	s_add_i32 m0, s26, 0x2000
	s_nop 0
	global_load_lds_dwordx4 v[130:131], off
	s_add_i32 s26, 0, 0x18000
	v_add_u32_e32 v142, s26, v157
	s_waitcnt vmcnt(6)
	s_barrier
	v_mfma_f32_16x16x32_bf16 v[50:53], v[196:199], v[160:163], v[50:53]
	v_mfma_f32_16x16x32_bf16 v[42:45], v[204:207], v[160:163], v[42:45]
	v_mfma_f32_16x16x32_bf16 v[34:37], v[196:199], v[168:171], v[34:37]
	v_mfma_f32_16x16x32_bf16 v[26:29], v[204:207], v[168:171], v[26:29]
	v_mfma_f32_16x16x32_bf16 v[18:21], v[196:199], v[180:183], v[18:21]
	v_mfma_f32_16x16x32_bf16 v[10:13], v[204:207], v[180:183], v[10:13]
	v_mfma_f32_16x16x32_bf16 v[6:9], v[196:199], v[188:191], v[6:9]
	v_mfma_f32_16x16x32_bf16 v[2:5], v[204:207], v[188:191], v[2:5]
	v_mfma_f32_16x16x32_bf16 v[50:53], v[200:203], v[164:167], v[50:53]
	v_mfma_f32_16x16x32_bf16 v[42:45], v[226:229], v[164:167], v[42:45]
	v_mfma_f32_16x16x32_bf16 v[34:37], v[200:203], v[172:175], v[34:37]
	v_mfma_f32_16x16x32_bf16 v[26:29], v[226:229], v[172:175], v[26:29]
	v_mfma_f32_16x16x32_bf16 v[18:21], v[200:203], v[184:187], v[18:21]
	v_mfma_f32_16x16x32_bf16 v[10:13], v[226:229], v[184:187], v[10:13]
	v_mfma_f32_16x16x32_bf16 v[6:9], v[200:203], v[192:195], v[6:9]
	v_mfma_f32_16x16x32_bf16 v[2:5], v[226:229], v[192:195], v[2:5]
	s_barrier
	ds_read_b128 v[130:133], v142
	ds_read_b128 v[134:137], v142 offset:1024
	ds_read_b128 v[138:141], v142 offset:2048
	ds_read_b128 v[142:145], v142 offset:3072
	s_add_u32 s8, s14, 0xb0000
	s_addc_u32 s9, s15, 0
	s_mov_b32 m0, s31
	v_lshl_add_u64 v[196:197], s[8:9], 0, v[148:149]
	ds_read_b128 v[160:163], v158 offset:32768
	ds_read_b128 v[164:167], v158 offset:33792
	ds_read_b128 v[168:171], v158 offset:34816
	ds_read_b128 v[172:175], v158 offset:35840
	ds_read_b128 v[180:183], v158 offset:36864
	ds_read_b128 v[184:187], v158 offset:37888
	ds_read_b128 v[188:191], v158 offset:38912
	ds_read_b128 v[192:195], v158 offset:39936
	global_load_lds_dwordx4 v[196:197], off
	v_lshl_add_u64 v[196:197], s[8:9], 0, v[146:147]
	s_mov_b32 m0, s36
	s_nop 0
	global_load_lds_dwordx4 v[196:197], off
	s_waitcnt lgkmcnt(0)
	s_barrier
	v_mfma_f32_16x16x32_bf16 v[126:129], v[130:133], v[160:163], v[126:129]
	v_mfma_f32_16x16x32_bf16 v[122:125], v[138:141], v[160:163], v[122:125]
	v_mfma_f32_16x16x32_bf16 v[118:121], v[130:133], v[168:171], v[118:121]
	v_mfma_f32_16x16x32_bf16 v[110:113], v[138:141], v[168:171], v[110:113]
	v_mfma_f32_16x16x32_bf16 v[102:105], v[130:133], v[180:183], v[102:105]
	v_mfma_f32_16x16x32_bf16 v[94:97], v[138:141], v[180:183], v[94:97]
	v_mfma_f32_16x16x32_bf16 v[86:89], v[130:133], v[188:191], v[86:89]
	v_mfma_f32_16x16x32_bf16 v[78:81], v[138:141], v[188:191], v[78:81]
	v_mfma_f32_16x16x32_bf16 v[126:129], v[134:137], v[164:167], v[126:129]
	v_mfma_f32_16x16x32_bf16 v[122:125], v[142:145], v[164:167], v[122:125]
	v_mfma_f32_16x16x32_bf16 v[118:121], v[134:137], v[172:175], v[118:121]
	v_mfma_f32_16x16x32_bf16 v[110:113], v[142:145], v[172:175], v[110:113]
	v_mfma_f32_16x16x32_bf16 v[102:105], v[134:137], v[184:187], v[102:105]
	v_mfma_f32_16x16x32_bf16 v[94:97], v[142:145], v[184:187], v[94:97]
	v_mfma_f32_16x16x32_bf16 v[86:89], v[134:137], v[192:195], v[86:89]
	v_mfma_f32_16x16x32_bf16 v[78:81], v[142:145], v[192:195], v[78:81]
	s_barrier
	s_add_i32 s14, 0, 0x1c000
	s_add_i32 s8, s26, s18
	v_add_u32_e32 v159, s14, v157
	v_lshl_add_u64 v[154:155], v[154:155], 0, s[86:87]
	s_mov_b32 m0, s8
	ds_read_b128 v[196:199], v159
	ds_read_b128 v[200:203], v159 offset:1024
	ds_read_b128 v[204:207], v159 offset:2048
	ds_read_b128 v[226:229], v159 offset:3072
	global_load_lds_dwordx4 v[154:155], off
	v_lshl_add_u64 v[154:155], v[176:177], 0, s[86:87]
	s_add_i32 m0, s8, 0x2000
	s_nop 0
	global_load_lds_dwordx4 v[154:155], off
	s_nop 1
	s_mov_b32 m0, s52
	v_lshl_add_u64 v[154:155], v[208:209], 0, s[86:87]
	s_waitcnt lgkmcnt(0)
	s_barrier
	v_mfma_f32_16x16x32_bf16 v[114:117], v[196:199], v[160:163], v[114:117]
	v_mfma_f32_16x16x32_bf16 v[106:109], v[204:207], v[160:163], v[106:109]
	v_mfma_f32_16x16x32_bf16 v[98:101], v[196:199], v[168:171], v[98:101]
	v_mfma_f32_16x16x32_bf16 v[90:93], v[204:207], v[168:171], v[90:93]
	v_mfma_f32_16x16x32_bf16 v[82:85], v[196:199], v[180:183], v[82:85]
	v_mfma_f32_16x16x32_bf16 v[74:77], v[204:207], v[180:183], v[74:77]
	v_mfma_f32_16x16x32_bf16 v[70:73], v[196:199], v[188:191], v[70:73]
	v_mfma_f32_16x16x32_bf16 v[66:69], v[204:207], v[188:191], v[66:69]
	v_mfma_f32_16x16x32_bf16 v[114:117], v[200:203], v[164:167], v[114:117]
	v_mfma_f32_16x16x32_bf16 v[106:109], v[226:229], v[164:167], v[106:109]
	v_mfma_f32_16x16x32_bf16 v[98:101], v[200:203], v[172:175], v[98:101]
	v_mfma_f32_16x16x32_bf16 v[90:93], v[226:229], v[172:175], v[90:93]
	v_mfma_f32_16x16x32_bf16 v[82:85], v[200:203], v[184:187], v[82:85]
	v_mfma_f32_16x16x32_bf16 v[74:77], v[226:229], v[184:187], v[74:77]
	v_mfma_f32_16x16x32_bf16 v[70:73], v[200:203], v[192:195], v[70:73]
	v_mfma_f32_16x16x32_bf16 v[66:69], v[226:229], v[192:195], v[66:69]
	s_barrier
	ds_read_b128 v[160:163], v158 offset:49152
	ds_read_b128 v[164:167], v158 offset:50176
	ds_read_b128 v[168:171], v158 offset:51200
	ds_read_b128 v[172:175], v158 offset:52224
	ds_read_b128 v[180:183], v158 offset:53248
	ds_read_b128 v[184:187], v158 offset:54272
	ds_read_b128 v[188:191], v158 offset:55296
	ds_read_b128 v[192:195], v158 offset:56320
	global_load_lds_dwordx4 v[154:155], off
	v_lshl_add_u64 v[154:155], v[230:231], 0, s[86:87]
	s_mov_b32 m0, s53
	s_nop 0
	global_load_lds_dwordx4 v[154:155], off
	s_waitcnt lgkmcnt(0)
	s_barrier
; #define PG8_STAGE(bufoff, gbase, voff) do { _Pragma("unroll") for (int _i = 0; _i < 2; ++_i) \
;         __builtin_amdgcn_global_load_lds((const unsigned*)((const char*)(gbase) + (voff)[_i]), (LAS unsigned*)(lds + (bufoff) + ldsw + _i * 8192), 16, 0, 0); } while (0)
; #define PG8_MMA(ai, bj, At, Bt) do { __builtin_amdgcn_s_setprio(1); _Pragma("unroll") for (int m = 0; m < 4; ++m) _Pragma("unroll") for (int n = 0; n < 2; ++n) _Pragma("unroll") for (int k = 0; k < 2; ++k) \
;         acc[ai][bj][m][n] = __builtin_amdgcn_mfma_f32_16x16x32_bf16(Bt[n][k], At[m][k], acc[ai][bj][m][n], 0, 0, 0); __builtin_amdgcn_s_setprio(0); } while (0)
; #define PG8_WAIT_V(n) asm volatile("s_waitcnt vmcnt(" #n ")" ::: "memory")
; #define PG8_BAR __builtin_amdgcn_s_barrier()
; template <class Epi>
; __device__ __forceinline__ void gemm_phase(LAS unsigned char* lds, const Gemm g, const Epi& E) {
;     ...
;             PG8_STAGE(PG8_SB(1, 1), b3 + hstepB, voffB);
;             PG8_WAIT_V(6); PG8_BAR; PG8_MMA(1, 1, At, B1); PG8_BAR;
;     __device__ __forceinline__ void operator()(const AccT& acc, const Unit& u, int wr, int wc, int fr, int fq) const {
;     ...
;         const int gpm = mapA.src(u.pm);
;         const int mb = gpm < 32 ? 32 : (gpm - 32) >> 3;
;         const int row0 = gpm * 256 + wr * 64 + fr, col0 = u.pn * 256 + wc * 32 + 4 * fq;
;         const float* gp = modl + ((size_t)mb * 6 + gi) * 1024;
;         f32x4 gv[2][2];
; #pragma unroll
;         for (int bj = 0; bj < 2; ++bj)
; #pragma unroll
;             for (int n = 0; n < 2; ++n) { gv[bj][n] = *(const f32x4*)(gp + col0 + bj * 128 + n * 16); if (scale) gv[bj][n] = gv[bj][n] * *(const f32x4*)(scale + col0 + bj * 128 + n * 16); }
;         const float* sbase = (gpm < 32 ? Xc : Xl) + (size_t)row0 * 1024 + col0;
; #pragma unroll
;         for (int ai = 0; ai < 2; ++ai) {
;             f32x4 xo[4][2][2];
; #pragma unroll
;             for (int m = 0; m < 4; ++m)
; #pragma unroll
;                 for (int bj = 0; bj < 2; ++bj)
; #pragma unroll
;                     for (int n = 0; n < 2; ++n) xo[m][bj][n] = *(const f32x4*)(sbase + (size_t)(ai * 128 + m * 16) * 1024 + bj * 128 + n * 16);
	v_mfma_f32_16x16x32_bf16 v[62:65], v[130:133], v[160:163], v[62:65]
	v_mfma_f32_16x16x32_bf16 v[58:61], v[138:141], v[160:163], v[58:61]
	v_mfma_f32_16x16x32_bf16 v[54:57], v[130:133], v[168:171], v[54:57]
	v_mfma_f32_16x16x32_bf16 v[46:49], v[138:141], v[168:171], v[46:49]
	v_mfma_f32_16x16x32_bf16 v[38:41], v[130:133], v[180:183], v[38:41]
	v_mfma_f32_16x16x32_bf16 v[30:33], v[138:141], v[180:183], v[30:33]
	v_mfma_f32_16x16x32_bf16 v[22:25], v[130:133], v[188:191], v[22:25]
	v_mfma_f32_16x16x32_bf16 v[14:17], v[138:141], v[188:191], v[14:17]
	v_mfma_f32_16x16x32_bf16 v[62:65], v[134:137], v[164:167], v[62:65]
	v_mfma_f32_16x16x32_bf16 v[58:61], v[142:145], v[164:167], v[58:61]
	v_mfma_f32_16x16x32_bf16 v[54:57], v[134:137], v[172:175], v[54:57]
	v_mfma_f32_16x16x32_bf16 v[46:49], v[142:145], v[172:175], v[46:49]
	v_mfma_f32_16x16x32_bf16 v[38:41], v[134:137], v[184:187], v[38:41]
	v_mfma_f32_16x16x32_bf16 v[30:33], v[142:145], v[184:187], v[30:33]
	v_mfma_f32_16x16x32_bf16 v[22:25], v[134:137], v[192:195], v[22:25]
	v_mfma_f32_16x16x32_bf16 v[14:17], v[142:145], v[192:195], v[14:17]
	s_barrier
	s_add_u32 s8, s12, 0xb0080
	s_addc_u32 s9, s13, 0
	s_add_i32 s12, s14, s18
	v_lshl_add_u64 v[130:131], s[8:9], 0, v[148:149]
	s_mov_b32 m0, s12
	s_nop 0
	global_load_lds_dwordx4 v[130:131], off
	v_lshl_add_u64 v[130:131], s[8:9], 0, v[146:147]
	s_add_i32 m0, s12, 0x2000
	s_nop 0
	global_load_lds_dwordx4 v[130:131], off
	s_waitcnt vmcnt(6)
	s_barrier
	v_mfma_f32_16x16x32_bf16 v[50:53], v[196:199], v[160:163], v[50:53]
	v_mfma_f32_16x16x32_bf16 v[42:45], v[204:207], v[160:163], v[42:45]
	v_mfma_f32_16x16x32_bf16 v[34:37], v[196:199], v[168:171], v[34:37]
	v_mfma_f32_16x16x32_bf16 v[26:29], v[204:207], v[168:171], v[26:29]
	v_mfma_f32_16x16x32_bf16 v[18:21], v[196:199], v[180:183], v[18:21]
	v_mfma_f32_16x16x32_bf16 v[10:13], v[204:207], v[180:183], v[10:13]
	v_mfma_f32_16x16x32_bf16 v[6:9], v[196:199], v[188:191], v[6:9]
	v_mfma_f32_16x16x32_bf16 v[2:5], v[204:207], v[188:191], v[2:5]
	v_mfma_f32_16x16x32_bf16 v[50:53], v[200:203], v[164:167], v[50:53]
	v_mfma_f32_16x16x32_bf16 v[42:45], v[226:229], v[164:167], v[42:45]
	v_mfma_f32_16x16x32_bf16 v[34:37], v[200:203], v[172:175], v[34:37]
	v_mfma_f32_16x16x32_bf16 v[26:29], v[226:229], v[172:175], v[26:29]
	v_mfma_f32_16x16x32_bf16 v[18:21], v[200:203], v[184:187], v[18:21]
	v_mfma_f32_16x16x32_bf16 v[10:13], v[226:229], v[184:187], v[10:13]
	v_mfma_f32_16x16x32_bf16 v[6:9], v[200:203], v[192:195], v[6:9]
	v_mfma_f32_16x16x32_bf16 v[2:5], v[226:229], v[192:195], v[2:5]
	s_add_i32 s67, s67, 2
	s_add_u32 s65, s65, 0x100
	s_addc_u32 s66, s66, 0
	s_cmp_gt_u32 s67, 41
	s_mov_b64 s[8:9], s[10:11]
	s_barrier
	s_cbranch_scc0 .LBB0_547
	v_readlane_b32 s8, v255, 27
	s_cmp_ge_i32 s64, s8
	s_cselect_b32 s8, s25, 0
	s_add_i32 s10, s64, s8
	s_sub_i32 s8, s10, 32
	s_lshl_b32 s9, s61, 8
	s_ashr_i32 s8, s8, 3
	s_or_b32 s9, s9, s50
	v_mov_b32_e32 v130, v1
	v_mov_b32_e32 v159, v156
	s_mul_i32 s8, s8, 6
	s_cmp_gt_i32 s10, 31
	s_cselect_b32 s8, s8, 0xc0
	v_lshl_add_u32 v130, v130, 2, s9
	s_ashr_i32 s9, s8, 31
	s_lshl_b64 s[8:9], s[8:9], 12
	v_readlane_b32 s12, v255, 14
	v_readlane_b32 s13, v255, 15
	s_add_u32 s8, s12, s8
	v_ashrrev_i32_e32 v131, 31, v130
	s_addc_u32 s9, s13, s9
	v_lshlrev_b64 v[154:155], 2, v[130:131]
	v_lshl_add_u64 v[130:131], s[8:9], 0, v[154:155]
	s_mov_b64 s[8:9], 0x5000
	v_lshl_add_u64 v[132:133], v[130:131], 0, s[8:9]
	s_movk_i32 s8, 0x5000
	v_add_co_u32_e32 v130, vcc, s8, v130
	s_lshl_b32 s8, s10, 8
	s_add_i32 s8, s8, s44
	v_add_u32_e32 v160, s8, v159
	v_ashrrev_i32_e32 v161, 31, v160
	v_readlane_b32 s8, v254, 0
	v_lshlrev_b64 v[160:161], 12, v[160:161]
	v_readlane_b32 s9, v254, 1
	v_addc_co_u32_e32 v131, vcc, 0, v131, vcc
	s_nop 0
	v_lshl_add_u64 v[160:161], s[8:9], 0, v[160:161]
	v_lshl_add_u64 v[154:155], v[160:161], 0, v[154:155]
	v_add_co_u32_e32 v176, vcc, s45, v154
	global_load_dwordx4 v[138:141], v[132:133], off offset:64
	global_load_dwordx4 v[134:137], v[132:133], off offset:512
	global_load_dwordx4 v[142:145], v[130:131], off
	s_nop 0
	global_load_dwordx4 v[130:133], v[132:133], off offset:576
	v_addc_co_u32_e32 v177, vcc, 0, v155, vcc
	v_add_co_u32_e32 v208, vcc, s19, v154
	global_load_dwordx4 v[160:163], v[154:155], off
	global_load_dwordx4 v[164:167], v[154:155], off offset:64
	global_load_dwordx4 v[168:171], v[154:155], off offset:512
	global_load_dwordx4 v[172:175], v[154:155], off offset:576
	v_addc_co_u32_e32 v209, vcc, 0, v155, vcc
	v_add_co_u32_e32 v246, vcc, s88, v154
	global_load_dwordx4 v[180:183], v[176:177], off
	global_load_dwordx4 v[184:187], v[176:177], off offset:64
	global_load_dwordx4 v[188:191], v[176:177], off offset:512
	global_load_dwordx4 v[192:195], v[176:177], off offset:576
	v_addc_co_u32_e32 v247, vcc, 0, v155, vcc
	global_load_dwordx4 v[196:199], v[208:209], off
	global_load_dwordx4 v[200:203], v[208:209], off offset:64
	global_load_dwordx4 v[204:207], v[208:209], off offset:512
	global_load_dwordx4 v[226:229], v[208:209], off offset:576
	global_load_dwordx4 v[230:233], v[246:247], off
	global_load_dwordx4 v[234:237], v[246:247], off offset:64
	global_load_dwordx4 v[238:241], v[246:247], off offset:512
	global_load_dwordx4 v[242:245], v[246:247], off offset:576
	s_mov_b64 s[8:9], 0x30000
	v_lshl_add_u64 v[248:249], v[154:155], 0, s[84:85]
	v_lshl_add_u64 v[250:251], v[154:155], 0, s[82:83]
	v_lshl_add_u64 v[252:253], v[154:155], 0, s[8:9]
	s_waitcnt vmcnt(0)
;     __device__ __forceinline__ void operator()(const AccT& acc, const Unit& u, int wr, int wc, int fr, int fq) const {
;     ...
;                     for (int n = 0; n < 2; ++n) xo[m][bj][n] = *(const f32x4*)(sbase + (size_t)(ai * 128 + m * 16) * 1024 + bj * 128 + n * 16);
;             __builtin_amdgcn_sched_barrier(0);
; #pragma unroll
;             for (int m = 0; m < 4; ++m) { float* rowp = X + (size_t)(row0 + ai * 128 + m * 16) * 1024 + col0;
; #pragma unroll
;                 for (int bj = 0; bj < 2; ++bj)
; #pragma unroll
;                     for (int n = 0; n < 2; ++n) *(f32x4*)(rowp + bj * 128 + n * 16) = xo[m][bj][n] + gv[bj][n] * acc[ai][bj][m][n]; }
	v_pk_fma_f32 v[108:109], v[108:109], v[132:133], v[174:175]
	v_pk_fma_f32 v[106:107], v[106:107], v[130:131], v[172:173]
	v_pk_fma_f32 v[92:93], v[92:93], v[132:133], v[194:195]
	v_pk_fma_f32 v[90:91], v[90:91], v[130:131], v[192:193]
	v_pk_fma_f32 v[76:77], v[76:77], v[132:133], v[228:229]
	v_pk_fma_f32 v[74:75], v[74:75], v[130:131], v[226:227]
	global_store_dwordx4 v[154:155], v[106:109], off offset:576
	global_store_dwordx4 v[248:249], v[90:93], off offset:576
	global_store_dwordx4 v[250:251], v[74:77], off offset:576
	v_pk_fma_f32 v[108:109], v[120:121], v[144:145], v[182:183]
	v_pk_fma_f32 v[106:107], v[118:119], v[142:143], v[180:181]
	v_pk_fma_f32 v[92:93], v[104:105], v[144:145], v[198:199]
	v_pk_fma_f32 v[90:91], v[102:103], v[142:143], v[196:197]
	v_pk_fma_f32 v[76:77], v[88:89], v[144:145], v[232:233]
	v_pk_fma_f32 v[74:75], v[86:87], v[142:143], v[230:231]
	v_pk_fma_f32 v[128:129], v[128:129], v[144:145], v[162:163]
	v_pk_fma_f32 v[126:127], v[126:127], v[142:143], v[160:161]
	v_pk_fma_f32 v[124:125], v[124:125], v[140:141], v[166:167]
	v_pk_fma_f32 v[122:123], v[122:123], v[138:139], v[164:165]
	v_pk_fma_f32 v[116:117], v[116:117], v[136:137], v[170:171]
	v_pk_fma_f32 v[114:115], v[114:115], v[134:135], v[168:169]
	global_store_dwordx4 v[176:177], v[106:109], off
	v_pk_fma_f32 v[100:101], v[100:101], v[136:137], v[190:191]
	v_pk_fma_f32 v[98:99], v[98:99], v[134:135], v[188:189]
	v_pk_fma_f32 v[108:109], v[112:113], v[140:141], v[186:187]
	v_pk_fma_f32 v[106:107], v[110:111], v[138:139], v[184:185]
	global_store_dwordx4 v[208:209], v[90:93], off
	v_pk_fma_f32 v[84:85], v[84:85], v[136:137], v[206:207]
	v_pk_fma_f32 v[82:83], v[82:83], v[134:135], v[204:205]
	v_pk_fma_f32 v[92:93], v[96:97], v[140:141], v[202:203]
	v_pk_fma_f32 v[90:91], v[94:95], v[138:139], v[200:201]
	global_store_dwordx4 v[246:247], v[74:77], off
	v_pk_fma_f32 v[72:73], v[72:73], v[136:137], v[240:241]
	v_pk_fma_f32 v[70:71], v[70:71], v[134:135], v[238:239]
	v_pk_fma_f32 v[76:77], v[80:81], v[140:141], v[236:237]
	v_pk_fma_f32 v[74:75], v[78:79], v[138:139], v[234:235]
	v_pk_fma_f32 v[68:69], v[68:69], v[132:133], v[244:245]
	v_pk_fma_f32 v[66:67], v[66:67], v[130:131], v[242:243]
	global_store_dwordx4 v[154:155], v[126:129], off
	global_store_dwordx4 v[154:155], v[122:125], off offset:64
	global_store_dwordx4 v[154:155], v[114:117], off offset:512
	global_store_dwordx4 v[248:249], v[106:109], off offset:64
	global_store_dwordx4 v[248:249], v[98:101], off offset:512
	global_store_dwordx4 v[250:251], v[90:93], off offset:64
	global_store_dwordx4 v[250:251], v[82:85], off offset:512
	global_store_dwordx4 v[252:253], v[74:77], off offset:64
	global_store_dwordx4 v[252:253], v[70:73], off offset:512
	global_store_dwordx4 v[252:253], v[66:69], off offset:576
	s_mov_b64 s[8:9], 0x80000
	v_lshl_add_u64 v[160:161], v[154:155], 0, s[8:9]
	s_mov_b32 s8, 0x80000
	v_add_co_u32_e32 v162, vcc, s8, v154
	s_mov_b64 s[8:9], 0x90000
	s_nop 0
	v_addc_co_u32_e32 v163, vcc, 0, v155, vcc
	v_lshl_add_u64 v[164:165], v[154:155], 0, s[8:9]
	s_mov_b32 s8, 0x90000
	v_add_co_u32_e32 v166, vcc, s8, v154
	s_mov_b64 s[8:9], 0xa0000
	s_nop 0
	v_addc_co_u32_e32 v167, vcc, 0, v155, vcc
	v_lshl_add_u64 v[168:169], v[154:155], 0, s[8:9]
	s_mov_b32 s8, 0xa0000
	v_add_co_u32_e32 v170, vcc, s8, v154
	s_mov_b64 s[8:9], 0xb0000
	s_nop 0
	v_addc_co_u32_e32 v171, vcc, 0, v155, vcc
	v_lshl_add_u64 v[172:173], v[154:155], 0, s[8:9]
	s_mov_b32 s8, 0xb0000
	v_add_co_u32_e32 v154, vcc, s8, v154
	global_load_dwordx4 v[66:69], v[162:163], off
	global_load_dwordx4 v[70:73], v[162:163], off offset:64
	global_load_dwordx4 v[74:77], v[162:163], off offset:512
	global_load_dwordx4 v[78:81], v[162:163], off offset:576
	v_addc_co_u32_e32 v155, vcc, 0, v155, vcc
	global_load_dwordx4 v[82:85], v[166:167], off
	global_load_dwordx4 v[86:89], v[166:167], off offset:64
	global_load_dwordx4 v[90:93], v[166:167], off offset:512
	global_load_dwordx4 v[94:97], v[166:167], off offset:576
	global_load_dwordx4 v[98:101], v[170:171], off
	global_load_dwordx4 v[102:105], v[170:171], off offset:64
	global_load_dwordx4 v[106:109], v[170:171], off offset:512
	global_load_dwordx4 v[110:113], v[170:171], off offset:576
	global_load_dwordx4 v[114:117], v[154:155], off
	global_load_dwordx4 v[118:121], v[154:155], off offset:64
	global_load_dwordx4 v[122:125], v[154:155], off offset:512
	global_load_dwordx4 v[126:129], v[154:155], off offset:576
	s_waitcnt vmcnt(0)
; #define PG8_WAIT_V(n) asm volatile("s_waitcnt vmcnt(" #n ")" ::: "memory")
; #define PG8_BAR __builtin_amdgcn_s_barrier()
; template <class Epi>
; __device__ __forceinline__ void gemm_phase(LAS unsigned char* lds, const Gemm g, const Epi& E) {
;     ...
;         E(acc, cur, wr, wc, fr, fq);
;         if (!has_next) break;
; #pragma unroll
;         for (int a = 0; a < 2; ++a)
; #pragma unroll
;             for (int b = 0; b < 2; ++b)
; #pragma unroll
;                 for (int m = 0; m < 4; ++m)
; #pragma unroll
;                     for (int n = 0; n < 2; ++n) acc[a][b][m][n] = (f32x4){0.f, 0.f, 0.f, 0.f};
;         cur = nxt; cA = nA; cB = nB; ++ui;
;     }
;     PG8_WAIT_V(0);
;     if (wr == 0) PG8_BAR;
;     PG8_BAR;
;     __device__ __forceinline__ void operator()(const AccT& acc, const Unit& u, int wr, int wc, int fr, int fq) const {
;     ...
;                     for (int n = 0; n < 2; ++n) xo[m][bj][n] = *(const f32x4*)(sbase + (size_t)(ai * 128 + m * 16) * 1024 + bj * 128 + n * 16);
;             __builtin_amdgcn_sched_barrier(0);
; #pragma unroll
;             for (int m = 0; m < 4; ++m) { float* rowp = X + (size_t)(row0 + ai * 128 + m * 16) * 1024 + col0;
; #pragma unroll
;                 for (int bj = 0; bj < 2; ++bj)
; #pragma unroll
;                     for (int n = 0; n < 2; ++n) *(f32x4*)(rowp + bj * 128 + n * 16) = xo[m][bj][n] + gv[bj][n] * acc[ai][bj][m][n]; }
	v_pk_fma_f32 v[44:45], v[44:45], v[132:133], v[80:81]
	v_pk_fma_f32 v[42:43], v[42:43], v[130:131], v[78:79]
	v_pk_fma_f32 v[28:29], v[28:29], v[132:133], v[96:97]
	v_pk_fma_f32 v[26:27], v[26:27], v[130:131], v[94:95]
	v_pk_fma_f32 v[12:13], v[12:13], v[132:133], v[112:113]
	v_pk_fma_f32 v[10:11], v[10:11], v[130:131], v[110:111]
	global_store_dwordx4 v[160:161], v[42:45], off offset:576
	global_store_dwordx4 v[164:165], v[26:29], off offset:576
	global_store_dwordx4 v[168:169], v[10:13], off offset:576
	v_pk_fma_f32 v[44:45], v[56:57], v[144:145], v[84:85]
	v_pk_fma_f32 v[42:43], v[54:55], v[142:143], v[82:83]
	v_pk_fma_f32 v[28:29], v[40:41], v[144:145], v[100:101]
	v_pk_fma_f32 v[26:27], v[38:39], v[142:143], v[98:99]
	v_pk_fma_f32 v[12:13], v[24:25], v[144:145], v[116:117]
	v_pk_fma_f32 v[10:11], v[22:23], v[142:143], v[114:115]
	v_pk_fma_f32 v[64:65], v[64:65], v[144:145], v[68:69]
	v_pk_fma_f32 v[62:63], v[62:63], v[142:143], v[66:67]
	v_pk_fma_f32 v[60:61], v[60:61], v[140:141], v[72:73]
	v_pk_fma_f32 v[58:59], v[58:59], v[138:139], v[70:71]
	v_pk_fma_f32 v[52:53], v[52:53], v[136:137], v[76:77]
	v_pk_fma_f32 v[50:51], v[50:51], v[134:135], v[74:75]
	global_store_dwordx4 v[166:167], v[42:45], off
	v_pk_fma_f32 v[36:37], v[36:37], v[136:137], v[92:93]
	v_pk_fma_f32 v[34:35], v[34:35], v[134:135], v[90:91]
	v_pk_fma_f32 v[44:45], v[48:49], v[140:141], v[88:89]
	v_pk_fma_f32 v[42:43], v[46:47], v[138:139], v[86:87]
	global_store_dwordx4 v[170:171], v[26:29], off
	v_pk_fma_f32 v[20:21], v[20:21], v[136:137], v[108:109]
	v_pk_fma_f32 v[18:19], v[18:19], v[134:135], v[106:107]
	v_pk_fma_f32 v[28:29], v[32:33], v[140:141], v[104:105]
	v_pk_fma_f32 v[26:27], v[30:31], v[138:139], v[102:103]
	global_store_dwordx4 v[154:155], v[10:13], off
	v_pk_fma_f32 v[8:9], v[8:9], v[136:137], v[124:125]
	v_pk_fma_f32 v[6:7], v[6:7], v[134:135], v[122:123]
	v_pk_fma_f32 v[12:13], v[16:17], v[140:141], v[120:121]
	v_pk_fma_f32 v[10:11], v[14:15], v[138:139], v[118:119]
	v_pk_fma_f32 v[4:5], v[4:5], v[132:133], v[128:129]
	v_pk_fma_f32 v[2:3], v[2:3], v[130:131], v[126:127]
	global_store_dwordx4 v[162:163], v[62:65], off
	global_store_dwordx4 v[160:161], v[58:61], off offset:64
	global_store_dwordx4 v[160:161], v[50:53], off offset:512
	global_store_dwordx4 v[164:165], v[42:45], off offset:64
	global_store_dwordx4 v[164:165], v[34:37], off offset:512
	global_store_dwordx4 v[168:169], v[26:29], off offset:64
	global_store_dwordx4 v[168:169], v[18:21], off offset:512
	global_store_dwordx4 v[172:173], v[10:13], off offset:64
	global_store_dwordx4 v[172:173], v[6:9], off offset:512
	global_store_dwordx4 v[172:173], v[2:5], off offset:576
	s_and_b64 vcc, exec, s[2:3]
	s_mov_b32 s61, s59
	s_mov_b32 s64, s60
	s_mov_b64 s[10:11], s[6:7]
	s_mov_b64 s[8:9], s[4:5]
	s_cbranch_vccz .LBB0_540
	s_waitcnt vmcnt(0)
	s_cmpk_gt_u32 s1, 0xff
	s_movk_i32 s36, 0xf000
	s_cbranch_scc1 .LBB0_551
	s_barrier
